# gla_prep: per-token LDS broadcast reads software-pipelined one token ahead (was ds_read -> lgkmcnt(0) -> 4 FMAs, 252 times)
# baseline (speedup 1.0000x reference)
; __device__ __forceinline__ float log_sigmoid(float x) { return fminf(x, 0.f) - __logf(1.f + __expf(-fabsf(x))); }
; __device__ __forceinline__ void gla_prep_item(LAS unsigned char* lds, int item, const bf16_t* Z, const float* W2, const float* Bg, bf16_t* KDT, float* DEC) {
;     ...
;     for (int i = tid; i < 1024; i += 512) { const int t = i >> 4, r = i & 15; zgs[i] = bf2f(Z[(row0 + t) * ZLD + ZZG + r]); }
;     __syncthreads();
;     const int h = tid >> 7, kd = tid & 127, col = h * 128 + kd;
;     float w[16];
; #pragma unroll
;     for (int r = 0; r < 16; ++r) w[r] = W2[r * 512 + col];
;     const float bias = Bg[col];
;     float bend = 0.f; float gv[64];
; #pragma unroll
;     for (int t = 0; t < 64; ++t) {
;         float x = bias;
; #pragma unroll
;         for (int r = 0; r < 16; ++r) x += zgs[t * 16 + r] * w[r];
;         gv[t] = log_sigmoid(x) * (1.f / 16.f); bend += gv[t];
;     }
;     float bc = 0.f;
;     bf16_t* dst = KDT + (size_t)((b * 4 + h) * 32 + c) * 8192 + (size_t)((kd >> 4) * 2 * 64 + (kd & 15)) * 8;
;     const bf16_t* gk = Z + row0 * ZLD + ZGK + col;
; #pragma unroll
;     for (int t8 = 0; t8 < 8; ++t8) {
;         float kv[8];
; #pragma unroll
;         for (int e = 0; e < 8; ++e) {
;             const int t = t8 * 8 + e;
;             bc += gv[t];
;             kv[e] = bf2f(gk[(size_t)t * ZLD]) * __expf(bend - bc);
.LBB0_598:
	global_load_ushort v46, v[0:1], off
	v_add_co_u32_e32 v3, vcc, 0x200, v3
	s_waitcnt lgkmcnt(0)
	s_mov_b64 s[16:17], 0x30000
	v_lshl_add_u64 v[0:1], v[0:1], 0, s[16:17]
	s_xor_b64 s[16:17], vcc, -1
	s_and_b64 s[16:17], exec, s[16:17]
	s_or_b64 s[0:1], s[16:17], s[0:1]
	s_waitcnt vmcnt(0)
	v_lshlrev_b32_e32 v46, 16, v46
	ds_write_b32 v2, v46
	v_add_u32_e32 v2, 0x800, v2
	s_andn2_b64 exec, exec, s[0:1]
	s_cbranch_execnz .LBB0_598
	s_or_b64 exec, exec, s[0:1]
	s_waitcnt lgkmcnt(0)
	s_barrier
	global_load_dword v65, v[6:7], off
	global_load_dword v66, v[6:7], off offset:2048
	global_load_dword v67, v[8:9], off
	global_load_dword v68, v[10:11], off
	global_load_dword v55, v[12:13], off
	global_load_dword v62, v[14:15], off
	global_load_dword v63, v[16:17], off
	global_load_dword v64, v[18:19], off
	global_load_dword v52, v[20:21], off
	global_load_dword v53, v[22:23], off
	global_load_dword v50, v[24:25], off
	global_load_dword v51, v[26:27], off
	global_load_dword v48, v[28:29], off
	global_load_dword v49, v[30:31], off
	global_load_dword v46, v[32:33], off
	global_load_dword v47, v[34:35], off
	global_load_dword v69, v[36:37], off
	ds_read_b128 v[0:3], v5
	ds_read_b128 v[70:73], v5 offset:16
	ds_read_b128 v[74:77], v5 offset:32
	ds_read_b128 v[78:81], v5 offset:48
	s_and_b32 s9, s66, 31
	s_lshl_b32 s0, s9, 6
	s_or_b32 s6, s6, s0
	s_mulk_i32 s7, 0x1800
	v_mad_u64_u32 v[208:209], s[42:43], s6, v59, v[42:43]
	v_add_u32_e32 v209, s7, v209
	s_mov_b32 s43, 0
	global_load_ushort v140, v[208:209], off offset:2688
	s_mov_b32 s42, 0x2000
	v_lshl_add_u64 v[206:207], v[208:209], 0, s[42:43]
	global_load_ushort v141, v[206:207], off offset:640
	s_mov_b32 s42, 0x3000
	v_lshl_add_u64 v[206:207], v[208:209], 0, s[42:43]
	global_load_ushort v142, v[206:207], off offset:2688
	s_mov_b32 s42, 0x5000
	v_lshl_add_u64 v[206:207], v[208:209], 0, s[42:43]
	global_load_ushort v143, v[206:207], off offset:640
	s_mov_b32 s42, 0x6000
	v_lshl_add_u64 v[206:207], v[208:209], 0, s[42:43]
	global_load_ushort v144, v[206:207], off offset:2688
	s_mov_b32 s42, 0x8000
	v_lshl_add_u64 v[206:207], v[208:209], 0, s[42:43]
	global_load_ushort v145, v[206:207], off offset:640
	s_mov_b32 s42, 0x9000
	v_lshl_add_u64 v[206:207], v[208:209], 0, s[42:43]
	global_load_ushort v146, v[206:207], off offset:2688
	s_mov_b32 s42, 0xb000
	v_lshl_add_u64 v[206:207], v[208:209], 0, s[42:43]
	global_load_ushort v147, v[206:207], off offset:640
	s_mov_b32 s42, 0xc000
	v_lshl_add_u64 v[206:207], v[208:209], 0, s[42:43]
	global_load_ushort v148, v[206:207], off offset:2688
	s_mov_b32 s42, 0xe000
	v_lshl_add_u64 v[206:207], v[208:209], 0, s[42:43]
	global_load_ushort v149, v[206:207], off offset:640
	s_mov_b32 s42, 0xf000
	v_lshl_add_u64 v[206:207], v[208:209], 0, s[42:43]
	global_load_ushort v150, v[206:207], off offset:2688
	s_mov_b32 s42, 0x11000
	v_lshl_add_u64 v[206:207], v[208:209], 0, s[42:43]
	global_load_ushort v151, v[206:207], off offset:640
	s_mov_b32 s42, 0x12000
	v_lshl_add_u64 v[206:207], v[208:209], 0, s[42:43]
	global_load_ushort v152, v[206:207], off offset:2688
	s_mov_b32 s42, 0x14000
	v_lshl_add_u64 v[206:207], v[208:209], 0, s[42:43]
	global_load_ushort v153, v[206:207], off offset:640
	s_mov_b32 s42, 0x15000
	v_lshl_add_u64 v[206:207], v[208:209], 0, s[42:43]
	global_load_ushort v154, v[206:207], off offset:2688
	s_mov_b32 s42, 0x17000
	v_lshl_add_u64 v[206:207], v[208:209], 0, s[42:43]
	global_load_ushort v155, v[206:207], off offset:640
	s_mov_b32 s42, 0x18000
	v_lshl_add_u64 v[206:207], v[208:209], 0, s[42:43]
	global_load_ushort v156, v[206:207], off offset:2688
	s_mov_b32 s42, 0x1a000
	v_lshl_add_u64 v[206:207], v[208:209], 0, s[42:43]
	global_load_ushort v157, v[206:207], off offset:640
	s_mov_b32 s42, 0x1b000
	v_lshl_add_u64 v[206:207], v[208:209], 0, s[42:43]
	global_load_ushort v158, v[206:207], off offset:2688
	s_mov_b32 s42, 0x1d000
	v_lshl_add_u64 v[206:207], v[208:209], 0, s[42:43]
	global_load_ushort v159, v[206:207], off offset:640
	s_mov_b32 s42, 0x1e000
	v_lshl_add_u64 v[206:207], v[208:209], 0, s[42:43]
	global_load_ushort v160, v[206:207], off offset:2688
	s_mov_b32 s42, 0x20000
	v_lshl_add_u64 v[206:207], v[208:209], 0, s[42:43]
	global_load_ushort v161, v[206:207], off offset:640
	s_mov_b32 s42, 0x21000
	v_lshl_add_u64 v[206:207], v[208:209], 0, s[42:43]
	global_load_ushort v162, v[206:207], off offset:2688
	s_mov_b32 s42, 0x23000
	v_lshl_add_u64 v[206:207], v[208:209], 0, s[42:43]
	global_load_ushort v163, v[206:207], off offset:640
	s_mov_b32 s42, 0x24000
	v_lshl_add_u64 v[206:207], v[208:209], 0, s[42:43]
	global_load_ushort v164, v[206:207], off offset:2688
	s_mov_b32 s42, 0x26000
	v_lshl_add_u64 v[206:207], v[208:209], 0, s[42:43]
	global_load_ushort v165, v[206:207], off offset:640
	s_mov_b32 s42, 0x27000
	v_lshl_add_u64 v[206:207], v[208:209], 0, s[42:43]
	global_load_ushort v166, v[206:207], off offset:2688
	s_mov_b32 s42, 0x29000
	v_lshl_add_u64 v[206:207], v[208:209], 0, s[42:43]
	global_load_ushort v167, v[206:207], off offset:640
	s_mov_b32 s42, 0x2a000
	v_lshl_add_u64 v[206:207], v[208:209], 0, s[42:43]
	global_load_ushort v168, v[206:207], off offset:2688
	s_mov_b32 s42, 0x2c000
	v_lshl_add_u64 v[206:207], v[208:209], 0, s[42:43]
	global_load_ushort v169, v[206:207], off offset:640
	s_mov_b32 s42, 0x2d000
	v_lshl_add_u64 v[206:207], v[208:209], 0, s[42:43]
	global_load_ushort v170, v[206:207], off offset:2688
	s_mov_b32 s42, 0x2f000
	v_lshl_add_u64 v[206:207], v[208:209], 0, s[42:43]
	global_load_ushort v171, v[206:207], off offset:640
	s_mov_b32 s42, 0x30000
	v_lshl_add_u64 v[206:207], v[208:209], 0, s[42:43]
; __device__ __forceinline__ float log_sigmoid(float x) { return fminf(x, 0.f) - __logf(1.f + __expf(-fabsf(x))); }
; __device__ __forceinline__ void gla_prep_item(LAS unsigned char* lds, int item, const bf16_t* Z, const float* W2, const float* Bg, bf16_t* KDT, float* DEC) {
;     ...
; #pragma unroll
;     for (int t = 0; t < 64; ++t) {
;         float x = bias;
; #pragma unroll
;         for (int r = 0; r < 16; ++r) x += zgs[t * 16 + r] * w[r];
;         gv[t] = log_sigmoid(x) * (1.f / 16.f); bend += gv[t];
;     }
;     float bc = 0.f;
;     bf16_t* dst = KDT + (size_t)((b * 4 + h) * 32 + c) * 8192 + (size_t)((kd >> 4) * 2 * 64 + (kd & 15)) * 8;
;     const bf16_t* gk = Z + row0 * ZLD + ZGK + col;
; #pragma unroll
;     for (int t8 = 0; t8 < 8; ++t8) {
;         float kv[8];
; #pragma unroll
;         for (int e = 0; e < 8; ++e) {
;             const int t = t8 * 8 + e;
;             bc += gv[t];
;             kv[e] = bf2f(gk[(size_t)t * ZLD]) * __expf(bend - bc);
	global_load_ushort v172, v[206:207], off offset:2688
	s_mov_b32 s42, 0x32000
	v_lshl_add_u64 v[206:207], v[208:209], 0, s[42:43]
	global_load_ushort v173, v[206:207], off offset:640
	s_mov_b32 s42, 0x33000
	v_lshl_add_u64 v[206:207], v[208:209], 0, s[42:43]
	global_load_ushort v174, v[206:207], off offset:2688
	s_mov_b32 s42, 0x35000
	v_lshl_add_u64 v[206:207], v[208:209], 0, s[42:43]
	global_load_ushort v175, v[206:207], off offset:640
	s_mov_b32 s42, 0x36000
	v_lshl_add_u64 v[206:207], v[208:209], 0, s[42:43]
	global_load_ushort v176, v[206:207], off offset:2688
	s_mov_b32 s42, 0x38000
	v_lshl_add_u64 v[206:207], v[208:209], 0, s[42:43]
	global_load_ushort v177, v[206:207], off offset:640
	s_mov_b32 s42, 0x39000
	v_lshl_add_u64 v[206:207], v[208:209], 0, s[42:43]
	global_load_ushort v178, v[206:207], off offset:2688
	s_mov_b32 s42, 0x3b000
	v_lshl_add_u64 v[206:207], v[208:209], 0, s[42:43]
	global_load_ushort v179, v[206:207], off offset:640
	s_mov_b32 s42, 0x3c000
	v_lshl_add_u64 v[206:207], v[208:209], 0, s[42:43]
	global_load_ushort v180, v[206:207], off offset:2688
	s_mov_b32 s42, 0x3e000
	v_lshl_add_u64 v[206:207], v[208:209], 0, s[42:43]
	global_load_ushort v181, v[206:207], off offset:640
	s_mov_b32 s42, 0x3f000
	v_lshl_add_u64 v[206:207], v[208:209], 0, s[42:43]
	global_load_ushort v182, v[206:207], off offset:2688
	s_mov_b32 s42, 0x41000
	v_lshl_add_u64 v[206:207], v[208:209], 0, s[42:43]
	global_load_ushort v183, v[206:207], off offset:640
	s_mov_b32 s42, 0x42000
	v_lshl_add_u64 v[206:207], v[208:209], 0, s[42:43]
	global_load_ushort v186, v[206:207], off offset:2688
	s_mov_b32 s42, 0x44000
	v_lshl_add_u64 v[206:207], v[208:209], 0, s[42:43]
	global_load_ushort v187, v[206:207], off offset:640
	s_mov_b32 s42, 0x45000
	v_lshl_add_u64 v[206:207], v[208:209], 0, s[42:43]
	global_load_ushort v188, v[206:207], off offset:2688
	s_mov_b32 s42, 0x47000
	v_lshl_add_u64 v[206:207], v[208:209], 0, s[42:43]
	global_load_ushort v189, v[206:207], off offset:640
	s_mov_b32 s42, 0x48000
	v_lshl_add_u64 v[206:207], v[208:209], 0, s[42:43]
	global_load_ushort v190, v[206:207], off offset:2688
	s_mov_b32 s42, 0x4a000
	v_lshl_add_u64 v[206:207], v[208:209], 0, s[42:43]
	global_load_ushort v191, v[206:207], off offset:640
	s_mov_b32 s42, 0x4b000
	v_lshl_add_u64 v[206:207], v[208:209], 0, s[42:43]
	global_load_ushort v192, v[206:207], off offset:2688
	s_mov_b32 s42, 0x4d000
	v_lshl_add_u64 v[206:207], v[208:209], 0, s[42:43]
	global_load_ushort v193, v[206:207], off offset:640
	s_mov_b32 s42, 0x4e000
	v_lshl_add_u64 v[206:207], v[208:209], 0, s[42:43]
	global_load_ushort v194, v[206:207], off offset:2688
	s_mov_b32 s42, 0x50000
	v_lshl_add_u64 v[206:207], v[208:209], 0, s[42:43]
	global_load_ushort v195, v[206:207], off offset:640
	s_mov_b32 s42, 0x51000
	v_lshl_add_u64 v[206:207], v[208:209], 0, s[42:43]
	global_load_ushort v196, v[206:207], off offset:2688
	s_mov_b32 s42, 0x53000
	v_lshl_add_u64 v[206:207], v[208:209], 0, s[42:43]
	global_load_ushort v197, v[206:207], off offset:640
	s_mov_b32 s42, 0x54000
	v_lshl_add_u64 v[206:207], v[208:209], 0, s[42:43]
	global_load_ushort v198, v[206:207], off offset:2688
	s_mov_b32 s42, 0x56000
	v_lshl_add_u64 v[206:207], v[208:209], 0, s[42:43]
	global_load_ushort v199, v[206:207], off offset:640
	s_mov_b32 s42, 0x57000
	v_lshl_add_u64 v[206:207], v[208:209], 0, s[42:43]
	global_load_ushort v200, v[206:207], off offset:2688
	s_mov_b32 s42, 0x59000
	v_lshl_add_u64 v[206:207], v[208:209], 0, s[42:43]
	global_load_ushort v201, v[206:207], off offset:640
	s_mov_b32 s42, 0x5a000
	v_lshl_add_u64 v[206:207], v[208:209], 0, s[42:43]
	global_load_ushort v202, v[206:207], off offset:2688
	s_mov_b32 s42, 0x5c000
	v_lshl_add_u64 v[206:207], v[208:209], 0, s[42:43]
	global_load_ushort v203, v[206:207], off offset:640
	s_mov_b32 s42, 0x5d000
	v_lshl_add_u64 v[206:207], v[208:209], 0, s[42:43]
	global_load_ushort v204, v[206:207], off offset:2688
	s_mov_b32 s42, 0x5f000
	v_lshl_add_u64 v[206:207], v[208:209], 0, s[42:43]
	global_load_ushort v205, v[206:207], off offset:640
	s_add_i32 s66, s66, s15
	s_add_i32 s65, s65, s15
	s_cmpk_gt_i32 s66, 0xff
	s_waitcnt vmcnt(0) lgkmcnt(3)
	v_fma_f32 v54, v65, v0, v69
	v_fmac_f32_e32 v54, v66, v1
	v_fmac_f32_e32 v54, v67, v2
	v_fmac_f32_e32 v54, v68, v3
	s_waitcnt lgkmcnt(2)
	v_fmac_f32_e32 v54, v55, v70
	v_fmac_f32_e32 v54, v62, v71
	v_fmac_f32_e32 v54, v63, v72
	v_fmac_f32_e32 v54, v64, v73
	s_waitcnt lgkmcnt(1)
	v_fmac_f32_e32 v54, v52, v74
	v_fmac_f32_e32 v54, v53, v75
	v_fmac_f32_e32 v54, v50, v76
	v_fmac_f32_e32 v54, v51, v77
	s_waitcnt lgkmcnt(0)
	v_pk_mul_f32 v[0:1], v[48:49], v[78:79]
	s_nop 0
	v_add_f32_e32 v0, v54, v0
	v_add_f32_e32 v2, v0, v1
	v_pk_mul_f32 v[0:1], v[46:47], v[80:81]
	s_nop 0
	v_add_f32_e32 v0, v2, v0
	v_add_f32_e32 v0, v0, v1
	v_min_f32_e32 v1, 0, v0
	v_mul_f32_e64 v0, |v0|, s11
	v_exp_f32_e32 v0, v0
	s_nop 0
	v_add_f32_e32 v0, 1.0, v0
	v_cmp_gt_f32_e32 vcc, s12, v0
	s_nop 1
	v_cndmask_b32_e64 v2, 0, 32, vcc
	v_ldexp_f32 v0, v0, v2
	v_log_f32_e32 v0, v0
	s_nop 0
	v_mul_f32_e32 v2, 0x3f317217, v0
	v_fma_f32 v2, v0, s13, -v2
	v_fmac_f32_e32 v2, 0x3377d1cf, v0
	v_fmac_f32_e32 v2, 0x3f317217, v0
	v_cmp_lt_f32_e64 s[0:1], |v0|, s36
	s_nop 1
	v_cndmask_b32_e64 v0, v0, v2, s[0:1]
	v_cndmask_b32_e32 v2, 0, v60, vcc
	v_sub_f32_e32 v0, v0, v2
	v_sub_f32_e32 v0, v1, v0
	s_mov_b32 s0, 0x3d800000
	v_fma_f32 v54, v0, s0, 0
	ds_read_b128 v[240:243], v5 offset:64
	ds_read_b128 v[244:247], v5 offset:80
	ds_read_b128 v[248:251], v5 offset:96
	ds_read_b128 v[252:255], v5 offset:112
	ds_read_b128 v[210:213], v5 offset:128
	ds_read_b128 v[214:217], v5 offset:144
	ds_read_b128 v[218:221], v5 offset:160
	ds_read_b128 v[222:225], v5 offset:176
	s_waitcnt lgkmcnt(4)
; __device__ __forceinline__ float log_sigmoid(float x) { return fminf(x, 0.f) - __logf(1.f + __expf(-fabsf(x))); }
; __device__ __forceinline__ void gla_prep_item(LAS unsigned char* lds, int item, const bf16_t* Z, const float* W2, const float* Bg, bf16_t* KDT, float* DEC) {
;     ...
; #pragma unroll
;     for (int t = 0; t < 64; ++t) {
;         float x = bias;
; #pragma unroll
;         for (int r = 0; r < 16; ++r) x += zgs[t * 16 + r] * w[r];
;         gv[t] = log_sigmoid(x) * (1.f / 16.f); bend += gv[t];
;     }
	v_fma_f32 v70, v65, v240, v69
	v_fmac_f32_e32 v70, v66, v241
	v_fmac_f32_e32 v70, v67, v242
	v_fmac_f32_e32 v70, v68, v243
	v_fmac_f32_e32 v70, v55, v244
	v_fmac_f32_e32 v70, v62, v245
	v_fmac_f32_e32 v70, v63, v246
	v_fmac_f32_e32 v70, v64, v247
	v_fmac_f32_e32 v70, v52, v248
	v_fmac_f32_e32 v70, v53, v249
	v_fmac_f32_e32 v70, v50, v250
	v_fmac_f32_e32 v70, v51, v251
	v_pk_mul_f32 v[0:1], v[48:49], v[252:253]
	s_nop 0
	v_add_f32_e32 v0, v70, v0
	v_add_f32_e32 v70, v0, v1
	v_pk_mul_f32 v[0:1], v[46:47], v[254:255]
	s_nop 0
	v_add_f32_e32 v0, v70, v0
	v_add_f32_e32 v0, v0, v1
	v_min_f32_e32 v1, 0, v0
	v_mul_f32_e64 v0, |v0|, s11
	v_exp_f32_e32 v0, v0
	s_nop 0
	v_add_f32_e32 v0, 1.0, v0
	v_cmp_gt_f32_e32 vcc, s12, v0
	s_nop 1
	v_cndmask_b32_e64 v2, 0, 32, vcc
	v_ldexp_f32 v0, v0, v2
	v_log_f32_e32 v0, v0
	s_nop 0
	v_mul_f32_e32 v2, 0x3f317217, v0
	v_fma_f32 v2, v0, s13, -v2
	v_fmac_f32_e32 v2, 0x3377d1cf, v0
	v_fmac_f32_e32 v2, 0x3f317217, v0
	v_cmp_lt_f32_e64 s[0:1], |v0|, s36
	s_nop 1
	v_cndmask_b32_e64 v0, v0, v2, s[0:1]
	v_cndmask_b32_e32 v2, 0, v60, vcc
	v_sub_f32_e32 v0, v0, v2
	v_sub_f32_e32 v0, v1, v0
	v_fmamk_f32 v70, v0, 0x3d800000, v54
	ds_read_b128 v[240:243], v5 offset:192
	ds_read_b128 v[244:247], v5 offset:208
	ds_read_b128 v[248:251], v5 offset:224
	ds_read_b128 v[252:255], v5 offset:240
	s_waitcnt lgkmcnt(4)
	v_fma_f32 v71, v65, v210, v69
	v_fmac_f32_e32 v71, v66, v211
	v_fmac_f32_e32 v71, v67, v212
	v_fmac_f32_e32 v71, v68, v213
	v_fmac_f32_e32 v71, v55, v214
	v_fmac_f32_e32 v71, v62, v215
	v_fmac_f32_e32 v71, v63, v216
	v_fmac_f32_e32 v71, v64, v217
	v_fmac_f32_e32 v71, v52, v218
	v_fmac_f32_e32 v71, v53, v219
	v_fmac_f32_e32 v71, v50, v220
	v_fmac_f32_e32 v71, v51, v221
	v_pk_mul_f32 v[0:1], v[48:49], v[222:223]
	s_nop 0
	v_add_f32_e32 v0, v71, v0
	v_add_f32_e32 v71, v0, v1
	v_pk_mul_f32 v[0:1], v[46:47], v[224:225]
	s_nop 0
	v_add_f32_e32 v0, v71, v0
	v_add_f32_e32 v0, v0, v1
	v_min_f32_e32 v1, 0, v0
	v_mul_f32_e64 v0, |v0|, s11
	v_exp_f32_e32 v0, v0
	s_nop 0
	v_add_f32_e32 v0, 1.0, v0
	v_cmp_gt_f32_e32 vcc, s12, v0
	s_nop 1
	v_cndmask_b32_e64 v2, 0, 32, vcc
	v_ldexp_f32 v0, v0, v2
	v_log_f32_e32 v0, v0
	s_nop 0
	v_mul_f32_e32 v2, 0x3f317217, v0
	v_fma_f32 v2, v0, s13, -v2
	v_fmac_f32_e32 v2, 0x3377d1cf, v0
	v_fmac_f32_e32 v2, 0x3f317217, v0
	v_cmp_lt_f32_e64 s[0:1], |v0|, s36
	s_nop 1
	v_cndmask_b32_e64 v0, v0, v2, s[0:1]
	v_cndmask_b32_e32 v2, 0, v60, vcc
	v_sub_f32_e32 v0, v0, v2
	v_sub_f32_e32 v0, v1, v0
	v_fmamk_f32 v71, v0, 0x3d800000, v70
	ds_read_b128 v[210:213], v5 offset:256
	ds_read_b128 v[214:217], v5 offset:272
	ds_read_b128 v[218:221], v5 offset:288
	ds_read_b128 v[222:225], v5 offset:304
	s_waitcnt lgkmcnt(4)
	v_fma_f32 v72, v65, v240, v69
	v_fmac_f32_e32 v72, v66, v241
	v_fmac_f32_e32 v72, v67, v242
	v_fmac_f32_e32 v72, v68, v243
	v_fmac_f32_e32 v72, v55, v244
	v_fmac_f32_e32 v72, v62, v245
	v_fmac_f32_e32 v72, v63, v246
	v_fmac_f32_e32 v72, v64, v247
	v_fmac_f32_e32 v72, v52, v248
	v_fmac_f32_e32 v72, v53, v249
	v_fmac_f32_e32 v72, v50, v250
	v_fmac_f32_e32 v72, v51, v251
	v_pk_mul_f32 v[0:1], v[48:49], v[252:253]
	s_nop 0
	v_add_f32_e32 v0, v72, v0
	v_add_f32_e32 v72, v0, v1
	v_pk_mul_f32 v[0:1], v[46:47], v[254:255]
	s_nop 0
	v_add_f32_e32 v0, v72, v0
	v_add_f32_e32 v0, v0, v1
	v_min_f32_e32 v1, 0, v0
	v_mul_f32_e64 v0, |v0|, s11
	v_exp_f32_e32 v0, v0
	s_nop 0
	v_add_f32_e32 v0, 1.0, v0
	v_cmp_gt_f32_e32 vcc, s12, v0
	s_nop 1
	v_cndmask_b32_e64 v2, 0, 32, vcc
	v_ldexp_f32 v0, v0, v2
	v_log_f32_e32 v0, v0
	s_nop 0
	v_mul_f32_e32 v2, 0x3f317217, v0
	v_fma_f32 v2, v0, s13, -v2
	v_fmac_f32_e32 v2, 0x3377d1cf, v0
	v_fmac_f32_e32 v2, 0x3f317217, v0
	v_cmp_lt_f32_e64 s[0:1], |v0|, s36
	s_nop 1
	v_cndmask_b32_e64 v0, v0, v2, s[0:1]
	v_cndmask_b32_e32 v2, 0, v60, vcc
	v_sub_f32_e32 v0, v0, v2
	v_sub_f32_e32 v0, v1, v0
	v_fmamk_f32 v72, v0, 0x3d800000, v71
	ds_read_b128 v[240:243], v5 offset:320
	ds_read_b128 v[244:247], v5 offset:336
	ds_read_b128 v[248:251], v5 offset:352
	ds_read_b128 v[252:255], v5 offset:368
	s_waitcnt lgkmcnt(4)
	v_fma_f32 v73, v65, v210, v69
	v_fmac_f32_e32 v73, v66, v211
	v_fmac_f32_e32 v73, v67, v212
	v_fmac_f32_e32 v73, v68, v213
	v_fmac_f32_e32 v73, v55, v214
	v_fmac_f32_e32 v73, v62, v215
	v_fmac_f32_e32 v73, v63, v216
	v_fmac_f32_e32 v73, v64, v217
	v_fmac_f32_e32 v73, v52, v218
	v_fmac_f32_e32 v73, v53, v219
	v_fmac_f32_e32 v73, v50, v220
	v_fmac_f32_e32 v73, v51, v221
	v_pk_mul_f32 v[0:1], v[48:49], v[222:223]
	s_nop 0
	v_add_f32_e32 v0, v73, v0
	v_add_f32_e32 v73, v0, v1
	v_pk_mul_f32 v[0:1], v[46:47], v[224:225]
	s_nop 0
	v_add_f32_e32 v0, v73, v0
	v_add_f32_e32 v0, v0, v1
	v_min_f32_e32 v1, 0, v0
	v_mul_f32_e64 v0, |v0|, s11
	v_exp_f32_e32 v0, v0
	s_nop 0
	v_add_f32_e32 v0, 1.0, v0
	v_cmp_gt_f32_e32 vcc, s12, v0
	s_nop 1
	v_cndmask_b32_e64 v2, 0, 32, vcc
	v_ldexp_f32 v0, v0, v2
	v_log_f32_e32 v0, v0
	s_nop 0
	v_mul_f32_e32 v2, 0x3f317217, v0
	v_fma_f32 v2, v0, s13, -v2
	v_fmac_f32_e32 v2, 0x3377d1cf, v0
	v_fmac_f32_e32 v2, 0x3f317217, v0
	v_cmp_lt_f32_e64 s[0:1], |v0|, s36
	s_nop 1
	v_cndmask_b32_e64 v0, v0, v2, s[0:1]
	v_cndmask_b32_e32 v2, 0, v60, vcc
	v_sub_f32_e32 v0, v0, v2
	v_sub_f32_e32 v0, v1, v0
	v_fmamk_f32 v73, v0, 0x3d800000, v72
	ds_read_b128 v[210:213], v5 offset:384
	ds_read_b128 v[214:217], v5 offset:400
	ds_read_b128 v[218:221], v5 offset:416
	ds_read_b128 v[222:225], v5 offset:432
	s_waitcnt lgkmcnt(4)
; __device__ __forceinline__ float log_sigmoid(float x) { return fminf(x, 0.f) - __logf(1.f + __expf(-fabsf(x))); }
; __device__ __forceinline__ void gla_prep_item(LAS unsigned char* lds, int item, const bf16_t* Z, const float* W2, const float* Bg, bf16_t* KDT, float* DEC) {
;     ...
; #pragma unroll
;     for (int t = 0; t < 64; ++t) {
;         float x = bias;
; #pragma unroll
;         for (int r = 0; r < 16; ++r) x += zgs[t * 16 + r] * w[r];
;         gv[t] = log_sigmoid(x) * (1.f / 16.f); bend += gv[t];
;     }
	v_fma_f32 v74, v65, v240, v69
	v_fmac_f32_e32 v74, v66, v241
	v_fmac_f32_e32 v74, v67, v242
	v_fmac_f32_e32 v74, v68, v243
	v_fmac_f32_e32 v74, v55, v244
	v_fmac_f32_e32 v74, v62, v245
	v_fmac_f32_e32 v74, v63, v246
	v_fmac_f32_e32 v74, v64, v247
	v_fmac_f32_e32 v74, v52, v248
	v_fmac_f32_e32 v74, v53, v249
	v_fmac_f32_e32 v74, v50, v250
	v_fmac_f32_e32 v74, v51, v251
	v_pk_mul_f32 v[0:1], v[48:49], v[252:253]
	s_nop 0
	v_add_f32_e32 v0, v74, v0
	v_add_f32_e32 v74, v0, v1
	v_pk_mul_f32 v[0:1], v[46:47], v[254:255]
	s_nop 0
	v_add_f32_e32 v0, v74, v0
	v_add_f32_e32 v0, v0, v1
	v_min_f32_e32 v1, 0, v0
	v_mul_f32_e64 v0, |v0|, s11
	v_exp_f32_e32 v0, v0
	s_nop 0
	v_add_f32_e32 v0, 1.0, v0
	v_cmp_gt_f32_e32 vcc, s12, v0
	s_nop 1
	v_cndmask_b32_e64 v2, 0, 32, vcc
	v_ldexp_f32 v0, v0, v2
	v_log_f32_e32 v0, v0
	s_nop 0
	v_mul_f32_e32 v2, 0x3f317217, v0
	v_fma_f32 v2, v0, s13, -v2
	v_fmac_f32_e32 v2, 0x3377d1cf, v0
	v_fmac_f32_e32 v2, 0x3f317217, v0
	v_cmp_lt_f32_e64 s[0:1], |v0|, s36
	s_nop 1
	v_cndmask_b32_e64 v0, v0, v2, s[0:1]
	v_cndmask_b32_e32 v2, 0, v60, vcc
	v_sub_f32_e32 v0, v0, v2
	v_sub_f32_e32 v0, v1, v0
	v_fmamk_f32 v74, v0, 0x3d800000, v73
	ds_read_b128 v[240:243], v5 offset:448
	ds_read_b128 v[244:247], v5 offset:464
	ds_read_b128 v[248:251], v5 offset:480
	ds_read_b128 v[252:255], v5 offset:496
	s_waitcnt lgkmcnt(4)
	v_fma_f32 v75, v65, v210, v69
	v_fmac_f32_e32 v75, v66, v211
	v_fmac_f32_e32 v75, v67, v212
	v_fmac_f32_e32 v75, v68, v213
	v_fmac_f32_e32 v75, v55, v214
	v_fmac_f32_e32 v75, v62, v215
	v_fmac_f32_e32 v75, v63, v216
	v_fmac_f32_e32 v75, v64, v217
	v_fmac_f32_e32 v75, v52, v218
	v_fmac_f32_e32 v75, v53, v219
	v_fmac_f32_e32 v75, v50, v220
	v_fmac_f32_e32 v75, v51, v221
	v_pk_mul_f32 v[0:1], v[48:49], v[222:223]
	s_nop 0
	v_add_f32_e32 v0, v75, v0
	v_add_f32_e32 v75, v0, v1
	v_pk_mul_f32 v[0:1], v[46:47], v[224:225]
	s_nop 0
	v_add_f32_e32 v0, v75, v0
	v_add_f32_e32 v0, v0, v1
	v_min_f32_e32 v1, 0, v0
	v_mul_f32_e64 v0, |v0|, s11
	v_exp_f32_e32 v0, v0
	s_nop 0
	v_add_f32_e32 v0, 1.0, v0
	v_cmp_gt_f32_e32 vcc, s12, v0
	s_nop 1
	v_cndmask_b32_e64 v2, 0, 32, vcc
	v_ldexp_f32 v0, v0, v2
	v_log_f32_e32 v0, v0
	s_nop 0
	v_mul_f32_e32 v2, 0x3f317217, v0
	v_fma_f32 v2, v0, s13, -v2
	v_fmac_f32_e32 v2, 0x3377d1cf, v0
	v_fmac_f32_e32 v2, 0x3f317217, v0
	v_cmp_lt_f32_e64 s[0:1], |v0|, s36
	s_nop 1
	v_cndmask_b32_e64 v0, v0, v2, s[0:1]
	v_cndmask_b32_e32 v2, 0, v60, vcc
	v_sub_f32_e32 v0, v0, v2
	v_sub_f32_e32 v0, v1, v0
	v_fmamk_f32 v75, v0, 0x3d800000, v74
	ds_read_b128 v[210:213], v5 offset:512
	ds_read_b128 v[214:217], v5 offset:528
	ds_read_b128 v[218:221], v5 offset:544
	ds_read_b128 v[222:225], v5 offset:560
	s_waitcnt lgkmcnt(4)
	v_fma_f32 v76, v65, v240, v69
	v_fmac_f32_e32 v76, v66, v241
	v_fmac_f32_e32 v76, v67, v242
	v_fmac_f32_e32 v76, v68, v243
	v_fmac_f32_e32 v76, v55, v244
	v_fmac_f32_e32 v76, v62, v245
	v_fmac_f32_e32 v76, v63, v246
	v_fmac_f32_e32 v76, v64, v247
	v_fmac_f32_e32 v76, v52, v248
	v_fmac_f32_e32 v76, v53, v249
	v_fmac_f32_e32 v76, v50, v250
	v_fmac_f32_e32 v76, v51, v251
	v_pk_mul_f32 v[0:1], v[48:49], v[252:253]
	s_nop 0
	v_add_f32_e32 v0, v76, v0
	v_add_f32_e32 v76, v0, v1
	v_pk_mul_f32 v[0:1], v[46:47], v[254:255]
	s_nop 0
	v_add_f32_e32 v0, v76, v0
	v_add_f32_e32 v0, v0, v1
	v_min_f32_e32 v1, 0, v0
	v_mul_f32_e64 v0, |v0|, s11
	v_exp_f32_e32 v0, v0
	s_nop 0
	v_add_f32_e32 v0, 1.0, v0
	v_cmp_gt_f32_e32 vcc, s12, v0
	s_nop 1
	v_cndmask_b32_e64 v2, 0, 32, vcc
	v_ldexp_f32 v0, v0, v2
	v_log_f32_e32 v0, v0
	s_nop 0
	v_mul_f32_e32 v2, 0x3f317217, v0
	v_fma_f32 v2, v0, s13, -v2
	v_fmac_f32_e32 v2, 0x3377d1cf, v0
	v_fmac_f32_e32 v2, 0x3f317217, v0
	v_cmp_lt_f32_e64 s[0:1], |v0|, s36
	s_nop 1
	v_cndmask_b32_e64 v0, v0, v2, s[0:1]
	v_cndmask_b32_e32 v2, 0, v60, vcc
	v_sub_f32_e32 v0, v0, v2
	v_sub_f32_e32 v0, v1, v0
	v_fmamk_f32 v77, v0, 0x3d800000, v75
	ds_read_b128 v[240:243], v5 offset:576
	ds_read_b128 v[244:247], v5 offset:592
	ds_read_b128 v[248:251], v5 offset:608
	ds_read_b128 v[252:255], v5 offset:624
	s_waitcnt lgkmcnt(4)
	v_fma_f32 v76, v65, v210, v69
	v_fmac_f32_e32 v76, v66, v211
	v_fmac_f32_e32 v76, v67, v212
	v_fmac_f32_e32 v76, v68, v213
	v_fmac_f32_e32 v76, v55, v214
	v_fmac_f32_e32 v76, v62, v215
	v_fmac_f32_e32 v76, v63, v216
	v_fmac_f32_e32 v76, v64, v217
	v_fmac_f32_e32 v76, v52, v218
	v_fmac_f32_e32 v76, v53, v219
	v_fmac_f32_e32 v76, v50, v220
	v_fmac_f32_e32 v76, v51, v221
	v_pk_mul_f32 v[0:1], v[48:49], v[222:223]
	s_nop 0
	v_add_f32_e32 v0, v76, v0
	v_add_f32_e32 v76, v0, v1
	v_pk_mul_f32 v[0:1], v[46:47], v[224:225]
	s_nop 0
	v_add_f32_e32 v0, v76, v0
	v_add_f32_e32 v0, v0, v1
	v_min_f32_e32 v1, 0, v0
	v_mul_f32_e64 v0, |v0|, s11
	v_exp_f32_e32 v0, v0
	s_nop 0
	v_add_f32_e32 v0, 1.0, v0
	v_cmp_gt_f32_e32 vcc, s12, v0
	s_nop 1
	v_cndmask_b32_e64 v2, 0, 32, vcc
	v_ldexp_f32 v0, v0, v2
	v_log_f32_e32 v0, v0
	s_nop 0
	v_mul_f32_e32 v2, 0x3f317217, v0
	v_fma_f32 v2, v0, s13, -v2
	v_fmac_f32_e32 v2, 0x3377d1cf, v0
	v_fmac_f32_e32 v2, 0x3f317217, v0
	v_cmp_lt_f32_e64 s[0:1], |v0|, s36
	s_nop 1
	v_cndmask_b32_e64 v0, v0, v2, s[0:1]
	v_cndmask_b32_e32 v2, 0, v60, vcc
	v_sub_f32_e32 v0, v0, v2
	v_sub_f32_e32 v0, v1, v0
	v_fmamk_f32 v76, v0, 0x3d800000, v77
	ds_read_b128 v[210:213], v5 offset:640
	ds_read_b128 v[214:217], v5 offset:656
	ds_read_b128 v[218:221], v5 offset:672
	ds_read_b128 v[222:225], v5 offset:688
	s_waitcnt lgkmcnt(4)
; __device__ __forceinline__ float log_sigmoid(float x) { return fminf(x, 0.f) - __logf(1.f + __expf(-fabsf(x))); }
; __device__ __forceinline__ void gla_prep_item(LAS unsigned char* lds, int item, const bf16_t* Z, const float* W2, const float* Bg, bf16_t* KDT, float* DEC) {
;     ...
; #pragma unroll
;     for (int t = 0; t < 64; ++t) {
;         float x = bias;
; #pragma unroll
;         for (int r = 0; r < 16; ++r) x += zgs[t * 16 + r] * w[r];
;         gv[t] = log_sigmoid(x) * (1.f / 16.f); bend += gv[t];
;     }
	v_fma_f32 v78, v65, v240, v69
	v_fmac_f32_e32 v78, v66, v241
	v_fmac_f32_e32 v78, v67, v242
	v_fmac_f32_e32 v78, v68, v243
	v_fmac_f32_e32 v78, v55, v244
	v_fmac_f32_e32 v78, v62, v245
	v_fmac_f32_e32 v78, v63, v246
	v_fmac_f32_e32 v78, v64, v247
	v_fmac_f32_e32 v78, v52, v248
	v_fmac_f32_e32 v78, v53, v249
	v_fmac_f32_e32 v78, v50, v250
	v_fmac_f32_e32 v78, v51, v251
	v_pk_mul_f32 v[0:1], v[48:49], v[252:253]
	s_nop 0
	v_add_f32_e32 v0, v78, v0
	v_add_f32_e32 v78, v0, v1
	v_pk_mul_f32 v[0:1], v[46:47], v[254:255]
	s_nop 0
	v_add_f32_e32 v0, v78, v0
	v_add_f32_e32 v0, v0, v1
	v_min_f32_e32 v1, 0, v0
	v_mul_f32_e64 v0, |v0|, s11
	v_exp_f32_e32 v0, v0
	s_nop 0
	v_add_f32_e32 v0, 1.0, v0
	v_cmp_gt_f32_e32 vcc, s12, v0
	s_nop 1
	v_cndmask_b32_e64 v2, 0, 32, vcc
	v_ldexp_f32 v0, v0, v2
	v_log_f32_e32 v0, v0
	s_nop 0
	v_mul_f32_e32 v2, 0x3f317217, v0
	v_fma_f32 v2, v0, s13, -v2
	v_fmac_f32_e32 v2, 0x3377d1cf, v0
	v_fmac_f32_e32 v2, 0x3f317217, v0
	v_cmp_lt_f32_e64 s[0:1], |v0|, s36
	s_nop 1
	v_cndmask_b32_e64 v0, v0, v2, s[0:1]
	v_cndmask_b32_e32 v2, 0, v60, vcc
	v_sub_f32_e32 v0, v0, v2
	v_sub_f32_e32 v0, v1, v0
	v_fmamk_f32 v78, v0, 0x3d800000, v76
	ds_read_b128 v[240:243], v5 offset:704
	ds_read_b128 v[244:247], v5 offset:720
	ds_read_b128 v[248:251], v5 offset:736
	ds_read_b128 v[252:255], v5 offset:752
	s_waitcnt lgkmcnt(4)
	v_fma_f32 v79, v65, v210, v69
	v_fmac_f32_e32 v79, v66, v211
	v_fmac_f32_e32 v79, v67, v212
	v_fmac_f32_e32 v79, v68, v213
	v_fmac_f32_e32 v79, v55, v214
	v_fmac_f32_e32 v79, v62, v215
	v_fmac_f32_e32 v79, v63, v216
	v_fmac_f32_e32 v79, v64, v217
	v_fmac_f32_e32 v79, v52, v218
	v_fmac_f32_e32 v79, v53, v219
	v_fmac_f32_e32 v79, v50, v220
	v_fmac_f32_e32 v79, v51, v221
	v_pk_mul_f32 v[0:1], v[48:49], v[222:223]
	s_nop 0
	v_add_f32_e32 v0, v79, v0
	v_add_f32_e32 v79, v0, v1
	v_pk_mul_f32 v[0:1], v[46:47], v[224:225]
	s_nop 0
	v_add_f32_e32 v0, v79, v0
	v_add_f32_e32 v0, v0, v1
	v_min_f32_e32 v1, 0, v0
	v_mul_f32_e64 v0, |v0|, s11
	v_exp_f32_e32 v0, v0
	s_nop 0
	v_add_f32_e32 v0, 1.0, v0
	v_cmp_gt_f32_e32 vcc, s12, v0
	s_nop 1
	v_cndmask_b32_e64 v2, 0, 32, vcc
	v_ldexp_f32 v0, v0, v2
	v_log_f32_e32 v0, v0
	s_nop 0
	v_mul_f32_e32 v2, 0x3f317217, v0
	v_fma_f32 v2, v0, s13, -v2
	v_fmac_f32_e32 v2, 0x3377d1cf, v0
	v_fmac_f32_e32 v2, 0x3f317217, v0
	v_cmp_lt_f32_e64 s[0:1], |v0|, s36
	s_nop 1
	v_cndmask_b32_e64 v0, v0, v2, s[0:1]
	v_cndmask_b32_e32 v2, 0, v60, vcc
	v_sub_f32_e32 v0, v0, v2
	v_sub_f32_e32 v0, v1, v0
	v_fmamk_f32 v79, v0, 0x3d800000, v78
	ds_read_b128 v[210:213], v5 offset:768
	ds_read_b128 v[214:217], v5 offset:784
	ds_read_b128 v[218:221], v5 offset:800
	ds_read_b128 v[222:225], v5 offset:816
	s_waitcnt lgkmcnt(4)
	v_fma_f32 v80, v65, v240, v69
	v_fmac_f32_e32 v80, v66, v241
	v_fmac_f32_e32 v80, v67, v242
	v_fmac_f32_e32 v80, v68, v243
	v_fmac_f32_e32 v80, v55, v244
	v_fmac_f32_e32 v80, v62, v245
	v_fmac_f32_e32 v80, v63, v246
	v_fmac_f32_e32 v80, v64, v247
	v_fmac_f32_e32 v80, v52, v248
	v_fmac_f32_e32 v80, v53, v249
	v_fmac_f32_e32 v80, v50, v250
	v_fmac_f32_e32 v80, v51, v251
	v_pk_mul_f32 v[0:1], v[48:49], v[252:253]
	s_nop 0
	v_add_f32_e32 v0, v80, v0
	v_add_f32_e32 v80, v0, v1
	v_pk_mul_f32 v[0:1], v[46:47], v[254:255]
	s_nop 0
	v_add_f32_e32 v0, v80, v0
	v_add_f32_e32 v0, v0, v1
	v_min_f32_e32 v1, 0, v0
	v_mul_f32_e64 v0, |v0|, s11
	v_exp_f32_e32 v0, v0
	s_nop 0
	v_add_f32_e32 v0, 1.0, v0
	v_cmp_gt_f32_e32 vcc, s12, v0
	s_nop 1
	v_cndmask_b32_e64 v2, 0, 32, vcc
	v_ldexp_f32 v0, v0, v2
	v_log_f32_e32 v0, v0
	s_nop 0
	v_mul_f32_e32 v2, 0x3f317217, v0
	v_fma_f32 v2, v0, s13, -v2
	v_fmac_f32_e32 v2, 0x3377d1cf, v0
	v_fmac_f32_e32 v2, 0x3f317217, v0
	v_cmp_lt_f32_e64 s[0:1], |v0|, s36
	s_nop 1
	v_cndmask_b32_e64 v0, v0, v2, s[0:1]
	v_cndmask_b32_e32 v2, 0, v60, vcc
	v_sub_f32_e32 v0, v0, v2
	v_sub_f32_e32 v0, v1, v0
	v_fmamk_f32 v80, v0, 0x3d800000, v79
	ds_read_b128 v[240:243], v5 offset:832
	ds_read_b128 v[244:247], v5 offset:848
	ds_read_b128 v[248:251], v5 offset:864
	ds_read_b128 v[252:255], v5 offset:880
	s_waitcnt lgkmcnt(4)
	v_fma_f32 v81, v65, v210, v69
	v_fmac_f32_e32 v81, v66, v211
	v_fmac_f32_e32 v81, v67, v212
	v_fmac_f32_e32 v81, v68, v213
	v_fmac_f32_e32 v81, v55, v214
	v_fmac_f32_e32 v81, v62, v215
	v_fmac_f32_e32 v81, v63, v216
	v_fmac_f32_e32 v81, v64, v217
	v_fmac_f32_e32 v81, v52, v218
	v_fmac_f32_e32 v81, v53, v219
	v_fmac_f32_e32 v81, v50, v220
	v_fmac_f32_e32 v81, v51, v221
	v_pk_mul_f32 v[0:1], v[48:49], v[222:223]
	s_nop 0
	v_add_f32_e32 v0, v81, v0
	v_add_f32_e32 v81, v0, v1
	v_pk_mul_f32 v[0:1], v[46:47], v[224:225]
	s_nop 0
	v_add_f32_e32 v0, v81, v0
	v_add_f32_e32 v0, v0, v1
	v_min_f32_e32 v1, 0, v0
	v_mul_f32_e64 v0, |v0|, s11
	v_exp_f32_e32 v0, v0
	s_nop 0
	v_add_f32_e32 v0, 1.0, v0
	v_cmp_gt_f32_e32 vcc, s12, v0
	s_nop 1
	v_cndmask_b32_e64 v2, 0, 32, vcc
	v_ldexp_f32 v0, v0, v2
	v_log_f32_e32 v0, v0
	s_nop 0
	v_mul_f32_e32 v2, 0x3f317217, v0
	v_fma_f32 v2, v0, s13, -v2
	v_fmac_f32_e32 v2, 0x3377d1cf, v0
	v_fmac_f32_e32 v2, 0x3f317217, v0
	v_cmp_lt_f32_e64 s[0:1], |v0|, s36
	s_nop 1
	v_cndmask_b32_e64 v0, v0, v2, s[0:1]
	v_cndmask_b32_e32 v2, 0, v60, vcc
	v_sub_f32_e32 v0, v0, v2
	v_sub_f32_e32 v0, v1, v0
	v_fmamk_f32 v81, v0, 0x3d800000, v80
	ds_read_b128 v[210:213], v5 offset:896
	ds_read_b128 v[214:217], v5 offset:912
	ds_read_b128 v[218:221], v5 offset:928
	ds_read_b128 v[222:225], v5 offset:944
	s_waitcnt lgkmcnt(4)
; __device__ __forceinline__ float log_sigmoid(float x) { return fminf(x, 0.f) - __logf(1.f + __expf(-fabsf(x))); }
; __device__ __forceinline__ void gla_prep_item(LAS unsigned char* lds, int item, const bf16_t* Z, const float* W2, const float* Bg, bf16_t* KDT, float* DEC) {
;     ...
; #pragma unroll
;     for (int t = 0; t < 64; ++t) {
;         float x = bias;
; #pragma unroll
;         for (int r = 0; r < 16; ++r) x += zgs[t * 16 + r] * w[r];
;         gv[t] = log_sigmoid(x) * (1.f / 16.f); bend += gv[t];
;     }
	v_fma_f32 v82, v65, v240, v69
	v_fmac_f32_e32 v82, v66, v241
	v_fmac_f32_e32 v82, v67, v242
	v_fmac_f32_e32 v82, v68, v243
	v_fmac_f32_e32 v82, v55, v244
	v_fmac_f32_e32 v82, v62, v245
	v_fmac_f32_e32 v82, v63, v246
	v_fmac_f32_e32 v82, v64, v247
	v_fmac_f32_e32 v82, v52, v248
	v_fmac_f32_e32 v82, v53, v249
	v_fmac_f32_e32 v82, v50, v250
	v_fmac_f32_e32 v82, v51, v251
	v_pk_mul_f32 v[0:1], v[48:49], v[252:253]
	s_nop 0
	v_add_f32_e32 v0, v82, v0
	v_add_f32_e32 v82, v0, v1
	v_pk_mul_f32 v[0:1], v[46:47], v[254:255]
	s_nop 0
	v_add_f32_e32 v0, v82, v0
	v_add_f32_e32 v0, v0, v1
	v_min_f32_e32 v1, 0, v0
	v_mul_f32_e64 v0, |v0|, s11
	v_exp_f32_e32 v0, v0
	s_nop 0
	v_add_f32_e32 v0, 1.0, v0
	v_cmp_gt_f32_e32 vcc, s12, v0
	s_nop 1
	v_cndmask_b32_e64 v2, 0, 32, vcc
	v_ldexp_f32 v0, v0, v2
	v_log_f32_e32 v0, v0
	s_nop 0
	v_mul_f32_e32 v2, 0x3f317217, v0
	v_fma_f32 v2, v0, s13, -v2
	v_fmac_f32_e32 v2, 0x3377d1cf, v0
	v_fmac_f32_e32 v2, 0x3f317217, v0
	v_cmp_lt_f32_e64 s[0:1], |v0|, s36
	s_nop 1
	v_cndmask_b32_e64 v0, v0, v2, s[0:1]
	v_cndmask_b32_e32 v2, 0, v60, vcc
	v_sub_f32_e32 v0, v0, v2
	v_sub_f32_e32 v0, v1, v0
	v_fmamk_f32 v82, v0, 0x3d800000, v81
	ds_read_b128 v[240:243], v5 offset:960
	ds_read_b128 v[244:247], v5 offset:976
	ds_read_b128 v[248:251], v5 offset:992
	ds_read_b128 v[252:255], v5 offset:1008
	s_waitcnt lgkmcnt(4)
	v_fma_f32 v83, v65, v210, v69
	v_fmac_f32_e32 v83, v66, v211
	v_fmac_f32_e32 v83, v67, v212
	v_fmac_f32_e32 v83, v68, v213
	v_fmac_f32_e32 v83, v55, v214
	v_fmac_f32_e32 v83, v62, v215
	v_fmac_f32_e32 v83, v63, v216
	v_fmac_f32_e32 v83, v64, v217
	v_fmac_f32_e32 v83, v52, v218
	v_fmac_f32_e32 v83, v53, v219
	v_fmac_f32_e32 v83, v50, v220
	v_fmac_f32_e32 v83, v51, v221
	v_pk_mul_f32 v[0:1], v[48:49], v[222:223]
	s_nop 0
	v_add_f32_e32 v0, v83, v0
	v_add_f32_e32 v83, v0, v1
	v_pk_mul_f32 v[0:1], v[46:47], v[224:225]
	s_nop 0
	v_add_f32_e32 v0, v83, v0
	v_add_f32_e32 v0, v0, v1
	v_min_f32_e32 v1, 0, v0
	v_mul_f32_e64 v0, |v0|, s11
	v_exp_f32_e32 v0, v0
	s_nop 0
	v_add_f32_e32 v0, 1.0, v0
	v_cmp_gt_f32_e32 vcc, s12, v0
	s_nop 1
	v_cndmask_b32_e64 v2, 0, 32, vcc
	v_ldexp_f32 v0, v0, v2
	v_log_f32_e32 v0, v0
	s_nop 0
	v_mul_f32_e32 v2, 0x3f317217, v0
	v_fma_f32 v2, v0, s13, -v2
	v_fmac_f32_e32 v2, 0x3377d1cf, v0
	v_fmac_f32_e32 v2, 0x3f317217, v0
	v_cmp_lt_f32_e64 s[0:1], |v0|, s36
	s_nop 1
	v_cndmask_b32_e64 v0, v0, v2, s[0:1]
	v_cndmask_b32_e32 v2, 0, v60, vcc
	v_sub_f32_e32 v0, v0, v2
	v_sub_f32_e32 v0, v1, v0
	v_fmamk_f32 v83, v0, 0x3d800000, v82
	ds_read_b128 v[210:213], v5 offset:1024
	ds_read_b128 v[214:217], v5 offset:1040
	ds_read_b128 v[218:221], v5 offset:1056
	ds_read_b128 v[222:225], v5 offset:1072
	s_waitcnt lgkmcnt(4)
	v_fma_f32 v84, v65, v240, v69
	v_fmac_f32_e32 v84, v66, v241
	v_fmac_f32_e32 v84, v67, v242
	v_fmac_f32_e32 v84, v68, v243
	v_fmac_f32_e32 v84, v55, v244
	v_fmac_f32_e32 v84, v62, v245
	v_fmac_f32_e32 v84, v63, v246
	v_fmac_f32_e32 v84, v64, v247
	v_fmac_f32_e32 v84, v52, v248
	v_fmac_f32_e32 v84, v53, v249
	v_fmac_f32_e32 v84, v50, v250
	v_fmac_f32_e32 v84, v51, v251
	v_pk_mul_f32 v[0:1], v[48:49], v[252:253]
	s_nop 0
	v_add_f32_e32 v0, v84, v0
	v_add_f32_e32 v84, v0, v1
	v_pk_mul_f32 v[0:1], v[46:47], v[254:255]
	s_nop 0
	v_add_f32_e32 v0, v84, v0
	v_add_f32_e32 v0, v0, v1
	v_min_f32_e32 v1, 0, v0
	v_mul_f32_e64 v0, |v0|, s11
	v_exp_f32_e32 v0, v0
	s_nop 0
	v_add_f32_e32 v0, 1.0, v0
	v_cmp_gt_f32_e32 vcc, s12, v0
	s_nop 1
	v_cndmask_b32_e64 v2, 0, 32, vcc
	v_ldexp_f32 v0, v0, v2
	v_log_f32_e32 v0, v0
	s_nop 0
	v_mul_f32_e32 v2, 0x3f317217, v0
	v_fma_f32 v2, v0, s13, -v2
	v_fmac_f32_e32 v2, 0x3377d1cf, v0
	v_fmac_f32_e32 v2, 0x3f317217, v0
	v_cmp_lt_f32_e64 s[0:1], |v0|, s36
	s_nop 1
	v_cndmask_b32_e64 v0, v0, v2, s[0:1]
	v_cndmask_b32_e32 v2, 0, v60, vcc
	v_sub_f32_e32 v0, v0, v2
	v_sub_f32_e32 v0, v1, v0
	v_fmamk_f32 v84, v0, 0x3d800000, v83
	ds_read_b128 v[240:243], v5 offset:1088
	ds_read_b128 v[244:247], v5 offset:1104
	ds_read_b128 v[248:251], v5 offset:1120
	ds_read_b128 v[252:255], v5 offset:1136
	s_waitcnt lgkmcnt(4)
	v_fma_f32 v85, v65, v210, v69
	v_fmac_f32_e32 v85, v66, v211
	v_fmac_f32_e32 v85, v67, v212
	v_fmac_f32_e32 v85, v68, v213
	v_fmac_f32_e32 v85, v55, v214
	v_fmac_f32_e32 v85, v62, v215
	v_fmac_f32_e32 v85, v63, v216
	v_fmac_f32_e32 v85, v64, v217
	v_fmac_f32_e32 v85, v52, v218
	v_fmac_f32_e32 v85, v53, v219
	v_fmac_f32_e32 v85, v50, v220
	v_fmac_f32_e32 v85, v51, v221
	v_pk_mul_f32 v[0:1], v[48:49], v[222:223]
	s_nop 0
	v_add_f32_e32 v0, v85, v0
	v_add_f32_e32 v85, v0, v1
	v_pk_mul_f32 v[0:1], v[46:47], v[224:225]
	s_nop 0
	v_add_f32_e32 v0, v85, v0
	v_add_f32_e32 v0, v0, v1
	v_min_f32_e32 v1, 0, v0
	v_mul_f32_e64 v0, |v0|, s11
	v_exp_f32_e32 v0, v0
	s_nop 0
	v_add_f32_e32 v0, 1.0, v0
	v_cmp_gt_f32_e32 vcc, s12, v0
	s_nop 1
	v_cndmask_b32_e64 v2, 0, 32, vcc
	v_ldexp_f32 v0, v0, v2
	v_log_f32_e32 v0, v0
	s_nop 0
	v_mul_f32_e32 v2, 0x3f317217, v0
	v_fma_f32 v2, v0, s13, -v2
	v_fmac_f32_e32 v2, 0x3377d1cf, v0
	v_fmac_f32_e32 v2, 0x3f317217, v0
	v_cmp_lt_f32_e64 s[0:1], |v0|, s36
	s_nop 1
	v_cndmask_b32_e64 v0, v0, v2, s[0:1]
	v_cndmask_b32_e32 v2, 0, v60, vcc
	v_sub_f32_e32 v0, v0, v2
	v_sub_f32_e32 v0, v1, v0
	v_fmamk_f32 v85, v0, 0x3d800000, v84
	ds_read_b128 v[210:213], v5 offset:1152
	ds_read_b128 v[214:217], v5 offset:1168
	ds_read_b128 v[218:221], v5 offset:1184
	ds_read_b128 v[222:225], v5 offset:1200
	s_waitcnt lgkmcnt(4)
; __device__ __forceinline__ float log_sigmoid(float x) { return fminf(x, 0.f) - __logf(1.f + __expf(-fabsf(x))); }
; __device__ __forceinline__ void gla_prep_item(LAS unsigned char* lds, int item, const bf16_t* Z, const float* W2, const float* Bg, bf16_t* KDT, float* DEC) {
;     ...
; #pragma unroll
;     for (int t = 0; t < 64; ++t) {
;         float x = bias;
; #pragma unroll
;         for (int r = 0; r < 16; ++r) x += zgs[t * 16 + r] * w[r];
;         gv[t] = log_sigmoid(x) * (1.f / 16.f); bend += gv[t];
;     }
	v_fma_f32 v86, v65, v240, v69
	v_fmac_f32_e32 v86, v66, v241
	v_fmac_f32_e32 v86, v67, v242
	v_fmac_f32_e32 v86, v68, v243
	v_fmac_f32_e32 v86, v55, v244
	v_fmac_f32_e32 v86, v62, v245
	v_fmac_f32_e32 v86, v63, v246
	v_fmac_f32_e32 v86, v64, v247
	v_fmac_f32_e32 v86, v52, v248
	v_fmac_f32_e32 v86, v53, v249
	v_fmac_f32_e32 v86, v50, v250
	v_fmac_f32_e32 v86, v51, v251
	v_pk_mul_f32 v[0:1], v[48:49], v[252:253]
	s_nop 0
	v_add_f32_e32 v0, v86, v0
	v_add_f32_e32 v86, v0, v1
	v_pk_mul_f32 v[0:1], v[46:47], v[254:255]
	s_nop 0
	v_add_f32_e32 v0, v86, v0
	v_add_f32_e32 v0, v0, v1
	v_min_f32_e32 v1, 0, v0
	v_mul_f32_e64 v0, |v0|, s11
	v_exp_f32_e32 v0, v0
	s_nop 0
	v_add_f32_e32 v0, 1.0, v0
	v_cmp_gt_f32_e32 vcc, s12, v0
	s_nop 1
	v_cndmask_b32_e64 v2, 0, 32, vcc
	v_ldexp_f32 v0, v0, v2
	v_log_f32_e32 v0, v0
	s_nop 0
	v_mul_f32_e32 v2, 0x3f317217, v0
	v_fma_f32 v2, v0, s13, -v2
	v_fmac_f32_e32 v2, 0x3377d1cf, v0
	v_fmac_f32_e32 v2, 0x3f317217, v0
	v_cmp_lt_f32_e64 s[0:1], |v0|, s36
	s_nop 1
	v_cndmask_b32_e64 v0, v0, v2, s[0:1]
	v_cndmask_b32_e32 v2, 0, v60, vcc
	v_sub_f32_e32 v0, v0, v2
	v_sub_f32_e32 v0, v1, v0
	v_fmamk_f32 v86, v0, 0x3d800000, v85
	ds_read_b128 v[240:243], v5 offset:1216
	ds_read_b128 v[244:247], v5 offset:1232
	ds_read_b128 v[248:251], v5 offset:1248
	ds_read_b128 v[252:255], v5 offset:1264
	s_waitcnt lgkmcnt(4)
	v_fma_f32 v87, v65, v210, v69
	v_fmac_f32_e32 v87, v66, v211
	v_fmac_f32_e32 v87, v67, v212
	v_fmac_f32_e32 v87, v68, v213
	v_fmac_f32_e32 v87, v55, v214
	v_fmac_f32_e32 v87, v62, v215
	v_fmac_f32_e32 v87, v63, v216
	v_fmac_f32_e32 v87, v64, v217
	v_fmac_f32_e32 v87, v52, v218
	v_fmac_f32_e32 v87, v53, v219
	v_fmac_f32_e32 v87, v50, v220
	v_fmac_f32_e32 v87, v51, v221
	v_pk_mul_f32 v[0:1], v[48:49], v[222:223]
	s_nop 0
	v_add_f32_e32 v0, v87, v0
	v_add_f32_e32 v87, v0, v1
	v_pk_mul_f32 v[0:1], v[46:47], v[224:225]
	s_nop 0
	v_add_f32_e32 v0, v87, v0
	v_add_f32_e32 v0, v0, v1
	v_min_f32_e32 v1, 0, v0
	v_mul_f32_e64 v0, |v0|, s11
	v_exp_f32_e32 v0, v0
	s_nop 0
	v_add_f32_e32 v0, 1.0, v0
	v_cmp_gt_f32_e32 vcc, s12, v0
	s_nop 1
	v_cndmask_b32_e64 v2, 0, 32, vcc
	v_ldexp_f32 v0, v0, v2
	v_log_f32_e32 v0, v0
	s_nop 0
	v_mul_f32_e32 v2, 0x3f317217, v0
	v_fma_f32 v2, v0, s13, -v2
	v_fmac_f32_e32 v2, 0x3377d1cf, v0
	v_fmac_f32_e32 v2, 0x3f317217, v0
	v_cmp_lt_f32_e64 s[0:1], |v0|, s36
	s_nop 1
	v_cndmask_b32_e64 v0, v0, v2, s[0:1]
	v_cndmask_b32_e32 v2, 0, v60, vcc
	v_sub_f32_e32 v0, v0, v2
	v_sub_f32_e32 v0, v1, v0
	v_fmamk_f32 v87, v0, 0x3d800000, v86
	ds_read_b128 v[210:213], v5 offset:1280
	ds_read_b128 v[214:217], v5 offset:1296
	ds_read_b128 v[218:221], v5 offset:1312
	ds_read_b128 v[222:225], v5 offset:1328
	s_waitcnt lgkmcnt(4)
	v_fma_f32 v88, v65, v240, v69
	v_fmac_f32_e32 v88, v66, v241
	v_fmac_f32_e32 v88, v67, v242
	v_fmac_f32_e32 v88, v68, v243
	v_fmac_f32_e32 v88, v55, v244
	v_fmac_f32_e32 v88, v62, v245
	v_fmac_f32_e32 v88, v63, v246
	v_fmac_f32_e32 v88, v64, v247
	v_fmac_f32_e32 v88, v52, v248
	v_fmac_f32_e32 v88, v53, v249
	v_fmac_f32_e32 v88, v50, v250
	v_fmac_f32_e32 v88, v51, v251
	v_pk_mul_f32 v[0:1], v[48:49], v[252:253]
	s_nop 0
	v_add_f32_e32 v0, v88, v0
	v_add_f32_e32 v88, v0, v1
	v_pk_mul_f32 v[0:1], v[46:47], v[254:255]
	s_nop 0
	v_add_f32_e32 v0, v88, v0
	v_add_f32_e32 v0, v0, v1
	v_min_f32_e32 v1, 0, v0
	v_mul_f32_e64 v0, |v0|, s11
	v_exp_f32_e32 v0, v0
	s_nop 0
	v_add_f32_e32 v0, 1.0, v0
	v_cmp_gt_f32_e32 vcc, s12, v0
	s_nop 1
	v_cndmask_b32_e64 v2, 0, 32, vcc
	v_ldexp_f32 v0, v0, v2
	v_log_f32_e32 v0, v0
	s_nop 0
	v_mul_f32_e32 v2, 0x3f317217, v0
	v_fma_f32 v2, v0, s13, -v2
	v_fmac_f32_e32 v2, 0x3377d1cf, v0
	v_fmac_f32_e32 v2, 0x3f317217, v0
	v_cmp_lt_f32_e64 s[0:1], |v0|, s36
	s_nop 1
	v_cndmask_b32_e64 v0, v0, v2, s[0:1]
	v_cndmask_b32_e32 v2, 0, v60, vcc
	v_sub_f32_e32 v0, v0, v2
	v_sub_f32_e32 v0, v1, v0
	v_fmamk_f32 v88, v0, 0x3d800000, v87
	ds_read_b128 v[240:243], v5 offset:1344
	ds_read_b128 v[244:247], v5 offset:1360
	ds_read_b128 v[248:251], v5 offset:1376
	ds_read_b128 v[252:255], v5 offset:1392
	s_waitcnt lgkmcnt(4)
	v_fma_f32 v89, v65, v210, v69
	v_fmac_f32_e32 v89, v66, v211
	v_fmac_f32_e32 v89, v67, v212
	v_fmac_f32_e32 v89, v68, v213
	v_fmac_f32_e32 v89, v55, v214
	v_fmac_f32_e32 v89, v62, v215
	v_fmac_f32_e32 v89, v63, v216
	v_fmac_f32_e32 v89, v64, v217
	v_fmac_f32_e32 v89, v52, v218
	v_fmac_f32_e32 v89, v53, v219
	v_fmac_f32_e32 v89, v50, v220
	v_fmac_f32_e32 v89, v51, v221
	v_pk_mul_f32 v[0:1], v[48:49], v[222:223]
	s_nop 0
	v_add_f32_e32 v0, v89, v0
	v_add_f32_e32 v89, v0, v1
	v_pk_mul_f32 v[0:1], v[46:47], v[224:225]
	s_nop 0
	v_add_f32_e32 v0, v89, v0
	v_add_f32_e32 v0, v0, v1
	v_min_f32_e32 v1, 0, v0
	v_mul_f32_e64 v0, |v0|, s11
	v_exp_f32_e32 v0, v0
	s_nop 0
	v_add_f32_e32 v0, 1.0, v0
	v_cmp_gt_f32_e32 vcc, s12, v0
	s_nop 1
	v_cndmask_b32_e64 v2, 0, 32, vcc
	v_ldexp_f32 v0, v0, v2
	v_log_f32_e32 v0, v0
	s_nop 0
	v_mul_f32_e32 v2, 0x3f317217, v0
	v_fma_f32 v2, v0, s13, -v2
	v_fmac_f32_e32 v2, 0x3377d1cf, v0
	v_fmac_f32_e32 v2, 0x3f317217, v0
	v_cmp_lt_f32_e64 s[0:1], |v0|, s36
	s_nop 1
	v_cndmask_b32_e64 v0, v0, v2, s[0:1]
	v_cndmask_b32_e32 v2, 0, v60, vcc
	v_sub_f32_e32 v0, v0, v2
	v_sub_f32_e32 v0, v1, v0
	v_fmamk_f32 v89, v0, 0x3d800000, v88
	ds_read_b128 v[210:213], v5 offset:1408
	ds_read_b128 v[214:217], v5 offset:1424
	ds_read_b128 v[218:221], v5 offset:1440
	ds_read_b128 v[222:225], v5 offset:1456
	s_waitcnt lgkmcnt(4)
; __device__ __forceinline__ float log_sigmoid(float x) { return fminf(x, 0.f) - __logf(1.f + __expf(-fabsf(x))); }
; __device__ __forceinline__ void gla_prep_item(LAS unsigned char* lds, int item, const bf16_t* Z, const float* W2, const float* Bg, bf16_t* KDT, float* DEC) {
;     ...
; #pragma unroll
;     for (int t = 0; t < 64; ++t) {
;         float x = bias;
; #pragma unroll
;         for (int r = 0; r < 16; ++r) x += zgs[t * 16 + r] * w[r];
;         gv[t] = log_sigmoid(x) * (1.f / 16.f); bend += gv[t];
;     }
	v_fma_f32 v90, v65, v240, v69
	v_fmac_f32_e32 v90, v66, v241
	v_fmac_f32_e32 v90, v67, v242
	v_fmac_f32_e32 v90, v68, v243
	v_fmac_f32_e32 v90, v55, v244
	v_fmac_f32_e32 v90, v62, v245
	v_fmac_f32_e32 v90, v63, v246
	v_fmac_f32_e32 v90, v64, v247
	v_fmac_f32_e32 v90, v52, v248
	v_fmac_f32_e32 v90, v53, v249
	v_fmac_f32_e32 v90, v50, v250
	v_fmac_f32_e32 v90, v51, v251
	v_pk_mul_f32 v[0:1], v[48:49], v[252:253]
	s_nop 0
	v_add_f32_e32 v0, v90, v0
	v_add_f32_e32 v90, v0, v1
	v_pk_mul_f32 v[0:1], v[46:47], v[254:255]
	s_nop 0
	v_add_f32_e32 v0, v90, v0
	v_add_f32_e32 v0, v0, v1
	v_min_f32_e32 v1, 0, v0
	v_mul_f32_e64 v0, |v0|, s11
	v_exp_f32_e32 v0, v0
	s_nop 0
	v_add_f32_e32 v0, 1.0, v0
	v_cmp_gt_f32_e32 vcc, s12, v0
	s_nop 1
	v_cndmask_b32_e64 v2, 0, 32, vcc
	v_ldexp_f32 v0, v0, v2
	v_log_f32_e32 v0, v0
	s_nop 0
	v_mul_f32_e32 v2, 0x3f317217, v0
	v_fma_f32 v2, v0, s13, -v2
	v_fmac_f32_e32 v2, 0x3377d1cf, v0
	v_fmac_f32_e32 v2, 0x3f317217, v0
	v_cmp_lt_f32_e64 s[0:1], |v0|, s36
	s_nop 1
	v_cndmask_b32_e64 v0, v0, v2, s[0:1]
	v_cndmask_b32_e32 v2, 0, v60, vcc
	v_sub_f32_e32 v0, v0, v2
	v_sub_f32_e32 v0, v1, v0
	v_fmamk_f32 v90, v0, 0x3d800000, v89
	ds_read_b128 v[240:243], v5 offset:1472
	ds_read_b128 v[244:247], v5 offset:1488
	ds_read_b128 v[248:251], v5 offset:1504
	ds_read_b128 v[252:255], v5 offset:1520
	s_waitcnt lgkmcnt(4)
	v_fma_f32 v91, v65, v210, v69
	v_fmac_f32_e32 v91, v66, v211
	v_fmac_f32_e32 v91, v67, v212
	v_fmac_f32_e32 v91, v68, v213
	v_fmac_f32_e32 v91, v55, v214
	v_fmac_f32_e32 v91, v62, v215
	v_fmac_f32_e32 v91, v63, v216
	v_fmac_f32_e32 v91, v64, v217
	v_fmac_f32_e32 v91, v52, v218
	v_fmac_f32_e32 v91, v53, v219
	v_fmac_f32_e32 v91, v50, v220
	v_fmac_f32_e32 v91, v51, v221
	v_pk_mul_f32 v[0:1], v[48:49], v[222:223]
	s_nop 0
	v_add_f32_e32 v0, v91, v0
	v_add_f32_e32 v91, v0, v1
	v_pk_mul_f32 v[0:1], v[46:47], v[224:225]
	s_nop 0
	v_add_f32_e32 v0, v91, v0
	v_add_f32_e32 v0, v0, v1
	v_min_f32_e32 v1, 0, v0
	v_mul_f32_e64 v0, |v0|, s11
	v_exp_f32_e32 v0, v0
	s_nop 0
	v_add_f32_e32 v0, 1.0, v0
	v_cmp_gt_f32_e32 vcc, s12, v0
	s_nop 1
	v_cndmask_b32_e64 v2, 0, 32, vcc
	v_ldexp_f32 v0, v0, v2
	v_log_f32_e32 v0, v0
	s_nop 0
	v_mul_f32_e32 v2, 0x3f317217, v0
	v_fma_f32 v2, v0, s13, -v2
	v_fmac_f32_e32 v2, 0x3377d1cf, v0
	v_fmac_f32_e32 v2, 0x3f317217, v0
	v_cmp_lt_f32_e64 s[0:1], |v0|, s36
	s_nop 1
	v_cndmask_b32_e64 v0, v0, v2, s[0:1]
	v_cndmask_b32_e32 v2, 0, v60, vcc
	v_sub_f32_e32 v0, v0, v2
	v_sub_f32_e32 v0, v1, v0
	v_fmamk_f32 v91, v0, 0x3d800000, v90
	ds_read_b128 v[210:213], v5 offset:1536
	ds_read_b128 v[214:217], v5 offset:1552
	ds_read_b128 v[218:221], v5 offset:1568
	ds_read_b128 v[222:225], v5 offset:1584
	s_waitcnt lgkmcnt(4)
	v_fma_f32 v92, v65, v240, v69
	v_fmac_f32_e32 v92, v66, v241
	v_fmac_f32_e32 v92, v67, v242
	v_fmac_f32_e32 v92, v68, v243
	v_fmac_f32_e32 v92, v55, v244
	v_fmac_f32_e32 v92, v62, v245
	v_fmac_f32_e32 v92, v63, v246
	v_fmac_f32_e32 v92, v64, v247
	v_fmac_f32_e32 v92, v52, v248
	v_fmac_f32_e32 v92, v53, v249
	v_fmac_f32_e32 v92, v50, v250
	v_fmac_f32_e32 v92, v51, v251
	v_pk_mul_f32 v[0:1], v[48:49], v[252:253]
	s_nop 0
	v_add_f32_e32 v0, v92, v0
	v_add_f32_e32 v92, v0, v1
	v_pk_mul_f32 v[0:1], v[46:47], v[254:255]
	s_nop 0
	v_add_f32_e32 v0, v92, v0
	v_add_f32_e32 v0, v0, v1
	v_min_f32_e32 v1, 0, v0
	v_mul_f32_e64 v0, |v0|, s11
	v_exp_f32_e32 v0, v0
	s_nop 0
	v_add_f32_e32 v0, 1.0, v0
	v_cmp_gt_f32_e32 vcc, s12, v0
	s_nop 1
	v_cndmask_b32_e64 v2, 0, 32, vcc
	v_ldexp_f32 v0, v0, v2
	v_log_f32_e32 v0, v0
	s_nop 0
	v_mul_f32_e32 v2, 0x3f317217, v0
	v_fma_f32 v2, v0, s13, -v2
	v_fmac_f32_e32 v2, 0x3377d1cf, v0
	v_fmac_f32_e32 v2, 0x3f317217, v0
	v_cmp_lt_f32_e64 s[0:1], |v0|, s36
	s_nop 1
	v_cndmask_b32_e64 v0, v0, v2, s[0:1]
	v_cndmask_b32_e32 v2, 0, v60, vcc
	v_sub_f32_e32 v0, v0, v2
	v_sub_f32_e32 v0, v1, v0
	v_fmamk_f32 v92, v0, 0x3d800000, v91
	ds_read_b128 v[240:243], v5 offset:1600
	ds_read_b128 v[244:247], v5 offset:1616
	ds_read_b128 v[248:251], v5 offset:1632
	ds_read_b128 v[252:255], v5 offset:1648
	s_waitcnt lgkmcnt(4)
	v_fma_f32 v93, v65, v210, v69
	v_fmac_f32_e32 v93, v66, v211
	v_fmac_f32_e32 v93, v67, v212
	v_fmac_f32_e32 v93, v68, v213
	v_fmac_f32_e32 v93, v55, v214
	v_fmac_f32_e32 v93, v62, v215
	v_fmac_f32_e32 v93, v63, v216
	v_fmac_f32_e32 v93, v64, v217
	v_fmac_f32_e32 v93, v52, v218
	v_fmac_f32_e32 v93, v53, v219
	v_fmac_f32_e32 v93, v50, v220
	v_fmac_f32_e32 v93, v51, v221
	v_pk_mul_f32 v[0:1], v[48:49], v[222:223]
	s_nop 0
	v_add_f32_e32 v0, v93, v0
	v_add_f32_e32 v93, v0, v1
	v_pk_mul_f32 v[0:1], v[46:47], v[224:225]
	s_nop 0
	v_add_f32_e32 v0, v93, v0
	v_add_f32_e32 v0, v0, v1
	v_min_f32_e32 v1, 0, v0
	v_mul_f32_e64 v0, |v0|, s11
	v_exp_f32_e32 v0, v0
	s_nop 0
	v_add_f32_e32 v0, 1.0, v0
	v_cmp_gt_f32_e32 vcc, s12, v0
	s_nop 1
	v_cndmask_b32_e64 v2, 0, 32, vcc
	v_ldexp_f32 v0, v0, v2
	v_log_f32_e32 v0, v0
	s_nop 0
	v_mul_f32_e32 v2, 0x3f317217, v0
	v_fma_f32 v2, v0, s13, -v2
	v_fmac_f32_e32 v2, 0x3377d1cf, v0
	v_fmac_f32_e32 v2, 0x3f317217, v0
	v_cmp_lt_f32_e64 s[0:1], |v0|, s36
	s_nop 1
	v_cndmask_b32_e64 v0, v0, v2, s[0:1]
	v_cndmask_b32_e32 v2, 0, v60, vcc
	v_sub_f32_e32 v0, v0, v2
	v_sub_f32_e32 v0, v1, v0
	v_fmamk_f32 v93, v0, 0x3d800000, v92
	ds_read_b128 v[210:213], v5 offset:1664
	ds_read_b128 v[214:217], v5 offset:1680
	ds_read_b128 v[218:221], v5 offset:1696
	ds_read_b128 v[222:225], v5 offset:1712
	s_waitcnt lgkmcnt(4)
; __device__ __forceinline__ float log_sigmoid(float x) { return fminf(x, 0.f) - __logf(1.f + __expf(-fabsf(x))); }
; __device__ __forceinline__ void gla_prep_item(LAS unsigned char* lds, int item, const bf16_t* Z, const float* W2, const float* Bg, bf16_t* KDT, float* DEC) {
;     ...
; #pragma unroll
;     for (int t = 0; t < 64; ++t) {
;         float x = bias;
; #pragma unroll
;         for (int r = 0; r < 16; ++r) x += zgs[t * 16 + r] * w[r];
;         gv[t] = log_sigmoid(x) * (1.f / 16.f); bend += gv[t];
	v_fma_f32 v94, v65, v240, v69
	v_fmac_f32_e32 v94, v66, v241
	v_fmac_f32_e32 v94, v67, v242
	v_fmac_f32_e32 v94, v68, v243
	v_fmac_f32_e32 v94, v55, v244
	v_fmac_f32_e32 v94, v62, v245
	v_fmac_f32_e32 v94, v63, v246
	v_fmac_f32_e32 v94, v64, v247
	v_fmac_f32_e32 v94, v52, v248
	v_fmac_f32_e32 v94, v53, v249
	v_fmac_f32_e32 v94, v50, v250
	v_fmac_f32_e32 v94, v51, v251
	v_pk_mul_f32 v[0:1], v[48:49], v[252:253]
	s_nop 0
	v_add_f32_e32 v0, v94, v0
	v_add_f32_e32 v94, v0, v1
	v_pk_mul_f32 v[0:1], v[46:47], v[254:255]
	s_nop 0
	v_add_f32_e32 v0, v94, v0
	v_add_f32_e32 v0, v0, v1
	v_min_f32_e32 v1, 0, v0
	v_mul_f32_e64 v0, |v0|, s11
	v_exp_f32_e32 v0, v0
	s_nop 0
	v_add_f32_e32 v0, 1.0, v0
	v_cmp_gt_f32_e32 vcc, s12, v0
	s_nop 1
	v_cndmask_b32_e64 v2, 0, 32, vcc
	v_ldexp_f32 v0, v0, v2
	v_log_f32_e32 v0, v0
	s_nop 0
	v_mul_f32_e32 v2, 0x3f317217, v0
	v_fma_f32 v2, v0, s13, -v2
	v_fmac_f32_e32 v2, 0x3377d1cf, v0
	v_fmac_f32_e32 v2, 0x3f317217, v0
	v_cmp_lt_f32_e64 s[0:1], |v0|, s36
	s_nop 1
	v_cndmask_b32_e64 v0, v0, v2, s[0:1]
	v_cndmask_b32_e32 v2, 0, v60, vcc
	v_sub_f32_e32 v0, v0, v2
	v_sub_f32_e32 v0, v1, v0
	v_fmamk_f32 v94, v0, 0x3d800000, v93
	ds_read_b128 v[240:243], v5 offset:1728
	ds_read_b128 v[244:247], v5 offset:1744
	ds_read_b128 v[248:251], v5 offset:1760
	ds_read_b128 v[252:255], v5 offset:1776
	s_waitcnt lgkmcnt(4)
	v_fma_f32 v95, v65, v210, v69
	v_fmac_f32_e32 v95, v66, v211
	v_fmac_f32_e32 v95, v67, v212
	v_fmac_f32_e32 v95, v68, v213
	v_fmac_f32_e32 v95, v55, v214
	v_fmac_f32_e32 v95, v62, v215
	v_fmac_f32_e32 v95, v63, v216
	v_fmac_f32_e32 v95, v64, v217
	v_fmac_f32_e32 v95, v52, v218
	v_fmac_f32_e32 v95, v53, v219
	v_fmac_f32_e32 v95, v50, v220
	v_fmac_f32_e32 v95, v51, v221
	v_pk_mul_f32 v[0:1], v[48:49], v[222:223]
	s_nop 0
	v_add_f32_e32 v0, v95, v0
	v_add_f32_e32 v95, v0, v1
	v_pk_mul_f32 v[0:1], v[46:47], v[224:225]
	s_nop 0
	v_add_f32_e32 v0, v95, v0
	v_add_f32_e32 v0, v0, v1
	v_min_f32_e32 v1, 0, v0
	v_mul_f32_e64 v0, |v0|, s11
	v_exp_f32_e32 v0, v0
	s_nop 0
	v_add_f32_e32 v0, 1.0, v0
	v_cmp_gt_f32_e32 vcc, s12, v0
	s_nop 1
	v_cndmask_b32_e64 v2, 0, 32, vcc
	v_ldexp_f32 v0, v0, v2
	v_log_f32_e32 v0, v0
	s_nop 0
	v_mul_f32_e32 v2, 0x3f317217, v0
	v_fma_f32 v2, v0, s13, -v2
	v_fmac_f32_e32 v2, 0x3377d1cf, v0
	v_fmac_f32_e32 v2, 0x3f317217, v0
	v_cmp_lt_f32_e64 s[0:1], |v0|, s36
	s_nop 1
	v_cndmask_b32_e64 v0, v0, v2, s[0:1]
	v_cndmask_b32_e32 v2, 0, v60, vcc
	v_sub_f32_e32 v0, v0, v2
	v_sub_f32_e32 v0, v1, v0
	v_fmamk_f32 v95, v0, 0x3d800000, v94
	ds_read_b128 v[210:213], v5 offset:1792
	ds_read_b128 v[214:217], v5 offset:1808
	ds_read_b128 v[218:221], v5 offset:1824
	ds_read_b128 v[222:225], v5 offset:1840
	s_waitcnt lgkmcnt(4)
	v_fma_f32 v96, v65, v240, v69
	v_fmac_f32_e32 v96, v66, v241
	v_fmac_f32_e32 v96, v67, v242
	v_fmac_f32_e32 v96, v68, v243
	v_fmac_f32_e32 v96, v55, v244
	v_fmac_f32_e32 v96, v62, v245
	v_fmac_f32_e32 v96, v63, v246
	v_fmac_f32_e32 v96, v64, v247
	v_fmac_f32_e32 v96, v52, v248
	v_fmac_f32_e32 v96, v53, v249
	v_fmac_f32_e32 v96, v50, v250
	v_fmac_f32_e32 v96, v51, v251
	v_pk_mul_f32 v[0:1], v[48:49], v[252:253]
	s_nop 0
	v_add_f32_e32 v0, v96, v0
	v_add_f32_e32 v96, v0, v1
	v_pk_mul_f32 v[0:1], v[46:47], v[254:255]
	s_nop 0
	v_add_f32_e32 v0, v96, v0
	v_add_f32_e32 v0, v0, v1
	v_min_f32_e32 v1, 0, v0
	v_mul_f32_e64 v0, |v0|, s11
	v_exp_f32_e32 v0, v0
	s_nop 0
	v_add_f32_e32 v0, 1.0, v0
	v_cmp_gt_f32_e32 vcc, s12, v0
	s_nop 1
	v_cndmask_b32_e64 v2, 0, 32, vcc
	v_ldexp_f32 v0, v0, v2
	v_log_f32_e32 v0, v0
	s_nop 0
	v_mul_f32_e32 v2, 0x3f317217, v0
	v_fma_f32 v2, v0, s13, -v2
	v_fmac_f32_e32 v2, 0x3377d1cf, v0
	v_fmac_f32_e32 v2, 0x3f317217, v0
	v_cmp_lt_f32_e64 s[0:1], |v0|, s36
	s_nop 1
	v_cndmask_b32_e64 v0, v0, v2, s[0:1]
	v_cndmask_b32_e32 v2, 0, v60, vcc
	v_sub_f32_e32 v0, v0, v2
	v_sub_f32_e32 v0, v1, v0
	v_fmamk_f32 v96, v0, 0x3d800000, v95
	ds_read_b128 v[240:243], v5 offset:1856
	ds_read_b128 v[244:247], v5 offset:1872
	ds_read_b128 v[248:251], v5 offset:1888
	ds_read_b128 v[252:255], v5 offset:1904
	s_waitcnt lgkmcnt(4)
	v_fma_f32 v97, v65, v210, v69
	v_fmac_f32_e32 v97, v66, v211
	v_fmac_f32_e32 v97, v67, v212
	v_fmac_f32_e32 v97, v68, v213
	v_fmac_f32_e32 v97, v55, v214
	v_fmac_f32_e32 v97, v62, v215
	v_fmac_f32_e32 v97, v63, v216
	v_fmac_f32_e32 v97, v64, v217
	v_fmac_f32_e32 v97, v52, v218
	v_fmac_f32_e32 v97, v53, v219
	v_fmac_f32_e32 v97, v50, v220
	v_fmac_f32_e32 v97, v51, v221
	v_pk_mul_f32 v[0:1], v[48:49], v[222:223]
	s_nop 0
	v_add_f32_e32 v0, v97, v0
	v_add_f32_e32 v97, v0, v1
	v_pk_mul_f32 v[0:1], v[46:47], v[224:225]
	s_nop 0
	v_add_f32_e32 v0, v97, v0
	v_add_f32_e32 v0, v0, v1
	v_min_f32_e32 v1, 0, v0
	v_mul_f32_e64 v0, |v0|, s11
	v_exp_f32_e32 v0, v0
	s_nop 0
	v_add_f32_e32 v0, 1.0, v0
	v_cmp_gt_f32_e32 vcc, s12, v0
	s_nop 1
	v_cndmask_b32_e64 v2, 0, 32, vcc
	v_ldexp_f32 v0, v0, v2
	v_log_f32_e32 v0, v0
	s_nop 0
	v_mul_f32_e32 v2, 0x3f317217, v0
	v_fma_f32 v2, v0, s13, -v2
	v_fmac_f32_e32 v2, 0x3377d1cf, v0
	v_fmac_f32_e32 v2, 0x3f317217, v0
	v_cmp_lt_f32_e64 s[0:1], |v0|, s36
	s_nop 1
	v_cndmask_b32_e64 v0, v0, v2, s[0:1]
	v_cndmask_b32_e32 v2, 0, v60, vcc
	v_sub_f32_e32 v0, v0, v2
	v_sub_f32_e32 v0, v1, v0
	v_fmamk_f32 v97, v0, 0x3d800000, v96
	ds_read_b128 v[210:213], v5 offset:1920
	ds_read_b128 v[214:217], v5 offset:1936
	ds_read_b128 v[218:221], v5 offset:1952
	ds_read_b128 v[222:225], v5 offset:1968
	s_waitcnt lgkmcnt(4)
; __device__ __forceinline__ float log_sigmoid(float x) { return fminf(x, 0.f) - __logf(1.f + __expf(-fabsf(x))); }
; __device__ __forceinline__ void gla_prep_item(LAS unsigned char* lds, int item, const bf16_t* Z, const float* W2, const float* Bg, bf16_t* KDT, float* DEC) {
;     ...
; #pragma unroll
;     for (int t = 0; t < 64; ++t) {
;         float x = bias;
; #pragma unroll
;         for (int r = 0; r < 16; ++r) x += zgs[t * 16 + r] * w[r];
;         gv[t] = log_sigmoid(x) * (1.f / 16.f); bend += gv[t];
	v_fma_f32 v98, v65, v240, v69
	v_fmac_f32_e32 v98, v66, v241
	v_fmac_f32_e32 v98, v67, v242
	v_fmac_f32_e32 v98, v68, v243
	v_fmac_f32_e32 v98, v55, v244
	v_fmac_f32_e32 v98, v62, v245
	v_fmac_f32_e32 v98, v63, v246
	v_fmac_f32_e32 v98, v64, v247
	v_fmac_f32_e32 v98, v52, v248
	v_fmac_f32_e32 v98, v53, v249
	v_fmac_f32_e32 v98, v50, v250
	v_fmac_f32_e32 v98, v51, v251
	v_pk_mul_f32 v[0:1], v[48:49], v[252:253]
	s_nop 0
	v_add_f32_e32 v0, v98, v0
	v_add_f32_e32 v98, v0, v1
	v_pk_mul_f32 v[0:1], v[46:47], v[254:255]
	s_nop 0
	v_add_f32_e32 v0, v98, v0
	v_add_f32_e32 v0, v0, v1
	v_min_f32_e32 v1, 0, v0
	v_mul_f32_e64 v0, |v0|, s11
	v_exp_f32_e32 v0, v0
	s_nop 0
	v_add_f32_e32 v0, 1.0, v0
	v_cmp_gt_f32_e32 vcc, s12, v0
	s_nop 1
	v_cndmask_b32_e64 v2, 0, 32, vcc
	v_ldexp_f32 v0, v0, v2
	v_log_f32_e32 v0, v0
	s_nop 0
	v_mul_f32_e32 v2, 0x3f317217, v0
	v_fma_f32 v2, v0, s13, -v2
	v_fmac_f32_e32 v2, 0x3377d1cf, v0
	v_fmac_f32_e32 v2, 0x3f317217, v0
	v_cmp_lt_f32_e64 s[0:1], |v0|, s36
	s_nop 1
	v_cndmask_b32_e64 v0, v0, v2, s[0:1]
	v_cndmask_b32_e32 v2, 0, v60, vcc
	v_sub_f32_e32 v0, v0, v2
	v_sub_f32_e32 v0, v1, v0
	v_fmamk_f32 v98, v0, 0x3d800000, v97
	ds_read_b128 v[240:243], v5 offset:1984
	ds_read_b128 v[244:247], v5 offset:2000
	ds_read_b128 v[248:251], v5 offset:2016
	ds_read_b128 v[252:255], v5 offset:2032
	s_waitcnt lgkmcnt(4)
	v_fma_f32 v99, v65, v210, v69
	v_fmac_f32_e32 v99, v66, v211
	v_fmac_f32_e32 v99, v67, v212
	v_fmac_f32_e32 v99, v68, v213
	v_fmac_f32_e32 v99, v55, v214
	v_fmac_f32_e32 v99, v62, v215
	v_fmac_f32_e32 v99, v63, v216
	v_fmac_f32_e32 v99, v64, v217
	v_fmac_f32_e32 v99, v52, v218
	v_fmac_f32_e32 v99, v53, v219
	v_fmac_f32_e32 v99, v50, v220
	v_fmac_f32_e32 v99, v51, v221
	v_pk_mul_f32 v[0:1], v[48:49], v[222:223]
	s_nop 0
	v_add_f32_e32 v0, v99, v0
	v_add_f32_e32 v99, v0, v1
	v_pk_mul_f32 v[0:1], v[46:47], v[224:225]
	s_nop 0
	v_add_f32_e32 v0, v99, v0
	v_add_f32_e32 v0, v0, v1
	v_min_f32_e32 v1, 0, v0
	v_mul_f32_e64 v0, |v0|, s11
	v_exp_f32_e32 v0, v0
	s_nop 0
	v_add_f32_e32 v0, 1.0, v0
	v_cmp_gt_f32_e32 vcc, s12, v0
	s_nop 1
	v_cndmask_b32_e64 v2, 0, 32, vcc
	v_ldexp_f32 v0, v0, v2
	v_log_f32_e32 v0, v0
	s_nop 0
	v_mul_f32_e32 v2, 0x3f317217, v0
	v_fma_f32 v2, v0, s13, -v2
	v_fmac_f32_e32 v2, 0x3377d1cf, v0
	v_fmac_f32_e32 v2, 0x3f317217, v0
	v_cmp_lt_f32_e64 s[0:1], |v0|, s36
	s_nop 1
	v_cndmask_b32_e64 v0, v0, v2, s[0:1]
	v_cndmask_b32_e32 v2, 0, v60, vcc
	v_sub_f32_e32 v0, v0, v2
	v_sub_f32_e32 v0, v1, v0
	v_fmamk_f32 v99, v0, 0x3d800000, v98
	ds_read_b128 v[210:213], v5 offset:2048
	ds_read_b128 v[214:217], v5 offset:2064
	ds_read_b128 v[218:221], v5 offset:2080
	ds_read_b128 v[222:225], v5 offset:2096
	s_waitcnt lgkmcnt(4)
	v_fma_f32 v100, v65, v240, v69
	v_fmac_f32_e32 v100, v66, v241
	v_fmac_f32_e32 v100, v67, v242
	v_fmac_f32_e32 v100, v68, v243
	v_fmac_f32_e32 v100, v55, v244
	v_fmac_f32_e32 v100, v62, v245
	v_fmac_f32_e32 v100, v63, v246
	v_fmac_f32_e32 v100, v64, v247
	v_fmac_f32_e32 v100, v52, v248
	v_fmac_f32_e32 v100, v53, v249
	v_fmac_f32_e32 v100, v50, v250
	v_fmac_f32_e32 v100, v51, v251
	v_pk_mul_f32 v[0:1], v[48:49], v[252:253]
	s_nop 0
	v_add_f32_e32 v0, v100, v0
	v_add_f32_e32 v100, v0, v1
	v_pk_mul_f32 v[0:1], v[46:47], v[254:255]
	s_nop 0
	v_add_f32_e32 v0, v100, v0
	v_add_f32_e32 v0, v0, v1
	v_min_f32_e32 v1, 0, v0
	v_mul_f32_e64 v0, |v0|, s11
	v_exp_f32_e32 v0, v0
	s_nop 0
	v_add_f32_e32 v0, 1.0, v0
	v_cmp_gt_f32_e32 vcc, s12, v0
	s_nop 1
	v_cndmask_b32_e64 v2, 0, 32, vcc
	v_ldexp_f32 v0, v0, v2
	v_log_f32_e32 v0, v0
	s_nop 0
	v_mul_f32_e32 v2, 0x3f317217, v0
	v_fma_f32 v2, v0, s13, -v2
	v_fmac_f32_e32 v2, 0x3377d1cf, v0
	v_fmac_f32_e32 v2, 0x3f317217, v0
	v_cmp_lt_f32_e64 s[0:1], |v0|, s36
	s_nop 1
	v_cndmask_b32_e64 v0, v0, v2, s[0:1]
	v_cndmask_b32_e32 v2, 0, v60, vcc
	v_sub_f32_e32 v0, v0, v2
	v_sub_f32_e32 v0, v1, v0
	v_fmamk_f32 v100, v0, 0x3d800000, v99
	ds_read_b128 v[240:243], v5 offset:2112
	ds_read_b128 v[244:247], v5 offset:2128
	ds_read_b128 v[248:251], v5 offset:2144
	ds_read_b128 v[252:255], v5 offset:2160
	s_waitcnt lgkmcnt(4)
	v_fma_f32 v101, v65, v210, v69
	v_fmac_f32_e32 v101, v66, v211
	v_fmac_f32_e32 v101, v67, v212
	v_fmac_f32_e32 v101, v68, v213
	v_fmac_f32_e32 v101, v55, v214
	v_fmac_f32_e32 v101, v62, v215
	v_fmac_f32_e32 v101, v63, v216
	v_fmac_f32_e32 v101, v64, v217
	v_fmac_f32_e32 v101, v52, v218
	v_fmac_f32_e32 v101, v53, v219
	v_fmac_f32_e32 v101, v50, v220
	v_fmac_f32_e32 v101, v51, v221
	v_pk_mul_f32 v[0:1], v[48:49], v[222:223]
	s_nop 0
	v_add_f32_e32 v0, v101, v0
	v_add_f32_e32 v101, v0, v1
	v_pk_mul_f32 v[0:1], v[46:47], v[224:225]
	s_nop 0
	v_add_f32_e32 v0, v101, v0
	v_add_f32_e32 v0, v0, v1
	v_min_f32_e32 v1, 0, v0
	v_mul_f32_e64 v0, |v0|, s11
	v_exp_f32_e32 v0, v0
	s_nop 0
	v_add_f32_e32 v0, 1.0, v0
	v_cmp_gt_f32_e32 vcc, s12, v0
	s_nop 1
	v_cndmask_b32_e64 v2, 0, 32, vcc
	v_ldexp_f32 v0, v0, v2
	v_log_f32_e32 v0, v0
	s_nop 0
	v_mul_f32_e32 v2, 0x3f317217, v0
	v_fma_f32 v2, v0, s13, -v2
	v_fmac_f32_e32 v2, 0x3377d1cf, v0
	v_fmac_f32_e32 v2, 0x3f317217, v0
	v_cmp_lt_f32_e64 s[0:1], |v0|, s36
	s_nop 1
	v_cndmask_b32_e64 v0, v0, v2, s[0:1]
	v_cndmask_b32_e32 v2, 0, v60, vcc
	v_sub_f32_e32 v0, v0, v2
	v_sub_f32_e32 v0, v1, v0
	v_fmamk_f32 v101, v0, 0x3d800000, v100
	ds_read_b128 v[210:213], v5 offset:2176
	ds_read_b128 v[214:217], v5 offset:2192
	ds_read_b128 v[218:221], v5 offset:2208
	ds_read_b128 v[222:225], v5 offset:2224
	s_waitcnt lgkmcnt(4)
; __device__ __forceinline__ float log_sigmoid(float x) { return fminf(x, 0.f) - __logf(1.f + __expf(-fabsf(x))); }
; __device__ __forceinline__ void gla_prep_item(LAS unsigned char* lds, int item, const bf16_t* Z, const float* W2, const float* Bg, bf16_t* KDT, float* DEC) {
;     ...
; #pragma unroll
;     for (int t = 0; t < 64; ++t) {
;         float x = bias;
; #pragma unroll
;         for (int r = 0; r < 16; ++r) x += zgs[t * 16 + r] * w[r];
;         gv[t] = log_sigmoid(x) * (1.f / 16.f); bend += gv[t];
	v_fma_f32 v102, v65, v240, v69
	v_fmac_f32_e32 v102, v66, v241
	v_fmac_f32_e32 v102, v67, v242
	v_fmac_f32_e32 v102, v68, v243
	v_fmac_f32_e32 v102, v55, v244
	v_fmac_f32_e32 v102, v62, v245
	v_fmac_f32_e32 v102, v63, v246
	v_fmac_f32_e32 v102, v64, v247
	v_fmac_f32_e32 v102, v52, v248
	v_fmac_f32_e32 v102, v53, v249
	v_fmac_f32_e32 v102, v50, v250
	v_fmac_f32_e32 v102, v51, v251
	v_pk_mul_f32 v[0:1], v[48:49], v[252:253]
	s_nop 0
	v_add_f32_e32 v0, v102, v0
	v_add_f32_e32 v102, v0, v1
	v_pk_mul_f32 v[0:1], v[46:47], v[254:255]
	s_nop 0
	v_add_f32_e32 v0, v102, v0
	v_add_f32_e32 v0, v0, v1
	v_min_f32_e32 v1, 0, v0
	v_mul_f32_e64 v0, |v0|, s11
	v_exp_f32_e32 v0, v0
	s_nop 0
	v_add_f32_e32 v0, 1.0, v0
	v_cmp_gt_f32_e32 vcc, s12, v0
	s_nop 1
	v_cndmask_b32_e64 v2, 0, 32, vcc
	v_ldexp_f32 v0, v0, v2
	v_log_f32_e32 v0, v0
	s_nop 0
	v_mul_f32_e32 v2, 0x3f317217, v0
	v_fma_f32 v2, v0, s13, -v2
	v_fmac_f32_e32 v2, 0x3377d1cf, v0
	v_fmac_f32_e32 v2, 0x3f317217, v0
	v_cmp_lt_f32_e64 s[0:1], |v0|, s36
	s_nop 1
	v_cndmask_b32_e64 v0, v0, v2, s[0:1]
	v_cndmask_b32_e32 v2, 0, v60, vcc
	v_sub_f32_e32 v0, v0, v2
	v_sub_f32_e32 v0, v1, v0
	v_fmamk_f32 v102, v0, 0x3d800000, v101
	ds_read_b128 v[240:243], v5 offset:2240
	ds_read_b128 v[244:247], v5 offset:2256
	ds_read_b128 v[248:251], v5 offset:2272
	ds_read_b128 v[252:255], v5 offset:2288
	s_waitcnt lgkmcnt(4)
	v_fma_f32 v103, v65, v210, v69
	v_fmac_f32_e32 v103, v66, v211
	v_fmac_f32_e32 v103, v67, v212
	v_fmac_f32_e32 v103, v68, v213
	v_fmac_f32_e32 v103, v55, v214
	v_fmac_f32_e32 v103, v62, v215
	v_fmac_f32_e32 v103, v63, v216
	v_fmac_f32_e32 v103, v64, v217
	v_fmac_f32_e32 v103, v52, v218
	v_fmac_f32_e32 v103, v53, v219
	v_fmac_f32_e32 v103, v50, v220
	v_fmac_f32_e32 v103, v51, v221
	v_pk_mul_f32 v[0:1], v[48:49], v[222:223]
	s_nop 0
	v_add_f32_e32 v0, v103, v0
	v_add_f32_e32 v103, v0, v1
	v_pk_mul_f32 v[0:1], v[46:47], v[224:225]
	s_nop 0
	v_add_f32_e32 v0, v103, v0
	v_add_f32_e32 v0, v0, v1
	v_min_f32_e32 v1, 0, v0
	v_mul_f32_e64 v0, |v0|, s11
	v_exp_f32_e32 v0, v0
	s_nop 0
	v_add_f32_e32 v0, 1.0, v0
	v_cmp_gt_f32_e32 vcc, s12, v0
	s_nop 1
	v_cndmask_b32_e64 v2, 0, 32, vcc
	v_ldexp_f32 v0, v0, v2
	v_log_f32_e32 v0, v0
	s_nop 0
	v_mul_f32_e32 v2, 0x3f317217, v0
	v_fma_f32 v2, v0, s13, -v2
	v_fmac_f32_e32 v2, 0x3377d1cf, v0
	v_fmac_f32_e32 v2, 0x3f317217, v0
	v_cmp_lt_f32_e64 s[0:1], |v0|, s36
	s_nop 1
	v_cndmask_b32_e64 v0, v0, v2, s[0:1]
	v_cndmask_b32_e32 v2, 0, v60, vcc
	v_sub_f32_e32 v0, v0, v2
	v_sub_f32_e32 v0, v1, v0
	v_fmamk_f32 v103, v0, 0x3d800000, v102
	ds_read_b128 v[210:213], v5 offset:2304
	ds_read_b128 v[214:217], v5 offset:2320
	ds_read_b128 v[218:221], v5 offset:2336
	ds_read_b128 v[222:225], v5 offset:2352
	s_waitcnt lgkmcnt(4)
	v_fma_f32 v104, v65, v240, v69
	v_fmac_f32_e32 v104, v66, v241
	v_fmac_f32_e32 v104, v67, v242
	v_fmac_f32_e32 v104, v68, v243
	v_fmac_f32_e32 v104, v55, v244
	v_fmac_f32_e32 v104, v62, v245
	v_fmac_f32_e32 v104, v63, v246
	v_fmac_f32_e32 v104, v64, v247
	v_fmac_f32_e32 v104, v52, v248
	v_fmac_f32_e32 v104, v53, v249
	v_fmac_f32_e32 v104, v50, v250
	v_fmac_f32_e32 v104, v51, v251
	v_pk_mul_f32 v[0:1], v[48:49], v[252:253]
	s_nop 0
	v_add_f32_e32 v0, v104, v0
	v_add_f32_e32 v104, v0, v1
	v_pk_mul_f32 v[0:1], v[46:47], v[254:255]
	s_nop 0
	v_add_f32_e32 v0, v104, v0
	v_add_f32_e32 v0, v0, v1
	v_min_f32_e32 v1, 0, v0
	v_mul_f32_e64 v0, |v0|, s11
	v_exp_f32_e32 v0, v0
	s_nop 0
	v_add_f32_e32 v0, 1.0, v0
	v_cmp_gt_f32_e32 vcc, s12, v0
	s_nop 1
	v_cndmask_b32_e64 v2, 0, 32, vcc
	v_ldexp_f32 v0, v0, v2
	v_log_f32_e32 v0, v0
	s_nop 0
	v_mul_f32_e32 v2, 0x3f317217, v0
	v_fma_f32 v2, v0, s13, -v2
	v_fmac_f32_e32 v2, 0x3377d1cf, v0
	v_fmac_f32_e32 v2, 0x3f317217, v0
	v_cmp_lt_f32_e64 s[0:1], |v0|, s36
	s_nop 1
	v_cndmask_b32_e64 v0, v0, v2, s[0:1]
	v_cndmask_b32_e32 v2, 0, v60, vcc
	v_sub_f32_e32 v0, v0, v2
	v_sub_f32_e32 v0, v1, v0
	v_fmamk_f32 v104, v0, 0x3d800000, v103
	ds_read_b128 v[240:243], v5 offset:2368
	ds_read_b128 v[244:247], v5 offset:2384
	ds_read_b128 v[248:251], v5 offset:2400
	ds_read_b128 v[252:255], v5 offset:2416
	s_waitcnt lgkmcnt(4)
	v_fma_f32 v105, v65, v210, v69
	v_fmac_f32_e32 v105, v66, v211
	v_fmac_f32_e32 v105, v67, v212
	v_fmac_f32_e32 v105, v68, v213
	v_fmac_f32_e32 v105, v55, v214
	v_fmac_f32_e32 v105, v62, v215
	v_fmac_f32_e32 v105, v63, v216
	v_fmac_f32_e32 v105, v64, v217
	v_fmac_f32_e32 v105, v52, v218
	v_fmac_f32_e32 v105, v53, v219
	v_fmac_f32_e32 v105, v50, v220
	v_fmac_f32_e32 v105, v51, v221
	v_pk_mul_f32 v[0:1], v[48:49], v[222:223]
	s_nop 0
	v_add_f32_e32 v0, v105, v0
	v_add_f32_e32 v105, v0, v1
	v_pk_mul_f32 v[0:1], v[46:47], v[224:225]
	s_nop 0
	v_add_f32_e32 v0, v105, v0
	v_add_f32_e32 v0, v0, v1
	v_min_f32_e32 v1, 0, v0
	v_mul_f32_e64 v0, |v0|, s11
	v_exp_f32_e32 v0, v0
	s_nop 0
	v_add_f32_e32 v0, 1.0, v0
	v_cmp_gt_f32_e32 vcc, s12, v0
	s_nop 1
	v_cndmask_b32_e64 v2, 0, 32, vcc
	v_ldexp_f32 v0, v0, v2
	v_log_f32_e32 v0, v0
	s_nop 0
	v_mul_f32_e32 v2, 0x3f317217, v0
	v_fma_f32 v2, v0, s13, -v2
	v_fmac_f32_e32 v2, 0x3377d1cf, v0
	v_fmac_f32_e32 v2, 0x3f317217, v0
	v_cmp_lt_f32_e64 s[0:1], |v0|, s36
	s_nop 1
	v_cndmask_b32_e64 v0, v0, v2, s[0:1]
	v_cndmask_b32_e32 v2, 0, v60, vcc
	v_sub_f32_e32 v0, v0, v2
	v_sub_f32_e32 v0, v1, v0
	v_fmamk_f32 v105, v0, 0x3d800000, v104
	ds_read_b128 v[210:213], v5 offset:2432
	ds_read_b128 v[214:217], v5 offset:2448
	ds_read_b128 v[218:221], v5 offset:2464
	ds_read_b128 v[222:225], v5 offset:2480
	s_waitcnt lgkmcnt(4)
; __device__ __forceinline__ float log_sigmoid(float x) { return fminf(x, 0.f) - __logf(1.f + __expf(-fabsf(x))); }
; __device__ __forceinline__ void gla_prep_item(LAS unsigned char* lds, int item, const bf16_t* Z, const float* W2, const float* Bg, bf16_t* KDT, float* DEC) {
;     ...
; #pragma unroll
;     for (int t = 0; t < 64; ++t) {
;         float x = bias;
; #pragma unroll
;         for (int r = 0; r < 16; ++r) x += zgs[t * 16 + r] * w[r];
;         gv[t] = log_sigmoid(x) * (1.f / 16.f); bend += gv[t];
	v_fma_f32 v106, v65, v240, v69
	v_fmac_f32_e32 v106, v66, v241
	v_fmac_f32_e32 v106, v67, v242
	v_fmac_f32_e32 v106, v68, v243
	v_fmac_f32_e32 v106, v55, v244
	v_fmac_f32_e32 v106, v62, v245
	v_fmac_f32_e32 v106, v63, v246
	v_fmac_f32_e32 v106, v64, v247
	v_fmac_f32_e32 v106, v52, v248
	v_fmac_f32_e32 v106, v53, v249
	v_fmac_f32_e32 v106, v50, v250
	v_fmac_f32_e32 v106, v51, v251
	v_pk_mul_f32 v[0:1], v[48:49], v[252:253]
	s_nop 0
	v_add_f32_e32 v0, v106, v0
	v_add_f32_e32 v106, v0, v1
	v_pk_mul_f32 v[0:1], v[46:47], v[254:255]
	s_nop 0
	v_add_f32_e32 v0, v106, v0
	v_add_f32_e32 v0, v0, v1
	v_min_f32_e32 v1, 0, v0
	v_mul_f32_e64 v0, |v0|, s11
	v_exp_f32_e32 v0, v0
	s_nop 0
	v_add_f32_e32 v0, 1.0, v0
	v_cmp_gt_f32_e32 vcc, s12, v0
	s_nop 1
	v_cndmask_b32_e64 v2, 0, 32, vcc
	v_ldexp_f32 v0, v0, v2
	v_log_f32_e32 v0, v0
	s_nop 0
	v_mul_f32_e32 v2, 0x3f317217, v0
	v_fma_f32 v2, v0, s13, -v2
	v_fmac_f32_e32 v2, 0x3377d1cf, v0
	v_fmac_f32_e32 v2, 0x3f317217, v0
	v_cmp_lt_f32_e64 s[0:1], |v0|, s36
	s_nop 1
	v_cndmask_b32_e64 v0, v0, v2, s[0:1]
	v_cndmask_b32_e32 v2, 0, v60, vcc
	v_sub_f32_e32 v0, v0, v2
	v_sub_f32_e32 v0, v1, v0
	v_fmamk_f32 v106, v0, 0x3d800000, v105
	ds_read_b128 v[240:243], v5 offset:2496
	ds_read_b128 v[244:247], v5 offset:2512
	ds_read_b128 v[248:251], v5 offset:2528
	ds_read_b128 v[252:255], v5 offset:2544
	s_waitcnt lgkmcnt(4)
	v_fma_f32 v107, v65, v210, v69
	v_fmac_f32_e32 v107, v66, v211
	v_fmac_f32_e32 v107, v67, v212
	v_fmac_f32_e32 v107, v68, v213
	v_fmac_f32_e32 v107, v55, v214
	v_fmac_f32_e32 v107, v62, v215
	v_fmac_f32_e32 v107, v63, v216
	v_fmac_f32_e32 v107, v64, v217
	v_fmac_f32_e32 v107, v52, v218
	v_fmac_f32_e32 v107, v53, v219
	v_fmac_f32_e32 v107, v50, v220
	v_fmac_f32_e32 v107, v51, v221
	v_pk_mul_f32 v[0:1], v[48:49], v[222:223]
	s_nop 0
	v_add_f32_e32 v0, v107, v0
	v_add_f32_e32 v107, v0, v1
	v_pk_mul_f32 v[0:1], v[46:47], v[224:225]
	s_nop 0
	v_add_f32_e32 v0, v107, v0
	v_add_f32_e32 v0, v0, v1
	v_min_f32_e32 v1, 0, v0
	v_mul_f32_e64 v0, |v0|, s11
	v_exp_f32_e32 v0, v0
	s_nop 0
	v_add_f32_e32 v0, 1.0, v0
	v_cmp_gt_f32_e32 vcc, s12, v0
	s_nop 1
	v_cndmask_b32_e64 v2, 0, 32, vcc
	v_ldexp_f32 v0, v0, v2
	v_log_f32_e32 v0, v0
	s_nop 0
	v_mul_f32_e32 v2, 0x3f317217, v0
	v_fma_f32 v2, v0, s13, -v2
	v_fmac_f32_e32 v2, 0x3377d1cf, v0
	v_fmac_f32_e32 v2, 0x3f317217, v0
	v_cmp_lt_f32_e64 s[0:1], |v0|, s36
	s_nop 1
	v_cndmask_b32_e64 v0, v0, v2, s[0:1]
	v_cndmask_b32_e32 v2, 0, v60, vcc
	v_sub_f32_e32 v0, v0, v2
	v_sub_f32_e32 v0, v1, v0
	v_fmamk_f32 v107, v0, 0x3d800000, v106
	ds_read_b128 v[210:213], v5 offset:2560
	ds_read_b128 v[214:217], v5 offset:2576
	ds_read_b128 v[218:221], v5 offset:2592
	ds_read_b128 v[222:225], v5 offset:2608
	s_waitcnt lgkmcnt(4)
	v_fma_f32 v108, v65, v240, v69
	v_fmac_f32_e32 v108, v66, v241
	v_fmac_f32_e32 v108, v67, v242
	v_fmac_f32_e32 v108, v68, v243
	v_fmac_f32_e32 v108, v55, v244
	v_fmac_f32_e32 v108, v62, v245
	v_fmac_f32_e32 v108, v63, v246
	v_fmac_f32_e32 v108, v64, v247
	v_fmac_f32_e32 v108, v52, v248
	v_fmac_f32_e32 v108, v53, v249
	v_fmac_f32_e32 v108, v50, v250
	v_fmac_f32_e32 v108, v51, v251
	v_pk_mul_f32 v[0:1], v[48:49], v[252:253]
	s_nop 0
	v_add_f32_e32 v0, v108, v0
	v_add_f32_e32 v108, v0, v1
	v_pk_mul_f32 v[0:1], v[46:47], v[254:255]
	s_nop 0
	v_add_f32_e32 v0, v108, v0
	v_add_f32_e32 v0, v0, v1
	v_min_f32_e32 v1, 0, v0
	v_mul_f32_e64 v0, |v0|, s11
	v_exp_f32_e32 v0, v0
	s_nop 0
	v_add_f32_e32 v0, 1.0, v0
	v_cmp_gt_f32_e32 vcc, s12, v0
	s_nop 1
	v_cndmask_b32_e64 v2, 0, 32, vcc
	v_ldexp_f32 v0, v0, v2
	v_log_f32_e32 v0, v0
	s_nop 0
	v_mul_f32_e32 v2, 0x3f317217, v0
	v_fma_f32 v2, v0, s13, -v2
	v_fmac_f32_e32 v2, 0x3377d1cf, v0
	v_fmac_f32_e32 v2, 0x3f317217, v0
	v_cmp_lt_f32_e64 s[0:1], |v0|, s36
	s_nop 1
	v_cndmask_b32_e64 v0, v0, v2, s[0:1]
	v_cndmask_b32_e32 v2, 0, v60, vcc
	v_sub_f32_e32 v0, v0, v2
	v_sub_f32_e32 v0, v1, v0
	v_fmamk_f32 v108, v0, 0x3d800000, v107
	ds_read_b128 v[240:243], v5 offset:2624
	ds_read_b128 v[244:247], v5 offset:2640
	ds_read_b128 v[248:251], v5 offset:2656
	ds_read_b128 v[252:255], v5 offset:2672
	s_waitcnt lgkmcnt(4)
	v_fma_f32 v109, v65, v210, v69
	v_fmac_f32_e32 v109, v66, v211
	v_fmac_f32_e32 v109, v67, v212
	v_fmac_f32_e32 v109, v68, v213
	v_fmac_f32_e32 v109, v55, v214
	v_fmac_f32_e32 v109, v62, v215
	v_fmac_f32_e32 v109, v63, v216
	v_fmac_f32_e32 v109, v64, v217
	v_fmac_f32_e32 v109, v52, v218
	v_fmac_f32_e32 v109, v53, v219
	v_fmac_f32_e32 v109, v50, v220
	v_fmac_f32_e32 v109, v51, v221
	v_pk_mul_f32 v[0:1], v[48:49], v[222:223]
	s_nop 0
	v_add_f32_e32 v0, v109, v0
	v_add_f32_e32 v109, v0, v1
	v_pk_mul_f32 v[0:1], v[46:47], v[224:225]
	s_nop 0
	v_add_f32_e32 v0, v109, v0
	v_add_f32_e32 v0, v0, v1
	v_min_f32_e32 v1, 0, v0
	v_mul_f32_e64 v0, |v0|, s11
	v_exp_f32_e32 v0, v0
	s_nop 0
	v_add_f32_e32 v0, 1.0, v0
	v_cmp_gt_f32_e32 vcc, s12, v0
	s_nop 1
	v_cndmask_b32_e64 v2, 0, 32, vcc
	v_ldexp_f32 v0, v0, v2
	v_log_f32_e32 v0, v0
	s_nop 0
	v_mul_f32_e32 v2, 0x3f317217, v0
	v_fma_f32 v2, v0, s13, -v2
	v_fmac_f32_e32 v2, 0x3377d1cf, v0
	v_fmac_f32_e32 v2, 0x3f317217, v0
	v_cmp_lt_f32_e64 s[0:1], |v0|, s36
	s_nop 1
	v_cndmask_b32_e64 v0, v0, v2, s[0:1]
	v_cndmask_b32_e32 v2, 0, v60, vcc
	v_sub_f32_e32 v0, v0, v2
	v_sub_f32_e32 v0, v1, v0
	v_fmamk_f32 v109, v0, 0x3d800000, v108
	ds_read_b128 v[210:213], v5 offset:2688
	ds_read_b128 v[214:217], v5 offset:2704
	ds_read_b128 v[218:221], v5 offset:2720
	ds_read_b128 v[222:225], v5 offset:2736
	s_waitcnt lgkmcnt(4)
; __device__ __forceinline__ float log_sigmoid(float x) { return fminf(x, 0.f) - __logf(1.f + __expf(-fabsf(x))); }
; __device__ __forceinline__ void gla_prep_item(LAS unsigned char* lds, int item, const bf16_t* Z, const float* W2, const float* Bg, bf16_t* KDT, float* DEC) {
;     ...
; #pragma unroll
;     for (int t = 0; t < 64; ++t) {
;         float x = bias;
; #pragma unroll
;         for (int r = 0; r < 16; ++r) x += zgs[t * 16 + r] * w[r];
;         gv[t] = log_sigmoid(x) * (1.f / 16.f); bend += gv[t];
	v_fma_f32 v110, v65, v240, v69
	v_fmac_f32_e32 v110, v66, v241
	v_fmac_f32_e32 v110, v67, v242
	v_fmac_f32_e32 v110, v68, v243
	v_fmac_f32_e32 v110, v55, v244
	v_fmac_f32_e32 v110, v62, v245
	v_fmac_f32_e32 v110, v63, v246
	v_fmac_f32_e32 v110, v64, v247
	v_fmac_f32_e32 v110, v52, v248
	v_fmac_f32_e32 v110, v53, v249
	v_fmac_f32_e32 v110, v50, v250
	v_fmac_f32_e32 v110, v51, v251
	v_pk_mul_f32 v[0:1], v[48:49], v[252:253]
	s_nop 0
	v_add_f32_e32 v0, v110, v0
	v_add_f32_e32 v110, v0, v1
	v_pk_mul_f32 v[0:1], v[46:47], v[254:255]
	s_nop 0
	v_add_f32_e32 v0, v110, v0
	v_add_f32_e32 v0, v0, v1
	v_min_f32_e32 v1, 0, v0
	v_mul_f32_e64 v0, |v0|, s11
	v_exp_f32_e32 v0, v0
	s_nop 0
	v_add_f32_e32 v0, 1.0, v0
	v_cmp_gt_f32_e32 vcc, s12, v0
	s_nop 1
	v_cndmask_b32_e64 v2, 0, 32, vcc
	v_ldexp_f32 v0, v0, v2
	v_log_f32_e32 v0, v0
	s_nop 0
	v_mul_f32_e32 v2, 0x3f317217, v0
	v_fma_f32 v2, v0, s13, -v2
	v_fmac_f32_e32 v2, 0x3377d1cf, v0
	v_fmac_f32_e32 v2, 0x3f317217, v0
	v_cmp_lt_f32_e64 s[0:1], |v0|, s36
	s_nop 1
	v_cndmask_b32_e64 v0, v0, v2, s[0:1]
	v_cndmask_b32_e32 v2, 0, v60, vcc
	v_sub_f32_e32 v0, v0, v2
	v_sub_f32_e32 v0, v1, v0
	v_fmamk_f32 v110, v0, 0x3d800000, v109
	ds_read_b128 v[240:243], v5 offset:2752
	ds_read_b128 v[244:247], v5 offset:2768
	ds_read_b128 v[248:251], v5 offset:2784
	ds_read_b128 v[252:255], v5 offset:2800
	s_waitcnt lgkmcnt(4)
	v_fma_f32 v111, v65, v210, v69
	v_fmac_f32_e32 v111, v66, v211
	v_fmac_f32_e32 v111, v67, v212
	v_fmac_f32_e32 v111, v68, v213
	v_fmac_f32_e32 v111, v55, v214
	v_fmac_f32_e32 v111, v62, v215
	v_fmac_f32_e32 v111, v63, v216
	v_fmac_f32_e32 v111, v64, v217
	v_fmac_f32_e32 v111, v52, v218
	v_fmac_f32_e32 v111, v53, v219
	v_fmac_f32_e32 v111, v50, v220
	v_fmac_f32_e32 v111, v51, v221
	v_pk_mul_f32 v[0:1], v[48:49], v[222:223]
	s_nop 0
	v_add_f32_e32 v0, v111, v0
	v_add_f32_e32 v111, v0, v1
	v_pk_mul_f32 v[0:1], v[46:47], v[224:225]
	s_nop 0
	v_add_f32_e32 v0, v111, v0
	v_add_f32_e32 v0, v0, v1
	v_min_f32_e32 v1, 0, v0
	v_mul_f32_e64 v0, |v0|, s11
	v_exp_f32_e32 v0, v0
	s_nop 0
	v_add_f32_e32 v0, 1.0, v0
	v_cmp_gt_f32_e32 vcc, s12, v0
	s_nop 1
	v_cndmask_b32_e64 v2, 0, 32, vcc
	v_ldexp_f32 v0, v0, v2
	v_log_f32_e32 v0, v0
	s_nop 0
	v_mul_f32_e32 v2, 0x3f317217, v0
	v_fma_f32 v2, v0, s13, -v2
	v_fmac_f32_e32 v2, 0x3377d1cf, v0
	v_fmac_f32_e32 v2, 0x3f317217, v0
	v_cmp_lt_f32_e64 s[0:1], |v0|, s36
	s_nop 1
	v_cndmask_b32_e64 v0, v0, v2, s[0:1]
	v_cndmask_b32_e32 v2, 0, v60, vcc
	v_sub_f32_e32 v0, v0, v2
	v_sub_f32_e32 v0, v1, v0
	v_fmamk_f32 v111, v0, 0x3d800000, v110
	ds_read_b128 v[210:213], v5 offset:2816
	ds_read_b128 v[214:217], v5 offset:2832
	ds_read_b128 v[218:221], v5 offset:2848
	ds_read_b128 v[222:225], v5 offset:2864
	s_waitcnt lgkmcnt(4)
	v_fma_f32 v112, v65, v240, v69
	v_fmac_f32_e32 v112, v66, v241
	v_fmac_f32_e32 v112, v67, v242
	v_fmac_f32_e32 v112, v68, v243
	v_fmac_f32_e32 v112, v55, v244
	v_fmac_f32_e32 v112, v62, v245
	v_fmac_f32_e32 v112, v63, v246
	v_fmac_f32_e32 v112, v64, v247
	v_fmac_f32_e32 v112, v52, v248
	v_fmac_f32_e32 v112, v53, v249
	v_fmac_f32_e32 v112, v50, v250
	v_fmac_f32_e32 v112, v51, v251
	v_pk_mul_f32 v[0:1], v[48:49], v[252:253]
	s_nop 0
	v_add_f32_e32 v0, v112, v0
	v_add_f32_e32 v112, v0, v1
	v_pk_mul_f32 v[0:1], v[46:47], v[254:255]
	s_nop 0
	v_add_f32_e32 v0, v112, v0
	v_add_f32_e32 v0, v0, v1
	v_min_f32_e32 v1, 0, v0
	v_mul_f32_e64 v0, |v0|, s11
	v_exp_f32_e32 v0, v0
	s_nop 0
	v_add_f32_e32 v0, 1.0, v0
	v_cmp_gt_f32_e32 vcc, s12, v0
	s_nop 1
	v_cndmask_b32_e64 v2, 0, 32, vcc
	v_ldexp_f32 v0, v0, v2
	v_log_f32_e32 v0, v0
	s_nop 0
	v_mul_f32_e32 v2, 0x3f317217, v0
	v_fma_f32 v2, v0, s13, -v2
	v_fmac_f32_e32 v2, 0x3377d1cf, v0
	v_fmac_f32_e32 v2, 0x3f317217, v0
	v_cmp_lt_f32_e64 s[0:1], |v0|, s36
	s_nop 1
	v_cndmask_b32_e64 v0, v0, v2, s[0:1]
	v_cndmask_b32_e32 v2, 0, v60, vcc
	v_sub_f32_e32 v0, v0, v2
	v_sub_f32_e32 v0, v1, v0
	v_fmamk_f32 v112, v0, 0x3d800000, v111
	ds_read_b128 v[240:243], v5 offset:2880
	ds_read_b128 v[244:247], v5 offset:2896
	ds_read_b128 v[248:251], v5 offset:2912
	ds_read_b128 v[252:255], v5 offset:2928
	s_waitcnt lgkmcnt(4)
	v_fma_f32 v113, v65, v210, v69
	v_fmac_f32_e32 v113, v66, v211
	v_fmac_f32_e32 v113, v67, v212
	v_fmac_f32_e32 v113, v68, v213
	v_fmac_f32_e32 v113, v55, v214
	v_fmac_f32_e32 v113, v62, v215
	v_fmac_f32_e32 v113, v63, v216
	v_fmac_f32_e32 v113, v64, v217
	v_fmac_f32_e32 v113, v52, v218
	v_fmac_f32_e32 v113, v53, v219
	v_fmac_f32_e32 v113, v50, v220
	v_fmac_f32_e32 v113, v51, v221
	v_pk_mul_f32 v[0:1], v[48:49], v[222:223]
	s_nop 0
	v_add_f32_e32 v0, v113, v0
	v_add_f32_e32 v113, v0, v1
	v_pk_mul_f32 v[0:1], v[46:47], v[224:225]
	s_nop 0
	v_add_f32_e32 v0, v113, v0
	v_add_f32_e32 v0, v0, v1
	v_min_f32_e32 v1, 0, v0
	v_mul_f32_e64 v0, |v0|, s11
	v_exp_f32_e32 v0, v0
	s_nop 0
	v_add_f32_e32 v0, 1.0, v0
	v_cmp_gt_f32_e32 vcc, s12, v0
	s_nop 1
	v_cndmask_b32_e64 v2, 0, 32, vcc
	v_ldexp_f32 v0, v0, v2
	v_log_f32_e32 v0, v0
	s_nop 0
	v_mul_f32_e32 v2, 0x3f317217, v0
	v_fma_f32 v2, v0, s13, -v2
	v_fmac_f32_e32 v2, 0x3377d1cf, v0
	v_fmac_f32_e32 v2, 0x3f317217, v0
	v_cmp_lt_f32_e64 s[0:1], |v0|, s36
	s_nop 1
	v_cndmask_b32_e64 v0, v0, v2, s[0:1]
	v_cndmask_b32_e32 v2, 0, v60, vcc
	v_sub_f32_e32 v0, v0, v2
	v_sub_f32_e32 v0, v1, v0
	v_fmamk_f32 v113, v0, 0x3d800000, v112
	ds_read_b128 v[210:213], v5 offset:2944
	ds_read_b128 v[214:217], v5 offset:2960
	ds_read_b128 v[218:221], v5 offset:2976
	ds_read_b128 v[222:225], v5 offset:2992
	s_waitcnt lgkmcnt(4)
; __device__ __forceinline__ float log_sigmoid(float x) { return fminf(x, 0.f) - __logf(1.f + __expf(-fabsf(x))); }
; __device__ __forceinline__ void gla_prep_item(LAS unsigned char* lds, int item, const bf16_t* Z, const float* W2, const float* Bg, bf16_t* KDT, float* DEC) {
;     ...
; #pragma unroll
;     for (int t = 0; t < 64; ++t) {
;         float x = bias;
; #pragma unroll
;         for (int r = 0; r < 16; ++r) x += zgs[t * 16 + r] * w[r];
;         gv[t] = log_sigmoid(x) * (1.f / 16.f); bend += gv[t];
	v_fma_f32 v114, v65, v240, v69
	v_fmac_f32_e32 v114, v66, v241
	v_fmac_f32_e32 v114, v67, v242
	v_fmac_f32_e32 v114, v68, v243
	v_fmac_f32_e32 v114, v55, v244
	v_fmac_f32_e32 v114, v62, v245
	v_fmac_f32_e32 v114, v63, v246
	v_fmac_f32_e32 v114, v64, v247
	v_fmac_f32_e32 v114, v52, v248
	v_fmac_f32_e32 v114, v53, v249
	v_fmac_f32_e32 v114, v50, v250
	v_fmac_f32_e32 v114, v51, v251
	v_pk_mul_f32 v[0:1], v[48:49], v[252:253]
	s_nop 0
	v_add_f32_e32 v0, v114, v0
	v_add_f32_e32 v114, v0, v1
	v_pk_mul_f32 v[0:1], v[46:47], v[254:255]
	s_nop 0
	v_add_f32_e32 v0, v114, v0
	v_add_f32_e32 v0, v0, v1
	v_min_f32_e32 v1, 0, v0
	v_mul_f32_e64 v0, |v0|, s11
	v_exp_f32_e32 v0, v0
	s_nop 0
	v_add_f32_e32 v0, 1.0, v0
	v_cmp_gt_f32_e32 vcc, s12, v0
	s_nop 1
	v_cndmask_b32_e64 v2, 0, 32, vcc
	v_ldexp_f32 v0, v0, v2
	v_log_f32_e32 v0, v0
	s_nop 0
	v_mul_f32_e32 v2, 0x3f317217, v0
	v_fma_f32 v2, v0, s13, -v2
	v_fmac_f32_e32 v2, 0x3377d1cf, v0
	v_fmac_f32_e32 v2, 0x3f317217, v0
	v_cmp_lt_f32_e64 s[0:1], |v0|, s36
	s_nop 1
	v_cndmask_b32_e64 v0, v0, v2, s[0:1]
	v_cndmask_b32_e32 v2, 0, v60, vcc
	v_sub_f32_e32 v0, v0, v2
	v_sub_f32_e32 v0, v1, v0
	v_fmamk_f32 v114, v0, 0x3d800000, v113
	ds_read_b128 v[240:243], v5 offset:3008
	ds_read_b128 v[244:247], v5 offset:3024
	ds_read_b128 v[248:251], v5 offset:3040
	ds_read_b128 v[252:255], v5 offset:3056
	s_waitcnt lgkmcnt(4)
	v_fma_f32 v115, v65, v210, v69
	v_fmac_f32_e32 v115, v66, v211
	v_fmac_f32_e32 v115, v67, v212
	v_fmac_f32_e32 v115, v68, v213
	v_fmac_f32_e32 v115, v55, v214
	v_fmac_f32_e32 v115, v62, v215
	v_fmac_f32_e32 v115, v63, v216
	v_fmac_f32_e32 v115, v64, v217
	v_fmac_f32_e32 v115, v52, v218
	v_fmac_f32_e32 v115, v53, v219
	v_fmac_f32_e32 v115, v50, v220
	v_fmac_f32_e32 v115, v51, v221
	v_pk_mul_f32 v[0:1], v[48:49], v[222:223]
	s_nop 0
	v_add_f32_e32 v0, v115, v0
	v_add_f32_e32 v115, v0, v1
	v_pk_mul_f32 v[0:1], v[46:47], v[224:225]
	s_nop 0
	v_add_f32_e32 v0, v115, v0
	v_add_f32_e32 v0, v0, v1
	v_min_f32_e32 v1, 0, v0
	v_mul_f32_e64 v0, |v0|, s11
	v_exp_f32_e32 v0, v0
	s_nop 0
	v_add_f32_e32 v0, 1.0, v0
	v_cmp_gt_f32_e32 vcc, s12, v0
	s_nop 1
	v_cndmask_b32_e64 v2, 0, 32, vcc
	v_ldexp_f32 v0, v0, v2
	v_log_f32_e32 v0, v0
	s_nop 0
	v_mul_f32_e32 v2, 0x3f317217, v0
	v_fma_f32 v2, v0, s13, -v2
	v_fmac_f32_e32 v2, 0x3377d1cf, v0
	v_fmac_f32_e32 v2, 0x3f317217, v0
	v_cmp_lt_f32_e64 s[0:1], |v0|, s36
	s_nop 1
	v_cndmask_b32_e64 v0, v0, v2, s[0:1]
	v_cndmask_b32_e32 v2, 0, v60, vcc
	v_sub_f32_e32 v0, v0, v2
	v_sub_f32_e32 v0, v1, v0
	v_fmamk_f32 v115, v0, 0x3d800000, v114
	ds_read_b128 v[210:213], v5 offset:3072
	ds_read_b128 v[214:217], v5 offset:3088
	ds_read_b128 v[218:221], v5 offset:3104
	ds_read_b128 v[222:225], v5 offset:3120
	s_waitcnt lgkmcnt(4)
	v_fma_f32 v116, v65, v240, v69
	v_fmac_f32_e32 v116, v66, v241
	v_fmac_f32_e32 v116, v67, v242
	v_fmac_f32_e32 v116, v68, v243
	v_fmac_f32_e32 v116, v55, v244
	v_fmac_f32_e32 v116, v62, v245
	v_fmac_f32_e32 v116, v63, v246
	v_fmac_f32_e32 v116, v64, v247
	v_fmac_f32_e32 v116, v52, v248
	v_fmac_f32_e32 v116, v53, v249
	v_fmac_f32_e32 v116, v50, v250
	v_fmac_f32_e32 v116, v51, v251
	v_pk_mul_f32 v[0:1], v[48:49], v[252:253]
	s_nop 0
	v_add_f32_e32 v0, v116, v0
	v_add_f32_e32 v116, v0, v1
	v_pk_mul_f32 v[0:1], v[46:47], v[254:255]
	s_nop 0
	v_add_f32_e32 v0, v116, v0
	v_add_f32_e32 v0, v0, v1
	v_min_f32_e32 v1, 0, v0
	v_mul_f32_e64 v0, |v0|, s11
	v_exp_f32_e32 v0, v0
	s_nop 0
	v_add_f32_e32 v0, 1.0, v0
	v_cmp_gt_f32_e32 vcc, s12, v0
	s_nop 1
	v_cndmask_b32_e64 v2, 0, 32, vcc
	v_ldexp_f32 v0, v0, v2
	v_log_f32_e32 v0, v0
	s_nop 0
	v_mul_f32_e32 v2, 0x3f317217, v0
	v_fma_f32 v2, v0, s13, -v2
	v_fmac_f32_e32 v2, 0x3377d1cf, v0
	v_fmac_f32_e32 v2, 0x3f317217, v0
	v_cmp_lt_f32_e64 s[0:1], |v0|, s36
	s_nop 1
	v_cndmask_b32_e64 v0, v0, v2, s[0:1]
	v_cndmask_b32_e32 v2, 0, v60, vcc
	v_sub_f32_e32 v0, v0, v2
	v_sub_f32_e32 v0, v1, v0
	v_fmamk_f32 v116, v0, 0x3d800000, v115
	ds_read_b128 v[240:243], v5 offset:3136
	ds_read_b128 v[244:247], v5 offset:3152
	ds_read_b128 v[248:251], v5 offset:3168
	ds_read_b128 v[252:255], v5 offset:3184
	s_waitcnt lgkmcnt(4)
	v_fma_f32 v117, v65, v210, v69
	v_fmac_f32_e32 v117, v66, v211
	v_fmac_f32_e32 v117, v67, v212
	v_fmac_f32_e32 v117, v68, v213
	v_fmac_f32_e32 v117, v55, v214
	v_fmac_f32_e32 v117, v62, v215
	v_fmac_f32_e32 v117, v63, v216
	v_fmac_f32_e32 v117, v64, v217
	v_fmac_f32_e32 v117, v52, v218
	v_fmac_f32_e32 v117, v53, v219
	v_fmac_f32_e32 v117, v50, v220
	v_fmac_f32_e32 v117, v51, v221
	v_pk_mul_f32 v[0:1], v[48:49], v[222:223]
	s_nop 0
	v_add_f32_e32 v0, v117, v0
	v_add_f32_e32 v117, v0, v1
	v_pk_mul_f32 v[0:1], v[46:47], v[224:225]
	s_nop 0
	v_add_f32_e32 v0, v117, v0
	v_add_f32_e32 v0, v0, v1
	v_min_f32_e32 v1, 0, v0
	v_mul_f32_e64 v0, |v0|, s11
	v_exp_f32_e32 v0, v0
	s_nop 0
	v_add_f32_e32 v0, 1.0, v0
	v_cmp_gt_f32_e32 vcc, s12, v0
	s_nop 1
	v_cndmask_b32_e64 v2, 0, 32, vcc
	v_ldexp_f32 v0, v0, v2
	v_log_f32_e32 v0, v0
	s_nop 0
	v_mul_f32_e32 v2, 0x3f317217, v0
	v_fma_f32 v2, v0, s13, -v2
	v_fmac_f32_e32 v2, 0x3377d1cf, v0
	v_fmac_f32_e32 v2, 0x3f317217, v0
	v_cmp_lt_f32_e64 s[0:1], |v0|, s36
	s_nop 1
	v_cndmask_b32_e64 v0, v0, v2, s[0:1]
	v_cndmask_b32_e32 v2, 0, v60, vcc
	v_sub_f32_e32 v0, v0, v2
	v_sub_f32_e32 v0, v1, v0
	v_fmamk_f32 v117, v0, 0x3d800000, v116
	ds_read_b128 v[210:213], v5 offset:3200
	ds_read_b128 v[214:217], v5 offset:3216
	ds_read_b128 v[218:221], v5 offset:3232
	ds_read_b128 v[222:225], v5 offset:3248
	s_waitcnt lgkmcnt(4)
; __device__ __forceinline__ float log_sigmoid(float x) { return fminf(x, 0.f) - __logf(1.f + __expf(-fabsf(x))); }
; __device__ __forceinline__ void gla_prep_item(LAS unsigned char* lds, int item, const bf16_t* Z, const float* W2, const float* Bg, bf16_t* KDT, float* DEC) {
;     ...
; #pragma unroll
;     for (int t = 0; t < 64; ++t) {
;         float x = bias;
; #pragma unroll
;         for (int r = 0; r < 16; ++r) x += zgs[t * 16 + r] * w[r];
;         gv[t] = log_sigmoid(x) * (1.f / 16.f); bend += gv[t];
	v_fma_f32 v118, v65, v240, v69
	v_fmac_f32_e32 v118, v66, v241
	v_fmac_f32_e32 v118, v67, v242
	v_fmac_f32_e32 v118, v68, v243
	v_fmac_f32_e32 v118, v55, v244
	v_fmac_f32_e32 v118, v62, v245
	v_fmac_f32_e32 v118, v63, v246
	v_fmac_f32_e32 v118, v64, v247
	v_fmac_f32_e32 v118, v52, v248
	v_fmac_f32_e32 v118, v53, v249
	v_fmac_f32_e32 v118, v50, v250
	v_fmac_f32_e32 v118, v51, v251
	v_pk_mul_f32 v[0:1], v[48:49], v[252:253]
	s_nop 0
	v_add_f32_e32 v0, v118, v0
	v_add_f32_e32 v118, v0, v1
	v_pk_mul_f32 v[0:1], v[46:47], v[254:255]
	s_nop 0
	v_add_f32_e32 v0, v118, v0
	v_add_f32_e32 v0, v0, v1
	v_min_f32_e32 v1, 0, v0
	v_mul_f32_e64 v0, |v0|, s11
	v_exp_f32_e32 v0, v0
	s_nop 0
	v_add_f32_e32 v0, 1.0, v0
	v_cmp_gt_f32_e32 vcc, s12, v0
	s_nop 1
	v_cndmask_b32_e64 v2, 0, 32, vcc
	v_ldexp_f32 v0, v0, v2
	v_log_f32_e32 v0, v0
	s_nop 0
	v_mul_f32_e32 v2, 0x3f317217, v0
	v_fma_f32 v2, v0, s13, -v2
	v_fmac_f32_e32 v2, 0x3377d1cf, v0
	v_fmac_f32_e32 v2, 0x3f317217, v0
	v_cmp_lt_f32_e64 s[0:1], |v0|, s36
	s_nop 1
	v_cndmask_b32_e64 v0, v0, v2, s[0:1]
	v_cndmask_b32_e32 v2, 0, v60, vcc
	v_sub_f32_e32 v0, v0, v2
	v_sub_f32_e32 v0, v1, v0
	v_fmamk_f32 v118, v0, 0x3d800000, v117
	ds_read_b128 v[240:243], v5 offset:3264
	ds_read_b128 v[244:247], v5 offset:3280
	ds_read_b128 v[248:251], v5 offset:3296
	ds_read_b128 v[252:255], v5 offset:3312
	s_waitcnt lgkmcnt(4)
	v_fma_f32 v119, v65, v210, v69
	v_fmac_f32_e32 v119, v66, v211
	v_fmac_f32_e32 v119, v67, v212
	v_fmac_f32_e32 v119, v68, v213
	v_fmac_f32_e32 v119, v55, v214
	v_fmac_f32_e32 v119, v62, v215
	v_fmac_f32_e32 v119, v63, v216
	v_fmac_f32_e32 v119, v64, v217
	v_fmac_f32_e32 v119, v52, v218
	v_fmac_f32_e32 v119, v53, v219
	v_fmac_f32_e32 v119, v50, v220
	v_fmac_f32_e32 v119, v51, v221
	v_pk_mul_f32 v[0:1], v[48:49], v[222:223]
	s_nop 0
	v_add_f32_e32 v0, v119, v0
	v_add_f32_e32 v119, v0, v1
	v_pk_mul_f32 v[0:1], v[46:47], v[224:225]
	s_nop 0
	v_add_f32_e32 v0, v119, v0
	v_add_f32_e32 v0, v0, v1
	v_min_f32_e32 v1, 0, v0
	v_mul_f32_e64 v0, |v0|, s11
	v_exp_f32_e32 v0, v0
	s_nop 0
	v_add_f32_e32 v0, 1.0, v0
	v_cmp_gt_f32_e32 vcc, s12, v0
	s_nop 1
	v_cndmask_b32_e64 v2, 0, 32, vcc
	v_ldexp_f32 v0, v0, v2
	v_log_f32_e32 v0, v0
	s_nop 0
	v_mul_f32_e32 v2, 0x3f317217, v0
	v_fma_f32 v2, v0, s13, -v2
	v_fmac_f32_e32 v2, 0x3377d1cf, v0
	v_fmac_f32_e32 v2, 0x3f317217, v0
	v_cmp_lt_f32_e64 s[0:1], |v0|, s36
	s_nop 1
	v_cndmask_b32_e64 v0, v0, v2, s[0:1]
	v_cndmask_b32_e32 v2, 0, v60, vcc
	v_sub_f32_e32 v0, v0, v2
	v_sub_f32_e32 v0, v1, v0
	v_fmamk_f32 v119, v0, 0x3d800000, v118
	ds_read_b128 v[210:213], v5 offset:3328
	ds_read_b128 v[214:217], v5 offset:3344
	ds_read_b128 v[218:221], v5 offset:3360
	ds_read_b128 v[222:225], v5 offset:3376
	s_waitcnt lgkmcnt(4)
	v_fma_f32 v120, v65, v240, v69
	v_fmac_f32_e32 v120, v66, v241
	v_fmac_f32_e32 v120, v67, v242
	v_fmac_f32_e32 v120, v68, v243
	v_fmac_f32_e32 v120, v55, v244
	v_fmac_f32_e32 v120, v62, v245
	v_fmac_f32_e32 v120, v63, v246
	v_fmac_f32_e32 v120, v64, v247
	v_fmac_f32_e32 v120, v52, v248
	v_fmac_f32_e32 v120, v53, v249
	v_fmac_f32_e32 v120, v50, v250
	v_fmac_f32_e32 v120, v51, v251
	v_pk_mul_f32 v[0:1], v[48:49], v[252:253]
	s_nop 0
	v_add_f32_e32 v0, v120, v0
	v_add_f32_e32 v120, v0, v1
	v_pk_mul_f32 v[0:1], v[46:47], v[254:255]
	s_nop 0
	v_add_f32_e32 v0, v120, v0
	v_add_f32_e32 v0, v0, v1
	v_min_f32_e32 v1, 0, v0
	v_mul_f32_e64 v0, |v0|, s11
	v_exp_f32_e32 v0, v0
	s_nop 0
	v_add_f32_e32 v0, 1.0, v0
	v_cmp_gt_f32_e32 vcc, s12, v0
	s_nop 1
	v_cndmask_b32_e64 v2, 0, 32, vcc
	v_ldexp_f32 v0, v0, v2
	v_log_f32_e32 v0, v0
	s_nop 0
	v_mul_f32_e32 v2, 0x3f317217, v0
	v_fma_f32 v2, v0, s13, -v2
	v_fmac_f32_e32 v2, 0x3377d1cf, v0
	v_fmac_f32_e32 v2, 0x3f317217, v0
	v_cmp_lt_f32_e64 s[0:1], |v0|, s36
	s_nop 1
	v_cndmask_b32_e64 v0, v0, v2, s[0:1]
	v_cndmask_b32_e32 v2, 0, v60, vcc
	v_sub_f32_e32 v0, v0, v2
	v_sub_f32_e32 v0, v1, v0
	v_fmamk_f32 v120, v0, 0x3d800000, v119
	ds_read_b128 v[240:243], v5 offset:3392
	ds_read_b128 v[244:247], v5 offset:3408
	ds_read_b128 v[248:251], v5 offset:3424
	ds_read_b128 v[252:255], v5 offset:3440
	s_waitcnt lgkmcnt(4)
	v_fma_f32 v121, v65, v210, v69
	v_fmac_f32_e32 v121, v66, v211
	v_fmac_f32_e32 v121, v67, v212
	v_fmac_f32_e32 v121, v68, v213
	v_fmac_f32_e32 v121, v55, v214
	v_fmac_f32_e32 v121, v62, v215
	v_fmac_f32_e32 v121, v63, v216
	v_fmac_f32_e32 v121, v64, v217
	v_fmac_f32_e32 v121, v52, v218
	v_fmac_f32_e32 v121, v53, v219
	v_fmac_f32_e32 v121, v50, v220
	v_fmac_f32_e32 v121, v51, v221
	v_pk_mul_f32 v[0:1], v[48:49], v[222:223]
	s_nop 0
	v_add_f32_e32 v0, v121, v0
	v_add_f32_e32 v121, v0, v1
	v_pk_mul_f32 v[0:1], v[46:47], v[224:225]
	s_nop 0
	v_add_f32_e32 v0, v121, v0
	v_add_f32_e32 v0, v0, v1
	v_min_f32_e32 v1, 0, v0
	v_mul_f32_e64 v0, |v0|, s11
	v_exp_f32_e32 v0, v0
	s_nop 0
	v_add_f32_e32 v0, 1.0, v0
	v_cmp_gt_f32_e32 vcc, s12, v0
	s_nop 1
	v_cndmask_b32_e64 v2, 0, 32, vcc
	v_ldexp_f32 v0, v0, v2
	v_log_f32_e32 v0, v0
	s_nop 0
	v_mul_f32_e32 v2, 0x3f317217, v0
	v_fma_f32 v2, v0, s13, -v2
	v_fmac_f32_e32 v2, 0x3377d1cf, v0
	v_fmac_f32_e32 v2, 0x3f317217, v0
	v_cmp_lt_f32_e64 s[0:1], |v0|, s36
	s_nop 1
	v_cndmask_b32_e64 v0, v0, v2, s[0:1]
	v_cndmask_b32_e32 v2, 0, v60, vcc
	v_sub_f32_e32 v0, v0, v2
	v_sub_f32_e32 v0, v1, v0
	v_fmamk_f32 v121, v0, 0x3d800000, v120
	ds_read_b128 v[210:213], v5 offset:3456
	ds_read_b128 v[214:217], v5 offset:3472
	ds_read_b128 v[218:221], v5 offset:3488
	ds_read_b128 v[222:225], v5 offset:3504
	s_waitcnt lgkmcnt(4)
; __device__ __forceinline__ float log_sigmoid(float x) { return fminf(x, 0.f) - __logf(1.f + __expf(-fabsf(x))); }
; __device__ __forceinline__ void gla_prep_item(LAS unsigned char* lds, int item, const bf16_t* Z, const float* W2, const float* Bg, bf16_t* KDT, float* DEC) {
;     ...
; #pragma unroll
;     for (int t = 0; t < 64; ++t) {
;         float x = bias;
; #pragma unroll
;         for (int r = 0; r < 16; ++r) x += zgs[t * 16 + r] * w[r];
;         gv[t] = log_sigmoid(x) * (1.f / 16.f); bend += gv[t];
	v_fma_f32 v122, v65, v240, v69
	v_fmac_f32_e32 v122, v66, v241
	v_fmac_f32_e32 v122, v67, v242
	v_fmac_f32_e32 v122, v68, v243
	v_fmac_f32_e32 v122, v55, v244
	v_fmac_f32_e32 v122, v62, v245
	v_fmac_f32_e32 v122, v63, v246
	v_fmac_f32_e32 v122, v64, v247
	v_fmac_f32_e32 v122, v52, v248
	v_fmac_f32_e32 v122, v53, v249
	v_fmac_f32_e32 v122, v50, v250
	v_fmac_f32_e32 v122, v51, v251
	v_pk_mul_f32 v[0:1], v[48:49], v[252:253]
	s_nop 0
	v_add_f32_e32 v0, v122, v0
	v_add_f32_e32 v122, v0, v1
	v_pk_mul_f32 v[0:1], v[46:47], v[254:255]
	s_nop 0
	v_add_f32_e32 v0, v122, v0
	v_add_f32_e32 v0, v0, v1
	v_min_f32_e32 v1, 0, v0
	v_mul_f32_e64 v0, |v0|, s11
	v_exp_f32_e32 v0, v0
	s_nop 0
	v_add_f32_e32 v0, 1.0, v0
	v_cmp_gt_f32_e32 vcc, s12, v0
	s_nop 1
	v_cndmask_b32_e64 v2, 0, 32, vcc
	v_ldexp_f32 v0, v0, v2
	v_log_f32_e32 v0, v0
	s_nop 0
	v_mul_f32_e32 v2, 0x3f317217, v0
	v_fma_f32 v2, v0, s13, -v2
	v_fmac_f32_e32 v2, 0x3377d1cf, v0
	v_fmac_f32_e32 v2, 0x3f317217, v0
	v_cmp_lt_f32_e64 s[0:1], |v0|, s36
	s_nop 1
	v_cndmask_b32_e64 v0, v0, v2, s[0:1]
	v_cndmask_b32_e32 v2, 0, v60, vcc
	v_sub_f32_e32 v0, v0, v2
	v_sub_f32_e32 v0, v1, v0
	v_fmamk_f32 v122, v0, 0x3d800000, v121
	ds_read_b128 v[240:243], v5 offset:3520
	ds_read_b128 v[244:247], v5 offset:3536
	ds_read_b128 v[248:251], v5 offset:3552
	ds_read_b128 v[252:255], v5 offset:3568
	s_waitcnt lgkmcnt(4)
	v_fma_f32 v123, v65, v210, v69
	v_fmac_f32_e32 v123, v66, v211
	v_fmac_f32_e32 v123, v67, v212
	v_fmac_f32_e32 v123, v68, v213
	v_fmac_f32_e32 v123, v55, v214
	v_fmac_f32_e32 v123, v62, v215
	v_fmac_f32_e32 v123, v63, v216
	v_fmac_f32_e32 v123, v64, v217
	v_fmac_f32_e32 v123, v52, v218
	v_fmac_f32_e32 v123, v53, v219
	v_fmac_f32_e32 v123, v50, v220
	v_fmac_f32_e32 v123, v51, v221
	v_pk_mul_f32 v[0:1], v[48:49], v[222:223]
	s_nop 0
	v_add_f32_e32 v0, v123, v0
	v_add_f32_e32 v123, v0, v1
	v_pk_mul_f32 v[0:1], v[46:47], v[224:225]
	s_nop 0
	v_add_f32_e32 v0, v123, v0
	v_add_f32_e32 v0, v0, v1
	v_min_f32_e32 v1, 0, v0
	v_mul_f32_e64 v0, |v0|, s11
	v_exp_f32_e32 v0, v0
	s_nop 0
	v_add_f32_e32 v0, 1.0, v0
	v_cmp_gt_f32_e32 vcc, s12, v0
	s_nop 1
	v_cndmask_b32_e64 v2, 0, 32, vcc
	v_ldexp_f32 v0, v0, v2
	v_log_f32_e32 v0, v0
	s_nop 0
	v_mul_f32_e32 v2, 0x3f317217, v0
	v_fma_f32 v2, v0, s13, -v2
	v_fmac_f32_e32 v2, 0x3377d1cf, v0
	v_fmac_f32_e32 v2, 0x3f317217, v0
	v_cmp_lt_f32_e64 s[0:1], |v0|, s36
	s_nop 1
	v_cndmask_b32_e64 v0, v0, v2, s[0:1]
	v_cndmask_b32_e32 v2, 0, v60, vcc
	v_sub_f32_e32 v0, v0, v2
	v_sub_f32_e32 v0, v1, v0
	v_fmamk_f32 v123, v0, 0x3d800000, v122
	ds_read_b128 v[210:213], v5 offset:3584
	ds_read_b128 v[214:217], v5 offset:3600
	ds_read_b128 v[218:221], v5 offset:3616
	ds_read_b128 v[222:225], v5 offset:3632
	s_waitcnt lgkmcnt(4)
	v_fma_f32 v124, v65, v240, v69
	v_fmac_f32_e32 v124, v66, v241
	v_fmac_f32_e32 v124, v67, v242
	v_fmac_f32_e32 v124, v68, v243
	v_fmac_f32_e32 v124, v55, v244
	v_fmac_f32_e32 v124, v62, v245
	v_fmac_f32_e32 v124, v63, v246
	v_fmac_f32_e32 v124, v64, v247
	v_fmac_f32_e32 v124, v52, v248
	v_fmac_f32_e32 v124, v53, v249
	v_fmac_f32_e32 v124, v50, v250
	v_fmac_f32_e32 v124, v51, v251
	v_pk_mul_f32 v[0:1], v[48:49], v[252:253]
	s_nop 0
	v_add_f32_e32 v0, v124, v0
	v_add_f32_e32 v124, v0, v1
	v_pk_mul_f32 v[0:1], v[46:47], v[254:255]
	s_nop 0
	v_add_f32_e32 v0, v124, v0
	v_add_f32_e32 v0, v0, v1
	v_min_f32_e32 v1, 0, v0
	v_mul_f32_e64 v0, |v0|, s11
	v_exp_f32_e32 v0, v0
	s_nop 0
	v_add_f32_e32 v0, 1.0, v0
	v_cmp_gt_f32_e32 vcc, s12, v0
	s_nop 1
	v_cndmask_b32_e64 v2, 0, 32, vcc
	v_ldexp_f32 v0, v0, v2
	v_log_f32_e32 v0, v0
	s_nop 0
	v_mul_f32_e32 v2, 0x3f317217, v0
	v_fma_f32 v2, v0, s13, -v2
	v_fmac_f32_e32 v2, 0x3377d1cf, v0
	v_fmac_f32_e32 v2, 0x3f317217, v0
	v_cmp_lt_f32_e64 s[0:1], |v0|, s36
	s_nop 1
	v_cndmask_b32_e64 v0, v0, v2, s[0:1]
	v_cndmask_b32_e32 v2, 0, v60, vcc
	v_sub_f32_e32 v0, v0, v2
	v_sub_f32_e32 v0, v1, v0
	v_fmamk_f32 v124, v0, 0x3d800000, v123
	ds_read_b128 v[240:243], v5 offset:3648
	ds_read_b128 v[244:247], v5 offset:3664
	ds_read_b128 v[248:251], v5 offset:3680
	ds_read_b128 v[252:255], v5 offset:3696
	s_waitcnt lgkmcnt(4)
	v_fma_f32 v125, v65, v210, v69
	v_fmac_f32_e32 v125, v66, v211
	v_fmac_f32_e32 v125, v67, v212
	v_fmac_f32_e32 v125, v68, v213
	v_fmac_f32_e32 v125, v55, v214
	v_fmac_f32_e32 v125, v62, v215
	v_fmac_f32_e32 v125, v63, v216
	v_fmac_f32_e32 v125, v64, v217
	v_fmac_f32_e32 v125, v52, v218
	v_fmac_f32_e32 v125, v53, v219
	v_fmac_f32_e32 v125, v50, v220
	v_fmac_f32_e32 v125, v51, v221
	v_pk_mul_f32 v[0:1], v[48:49], v[222:223]
	s_nop 0
	v_add_f32_e32 v0, v125, v0
	v_add_f32_e32 v125, v0, v1
	v_pk_mul_f32 v[0:1], v[46:47], v[224:225]
	s_nop 0
	v_add_f32_e32 v0, v125, v0
	v_add_f32_e32 v0, v0, v1
	v_min_f32_e32 v1, 0, v0
	v_mul_f32_e64 v0, |v0|, s11
	v_exp_f32_e32 v0, v0
	s_nop 0
	v_add_f32_e32 v0, 1.0, v0
	v_cmp_gt_f32_e32 vcc, s12, v0
	s_nop 1
	v_cndmask_b32_e64 v2, 0, 32, vcc
	v_ldexp_f32 v0, v0, v2
	v_log_f32_e32 v0, v0
	s_nop 0
	v_mul_f32_e32 v2, 0x3f317217, v0
	v_fma_f32 v2, v0, s13, -v2
	v_fmac_f32_e32 v2, 0x3377d1cf, v0
	v_fmac_f32_e32 v2, 0x3f317217, v0
	v_cmp_lt_f32_e64 s[0:1], |v0|, s36
	s_nop 1
	v_cndmask_b32_e64 v0, v0, v2, s[0:1]
	v_cndmask_b32_e32 v2, 0, v60, vcc
	v_sub_f32_e32 v0, v0, v2
	v_sub_f32_e32 v0, v1, v0
	v_fmamk_f32 v125, v0, 0x3d800000, v124
	ds_read_b128 v[210:213], v5 offset:3712
	ds_read_b128 v[214:217], v5 offset:3728
	ds_read_b128 v[218:221], v5 offset:3744
	ds_read_b128 v[222:225], v5 offset:3760
	s_waitcnt lgkmcnt(4)
; __device__ __forceinline__ float log_sigmoid(float x) { return fminf(x, 0.f) - __logf(1.f + __expf(-fabsf(x))); }
; __device__ __forceinline__ void gla_prep_item(LAS unsigned char* lds, int item, const bf16_t* Z, const float* W2, const float* Bg, bf16_t* KDT, float* DEC) {
;     ...
; #pragma unroll
;     for (int t = 0; t < 64; ++t) {
;         float x = bias;
; #pragma unroll
;         for (int r = 0; r < 16; ++r) x += zgs[t * 16 + r] * w[r];
;         gv[t] = log_sigmoid(x) * (1.f / 16.f); bend += gv[t];
	v_fma_f32 v126, v65, v240, v69
	v_fmac_f32_e32 v126, v66, v241
	v_fmac_f32_e32 v126, v67, v242
	v_fmac_f32_e32 v126, v68, v243
	v_fmac_f32_e32 v126, v55, v244
	v_fmac_f32_e32 v126, v62, v245
	v_fmac_f32_e32 v126, v63, v246
	v_fmac_f32_e32 v126, v64, v247
	v_fmac_f32_e32 v126, v52, v248
	v_fmac_f32_e32 v126, v53, v249
	v_fmac_f32_e32 v126, v50, v250
	v_fmac_f32_e32 v126, v51, v251
	v_pk_mul_f32 v[0:1], v[48:49], v[252:253]
	s_nop 0
	v_add_f32_e32 v0, v126, v0
	v_add_f32_e32 v126, v0, v1
	v_pk_mul_f32 v[0:1], v[46:47], v[254:255]
	s_nop 0
	v_add_f32_e32 v0, v126, v0
	v_add_f32_e32 v0, v0, v1
	v_min_f32_e32 v1, 0, v0
	v_mul_f32_e64 v0, |v0|, s11
	v_exp_f32_e32 v0, v0
	s_nop 0
	v_add_f32_e32 v0, 1.0, v0
	v_cmp_gt_f32_e32 vcc, s12, v0
	s_nop 1
	v_cndmask_b32_e64 v2, 0, 32, vcc
	v_ldexp_f32 v0, v0, v2
	v_log_f32_e32 v0, v0
	s_nop 0
	v_mul_f32_e32 v2, 0x3f317217, v0
	v_fma_f32 v2, v0, s13, -v2
	v_fmac_f32_e32 v2, 0x3377d1cf, v0
	v_fmac_f32_e32 v2, 0x3f317217, v0
	v_cmp_lt_f32_e64 s[0:1], |v0|, s36
	s_nop 1
	v_cndmask_b32_e64 v0, v0, v2, s[0:1]
	v_cndmask_b32_e32 v2, 0, v60, vcc
	v_sub_f32_e32 v0, v0, v2
	v_sub_f32_e32 v0, v1, v0
	v_fmamk_f32 v126, v0, 0x3d800000, v125
	ds_read_b128 v[240:243], v5 offset:3776
	ds_read_b128 v[244:247], v5 offset:3792
	ds_read_b128 v[248:251], v5 offset:3808
	ds_read_b128 v[252:255], v5 offset:3824
	s_waitcnt lgkmcnt(4)
	v_fma_f32 v127, v65, v210, v69
	v_fmac_f32_e32 v127, v66, v211
	v_fmac_f32_e32 v127, v67, v212
	v_fmac_f32_e32 v127, v68, v213
	v_fmac_f32_e32 v127, v55, v214
	v_fmac_f32_e32 v127, v62, v215
	v_fmac_f32_e32 v127, v63, v216
	v_fmac_f32_e32 v127, v64, v217
	v_fmac_f32_e32 v127, v52, v218
	v_fmac_f32_e32 v127, v53, v219
	v_fmac_f32_e32 v127, v50, v220
	v_fmac_f32_e32 v127, v51, v221
	v_pk_mul_f32 v[0:1], v[48:49], v[222:223]
	s_nop 0
	v_add_f32_e32 v0, v127, v0
	v_add_f32_e32 v127, v0, v1
	v_pk_mul_f32 v[0:1], v[46:47], v[224:225]
	s_nop 0
	v_add_f32_e32 v0, v127, v0
	v_add_f32_e32 v0, v0, v1
	v_min_f32_e32 v1, 0, v0
	v_mul_f32_e64 v0, |v0|, s11
	v_exp_f32_e32 v0, v0
	s_nop 0
	v_add_f32_e32 v0, 1.0, v0
	v_cmp_gt_f32_e32 vcc, s12, v0
	s_nop 1
	v_cndmask_b32_e64 v2, 0, 32, vcc
	v_ldexp_f32 v0, v0, v2
	v_log_f32_e32 v0, v0
	s_nop 0
	v_mul_f32_e32 v2, 0x3f317217, v0
	v_fma_f32 v2, v0, s13, -v2
	v_fmac_f32_e32 v2, 0x3377d1cf, v0
	v_fmac_f32_e32 v2, 0x3f317217, v0
	v_cmp_lt_f32_e64 s[0:1], |v0|, s36
	s_nop 1
	v_cndmask_b32_e64 v0, v0, v2, s[0:1]
	v_cndmask_b32_e32 v2, 0, v60, vcc
	v_sub_f32_e32 v0, v0, v2
	v_sub_f32_e32 v0, v1, v0
	v_fmamk_f32 v127, v0, 0x3d800000, v126
	ds_read_b128 v[210:213], v5 offset:3840
	ds_read_b128 v[214:217], v5 offset:3856
	ds_read_b128 v[218:221], v5 offset:3872
	ds_read_b128 v[222:225], v5 offset:3888
	s_waitcnt lgkmcnt(4)
	v_fma_f32 v128, v65, v240, v69
	v_fmac_f32_e32 v128, v66, v241
	v_fmac_f32_e32 v128, v67, v242
	v_fmac_f32_e32 v128, v68, v243
	v_fmac_f32_e32 v128, v55, v244
	v_fmac_f32_e32 v128, v62, v245
	v_fmac_f32_e32 v128, v63, v246
	v_fmac_f32_e32 v128, v64, v247
	v_fmac_f32_e32 v128, v52, v248
	v_fmac_f32_e32 v128, v53, v249
	v_fmac_f32_e32 v128, v50, v250
	v_fmac_f32_e32 v128, v51, v251
	v_pk_mul_f32 v[0:1], v[48:49], v[252:253]
	s_nop 0
	v_add_f32_e32 v0, v128, v0
	v_add_f32_e32 v128, v0, v1
	v_pk_mul_f32 v[0:1], v[46:47], v[254:255]
	s_nop 0
	v_add_f32_e32 v0, v128, v0
	v_add_f32_e32 v0, v0, v1
	v_min_f32_e32 v1, 0, v0
	v_mul_f32_e64 v0, |v0|, s11
	v_exp_f32_e32 v0, v0
	s_nop 0
	v_add_f32_e32 v0, 1.0, v0
	v_cmp_gt_f32_e32 vcc, s12, v0
	s_nop 1
	v_cndmask_b32_e64 v2, 0, 32, vcc
	v_ldexp_f32 v0, v0, v2
	v_log_f32_e32 v0, v0
	s_nop 0
	v_mul_f32_e32 v2, 0x3f317217, v0
	v_fma_f32 v2, v0, s13, -v2
	v_fmac_f32_e32 v2, 0x3377d1cf, v0
	v_fmac_f32_e32 v2, 0x3f317217, v0
	v_cmp_lt_f32_e64 s[0:1], |v0|, s36
	s_nop 1
	v_cndmask_b32_e64 v0, v0, v2, s[0:1]
	v_cndmask_b32_e32 v2, 0, v60, vcc
	v_sub_f32_e32 v0, v0, v2
	v_sub_f32_e32 v0, v1, v0
	v_fmamk_f32 v128, v0, 0x3d800000, v127
	ds_read_b128 v[240:243], v5 offset:3904
	ds_read_b128 v[244:247], v5 offset:3920
	ds_read_b128 v[248:251], v5 offset:3936
	ds_read_b128 v[252:255], v5 offset:3952
	s_waitcnt lgkmcnt(4)
	v_fma_f32 v129, v65, v210, v69
	v_fmac_f32_e32 v129, v66, v211
	v_fmac_f32_e32 v129, v67, v212
	v_fmac_f32_e32 v129, v68, v213
	v_fmac_f32_e32 v129, v55, v214
	v_fmac_f32_e32 v129, v62, v215
	v_fmac_f32_e32 v129, v63, v216
	v_fmac_f32_e32 v129, v64, v217
	v_fmac_f32_e32 v129, v52, v218
	v_fmac_f32_e32 v129, v53, v219
	v_fmac_f32_e32 v129, v50, v220
	v_fmac_f32_e32 v129, v51, v221
	v_pk_mul_f32 v[0:1], v[48:49], v[222:223]
	s_nop 0
	v_add_f32_e32 v0, v129, v0
	v_add_f32_e32 v129, v0, v1
	v_pk_mul_f32 v[0:1], v[46:47], v[224:225]
	s_nop 0
	v_add_f32_e32 v0, v129, v0
	v_add_f32_e32 v0, v0, v1
	v_min_f32_e32 v1, 0, v0
	v_mul_f32_e64 v0, |v0|, s11
	v_exp_f32_e32 v0, v0
	s_nop 0
	v_add_f32_e32 v0, 1.0, v0
	v_cmp_gt_f32_e32 vcc, s12, v0
	s_nop 1
	v_cndmask_b32_e64 v2, 0, 32, vcc
	v_ldexp_f32 v0, v0, v2
	v_log_f32_e32 v0, v0
	s_nop 0
	v_mul_f32_e32 v2, 0x3f317217, v0
	v_fma_f32 v2, v0, s13, -v2
	v_fmac_f32_e32 v2, 0x3377d1cf, v0
	v_fmac_f32_e32 v2, 0x3f317217, v0
	v_cmp_lt_f32_e64 s[0:1], |v0|, s36
	s_nop 1
	v_cndmask_b32_e64 v0, v0, v2, s[0:1]
	v_cndmask_b32_e32 v2, 0, v60, vcc
	v_sub_f32_e32 v0, v0, v2
	v_sub_f32_e32 v0, v1, v0
	v_fmamk_f32 v129, v0, 0x3d800000, v128
	ds_read_b128 v[210:213], v5 offset:3968
	ds_read_b128 v[214:217], v5 offset:3984
	ds_read_b128 v[218:221], v5 offset:4000
	ds_read_b128 v[222:225], v5 offset:4016
	s_waitcnt lgkmcnt(4)
; __device__ __forceinline__ unsigned pk2(float lo, float hi) { f32x2_t v = {lo, hi}; bf16x2_t b = __builtin_convertvector(v, bf16x2_t); return __builtin_bit_cast(unsigned, b); }
; __device__ __forceinline__ float log_sigmoid(float x) { return fminf(x, 0.f) - __logf(1.f + __expf(-fabsf(x))); }
; __device__ __forceinline__ void gla_prep_item(LAS unsigned char* lds, int item, const bf16_t* Z, const float* W2, const float* Bg, bf16_t* KDT, float* DEC) {
;     ...
; #pragma unroll
;     for (int t = 0; t < 64; ++t) {
;         float x = bias;
; #pragma unroll
;         for (int r = 0; r < 16; ++r) x += zgs[t * 16 + r] * w[r];
;         gv[t] = log_sigmoid(x) * (1.f / 16.f); bend += gv[t];
;     }
;     float bc = 0.f;
;     bf16_t* dst = KDT + (size_t)((b * 4 + h) * 32 + c) * 8192 + (size_t)((kd >> 4) * 2 * 64 + (kd & 15)) * 8;
;     const bf16_t* gk = Z + row0 * ZLD + ZGK + col;
; #pragma unroll
;     for (int t8 = 0; t8 < 8; ++t8) {
;         float kv[8];
; #pragma unroll
;         for (int e = 0; e < 8; ++e) {
;             const int t = t8 * 8 + e;
;             bc += gv[t];
;             kv[e] = bf2f(gk[(size_t)t * ZLD]) * __expf(bend - bc);
;         }
;         u32x4 o; o.x = pk2(kv[0], kv[1]); o.y = pk2(kv[2], kv[3]); o.z = pk2(kv[4], kv[5]); o.w = pk2(kv[6], kv[7]);
;         *(u32x4*)(dst + ((t8 >> 2) * 64 + (t8 & 3) * 16) * 8) = o;
	v_fma_f32 v130, v65, v240, v69
	v_fmac_f32_e32 v130, v66, v241
	v_fmac_f32_e32 v130, v67, v242
	v_fmac_f32_e32 v130, v68, v243
	v_fmac_f32_e32 v130, v55, v244
	v_fmac_f32_e32 v130, v62, v245
	v_fmac_f32_e32 v130, v63, v246
	v_fmac_f32_e32 v130, v64, v247
	v_fmac_f32_e32 v130, v52, v248
	v_fmac_f32_e32 v130, v53, v249
	v_pk_mul_f32 v[0:1], v[50:51], v[250:251]
	s_nop 0
	v_add_f32_e32 v0, v130, v0
	v_add_f32_e32 v130, v0, v1
	v_pk_mul_f32 v[0:1], v[48:49], v[252:253]
	s_nop 0
	v_add_f32_e32 v0, v130, v0
	v_add_f32_e32 v130, v0, v1
	v_pk_mul_f32 v[0:1], v[46:47], v[254:255]
	s_nop 0
	v_add_f32_e32 v0, v130, v0
	v_add_f32_e32 v0, v0, v1
	v_min_f32_e32 v1, 0, v0
	v_mul_f32_e64 v0, |v0|, s11
	v_exp_f32_e32 v0, v0
	s_nop 0
	v_add_f32_e32 v0, 1.0, v0
	v_cmp_gt_f32_e32 vcc, s12, v0
	s_nop 1
	v_cndmask_b32_e64 v2, 0, 32, vcc
	v_ldexp_f32 v0, v0, v2
	v_log_f32_e32 v0, v0
	s_nop 0
	v_mul_f32_e32 v2, 0x3f317217, v0
	v_fma_f32 v2, v0, s13, -v2
	v_fmac_f32_e32 v2, 0x3377d1cf, v0
	v_fmac_f32_e32 v2, 0x3f317217, v0
	v_cmp_lt_f32_e64 s[0:1], |v0|, s36
	s_nop 1
	v_cndmask_b32_e64 v0, v0, v2, s[0:1]
	v_cndmask_b32_e32 v2, 0, v60, vcc
	v_sub_f32_e32 v0, v0, v2
	v_sub_f32_e32 v0, v1, v0
	v_fmamk_f32 v130, v0, 0x3d800000, v129
	ds_read_b128 v[240:243], v5 offset:4032
	ds_read_b128 v[244:247], v5 offset:4048
	ds_read_b128 v[248:251], v5 offset:4064
	ds_read_b128 v[252:255], v5 offset:4080
	s_waitcnt lgkmcnt(4)
	v_fma_f32 v131, v65, v210, v69
	v_fmac_f32_e32 v131, v66, v211
	v_fmac_f32_e32 v131, v67, v212
	v_fmac_f32_e32 v131, v68, v213
	v_fmac_f32_e32 v131, v55, v214
	v_fmac_f32_e32 v131, v62, v215
	v_fmac_f32_e32 v131, v63, v216
	v_fmac_f32_e32 v131, v64, v217
	v_fmac_f32_e32 v131, v52, v218
	v_fmac_f32_e32 v131, v53, v219
	v_pk_mul_f32 v[0:1], v[50:51], v[220:221]
	s_nop 0
	v_add_f32_e32 v0, v131, v0
	v_add_f32_e32 v131, v0, v1
	v_pk_mul_f32 v[0:1], v[48:49], v[222:223]
	s_nop 0
	v_add_f32_e32 v0, v131, v0
	v_add_f32_e32 v131, v0, v1
	v_pk_mul_f32 v[0:1], v[46:47], v[224:225]
	s_nop 0
	v_add_f32_e32 v0, v131, v0
	v_add_f32_e32 v0, v0, v1
	v_min_f32_e32 v1, 0, v0
	v_mul_f32_e64 v0, |v0|, s11
	v_exp_f32_e32 v0, v0
	s_nop 0
	v_add_f32_e32 v0, 1.0, v0
	v_cmp_gt_f32_e32 vcc, s12, v0
	s_nop 1
	v_cndmask_b32_e64 v2, 0, 32, vcc
	v_ldexp_f32 v0, v0, v2
	v_log_f32_e32 v0, v0
	s_nop 0
	v_mul_f32_e32 v2, 0x3f317217, v0
	v_fma_f32 v2, v0, s13, -v2
	v_fmac_f32_e32 v2, 0x3377d1cf, v0
	v_fmac_f32_e32 v2, 0x3f317217, v0
	v_cmp_lt_f32_e64 s[0:1], |v0|, s36
	s_nop 1
	v_cndmask_b32_e64 v0, v0, v2, s[0:1]
	v_cndmask_b32_e32 v2, 0, v60, vcc
	v_sub_f32_e32 v0, v0, v2
	v_sub_f32_e32 v0, v1, v0
	v_fmamk_f32 v131, v0, 0x3d800000, v130
	s_waitcnt lgkmcnt(0)
	v_fmac_f32_e32 v69, v65, v240
	v_fmac_f32_e32 v69, v66, v241
	v_fmac_f32_e32 v69, v67, v242
	v_fmac_f32_e32 v69, v68, v243
	v_fmac_f32_e32 v69, v55, v244
	v_fmac_f32_e32 v69, v62, v245
	v_fmac_f32_e32 v69, v63, v246
	v_fmac_f32_e32 v69, v64, v247
	v_pk_mul_f32 v[0:1], v[52:53], v[248:249]
	s_nop 0
	v_add_f32_e32 v0, v69, v0
	v_add_f32_e32 v52, v0, v1
	v_pk_mul_f32 v[0:1], v[50:51], v[250:251]
	s_nop 0
	v_add_f32_e32 v0, v52, v0
	v_add_f32_e32 v50, v0, v1
	v_pk_mul_f32 v[0:1], v[48:49], v[252:253]
	s_nop 0
	v_add_f32_e32 v0, v50, v0
	v_add_f32_e32 v48, v0, v1
	v_pk_mul_f32 v[0:1], v[46:47], v[254:255]
	s_nop 0
	v_add_f32_e32 v0, v48, v0
	v_add_f32_e32 v0, v0, v1
	v_min_f32_e32 v1, 0, v0
	v_mul_f32_e64 v0, |v0|, s11
	v_exp_f32_e32 v0, v0
	s_nop 0
	v_add_f32_e32 v0, 1.0, v0
	v_cmp_gt_f32_e32 vcc, s12, v0
	s_nop 1
	v_cndmask_b32_e64 v2, 0, 32, vcc
	v_ldexp_f32 v0, v0, v2
	v_log_f32_e32 v0, v0
	s_nop 0
	v_mul_f32_e32 v2, 0x3f317217, v0
	v_fma_f32 v2, v0, s13, -v2
	v_fmac_f32_e32 v2, 0x3377d1cf, v0
	v_fmac_f32_e32 v2, 0x3f317217, v0
	v_cmp_lt_f32_e64 s[0:1], |v0|, s36
	s_nop 1
	v_cndmask_b32_e64 v0, v0, v2, s[0:1]
	v_mad_u64_u32 v[46:47], s[0:1], s6, v59, v[42:43]
	s_movk_i32 s0, 0x2000
	v_cndmask_b32_e32 v2, 0, v60, vcc
	v_add_u32_e32 v47, s7, v47
	v_add_co_u32_e32 v50, vcc, s0, v46
	v_sub_f32_e32 v0, v0, v2
	s_nop 0
	v_addc_co_u32_e32 v51, vcc, 0, v47, vcc
	s_waitcnt vmcnt(0)
	v_mov_b32_e32 v50, v141
	s_nop 0
	v_mov_b32_e32 v52, v140
	s_movk_i32 s0, 0x3000
	v_sub_f32_e32 v0, v1, v0
	v_fmamk_f32 v62, v0, 0x3d800000, v131
	v_sub_f32_e32 v48, v62, v54
	v_sub_f32_e32 v49, v62, v70
	v_mul_f32_e32 v48, 0x3fb8aa3b, v48
	v_mul_f32_e32 v49, 0x3fb8aa3b, v49
	v_exp_f32_e32 v48, v48
	v_exp_f32_e32 v49, v49
	v_lshl_add_u32 v0, s8, 7, v56
	v_or_b32_e32 v0, s9, v0
	v_ashrrev_i32_e32 v1, 31, v0
	v_lshlrev_b64 v[2:3], 14, v[0:1]
	v_lshl_add_u64 v[2:3], v[38:39], 0, v[2:3]
	v_lshlrev_b64 v[0:1], 9, v[0:1]
	v_lshl_add_u64 v[0:1], v[40:41], 0, v[0:1]
	s_nop 0
	v_lshlrev_b32_e32 v51, 16, v50
	s_nop 0
	v_lshlrev_b32_e32 v50, 16, v52
	v_add_co_u32_e32 v52, vcc, s0, v46
	s_movk_i32 s0, 0x5000
	s_nop 0
	v_addc_co_u32_e32 v53, vcc, 0, v47, vcc
	v_mov_b32_e32 v54, v142
	v_add_co_u32_e32 v52, vcc, s0, v46
	s_movk_i32 s0, 0x6000
	s_nop 0
	v_addc_co_u32_e32 v53, vcc, 0, v47, vcc
	v_mov_b32_e32 v52, v143
	v_pk_mul_f32 v[48:49], v[48:49], v[50:51]
	v_sub_f32_e32 v50, v62, v71
	v_sub_f32_e32 v51, v62, v72
	v_mul_f32_e32 v50, 0x3fb8aa3b, v50
	v_mul_f32_e32 v51, 0x3fb8aa3b, v51
	v_exp_f32_e32 v50, v50
	v_exp_f32_e32 v51, v51
	v_cvt_pk_bf16_f32 v48, v48, v49
	s_nop 0
	v_lshlrev_b32_e32 v53, 16, v52
	v_lshlrev_b32_e32 v52, 16, v54
	v_add_co_u32_e32 v54, vcc, s0, v46
	s_mov_b32 s0, 0x8000
	s_nop 0
	v_addc_co_u32_e32 v55, vcc, 0, v47, vcc
	v_mov_b32_e32 v63, v144
	v_add_co_u32_e32 v54, vcc, s0, v46
	s_mov_b32 s0, 0x9000
	s_nop 0
	v_addc_co_u32_e32 v55, vcc, 0, v47, vcc
	v_mov_b32_e32 v54, v145
	v_add_co_u32_e32 v64, vcc, s0, v46
	s_mov_b32 s0, 0xb000
	s_nop 0
; __device__ __forceinline__ unsigned pk2(float lo, float hi) { f32x2_t v = {lo, hi}; bf16x2_t b = __builtin_convertvector(v, bf16x2_t); return __builtin_bit_cast(unsigned, b); }
; __device__ __forceinline__ void gla_prep_item(LAS unsigned char* lds, int item, const bf16_t* Z, const float* W2, const float* Bg, bf16_t* KDT, float* DEC) {
;     ...
;     for (int t8 = 0; t8 < 8; ++t8) {
;         float kv[8];
; #pragma unroll
;         for (int e = 0; e < 8; ++e) {
;             const int t = t8 * 8 + e;
;             bc += gv[t];
;             kv[e] = bf2f(gk[(size_t)t * ZLD]) * __expf(bend - bc);
;         }
;         u32x4 o; o.x = pk2(kv[0], kv[1]); o.y = pk2(kv[2], kv[3]); o.z = pk2(kv[4], kv[5]); o.w = pk2(kv[6], kv[7]);
;         *(u32x4*)(dst + ((t8 >> 2) * 64 + (t8 & 3) * 16) * 8) = o;
	v_addc_co_u32_e32 v65, vcc, 0, v47, vcc
	v_pk_mul_f32 v[50:51], v[50:51], v[52:53]
	v_sub_f32_e32 v52, v62, v73
	v_sub_f32_e32 v53, v62, v74
	v_mul_f32_e32 v52, 0x3fb8aa3b, v52
	v_mul_f32_e32 v53, 0x3fb8aa3b, v53
	v_exp_f32_e32 v52, v52
	v_exp_f32_e32 v53, v53
	v_cvt_pk_bf16_f32 v49, v50, v51
	s_nop 0
	v_lshlrev_b32_e32 v55, 16, v54
	v_lshlrev_b32_e32 v54, 16, v63
	v_mov_b32_e32 v63, v146
	v_add_co_u32_e32 v64, vcc, s0, v46
	v_pk_mul_f32 v[52:53], v[52:53], v[54:55]
	s_nop 0
	v_addc_co_u32_e32 v65, vcc, 0, v47, vcc
	v_mov_b32_e32 v64, v147
	v_sub_f32_e32 v54, v62, v75
	v_sub_f32_e32 v55, v62, v77
	v_mul_f32_e32 v54, 0x3fb8aa3b, v54
	v_mul_f32_e32 v55, 0x3fb8aa3b, v55
	v_exp_f32_e32 v54, v54
	v_exp_f32_e32 v55, v55
	v_cvt_pk_bf16_f32 v50, v52, v53
	s_mov_b32 s0, 0xc000
	s_nop 0
	v_lshlrev_b32_e32 v65, 16, v64
	v_lshlrev_b32_e32 v64, 16, v63
	v_pk_mul_f32 v[54:55], v[54:55], v[64:65]
	s_nop 0
	v_cvt_pk_bf16_f32 v51, v54, v55
	global_store_dwordx4 v[2:3], v[48:51], off
	s_nop 1
	v_add_co_u32_e32 v50, vcc, s0, v46
	s_mov_b32 s0, 0xe000
	s_nop 0
	v_addc_co_u32_e32 v51, vcc, 0, v47, vcc
	v_mov_b32_e32 v52, v148
	v_add_co_u32_e32 v50, vcc, s0, v46
	s_mov_b32 s0, 0xf000
	s_nop 0
	v_addc_co_u32_e32 v51, vcc, 0, v47, vcc
	v_mov_b32_e32 v50, v149
	v_sub_f32_e32 v48, v62, v76
	v_sub_f32_e32 v49, v62, v78
	v_mul_f32_e32 v48, 0x3fb8aa3b, v48
	v_mul_f32_e32 v49, 0x3fb8aa3b, v49
	v_exp_f32_e32 v48, v48
	v_exp_f32_e32 v49, v49
	s_nop 0
	v_lshlrev_b32_e32 v51, 16, v50
	v_lshlrev_b32_e32 v50, 16, v52
	v_add_co_u32_e32 v52, vcc, s0, v46
	s_mov_b32 s0, 0x11000
	s_nop 0
	v_addc_co_u32_e32 v53, vcc, 0, v47, vcc
	v_mov_b32_e32 v54, v150
	v_add_co_u32_e32 v52, vcc, s0, v46
	s_mov_b32 s0, 0x12000
	s_nop 0
	v_addc_co_u32_e32 v53, vcc, 0, v47, vcc
	v_mov_b32_e32 v52, v151
	v_pk_mul_f32 v[48:49], v[48:49], v[50:51]
	v_sub_f32_e32 v50, v62, v79
	v_sub_f32_e32 v51, v62, v80
	v_mul_f32_e32 v50, 0x3fb8aa3b, v50
	v_mul_f32_e32 v51, 0x3fb8aa3b, v51
	v_exp_f32_e32 v50, v50
	v_exp_f32_e32 v51, v51
	v_cvt_pk_bf16_f32 v48, v48, v49
	s_nop 0
	v_lshlrev_b32_e32 v53, 16, v52
	v_lshlrev_b32_e32 v52, 16, v54
	v_add_co_u32_e32 v54, vcc, s0, v46
	s_mov_b32 s0, 0x14000
	s_nop 0
	v_addc_co_u32_e32 v55, vcc, 0, v47, vcc
	v_mov_b32_e32 v63, v152
	v_add_co_u32_e32 v54, vcc, s0, v46
	s_mov_b32 s0, 0x15000
	s_nop 0
	v_addc_co_u32_e32 v55, vcc, 0, v47, vcc
	v_mov_b32_e32 v54, v153
	v_add_co_u32_e32 v64, vcc, s0, v46
	s_mov_b32 s0, 0x17000
	s_nop 0
	v_addc_co_u32_e32 v65, vcc, 0, v47, vcc
	v_pk_mul_f32 v[50:51], v[50:51], v[52:53]
	v_sub_f32_e32 v52, v62, v81
	v_sub_f32_e32 v53, v62, v82
	v_mul_f32_e32 v52, 0x3fb8aa3b, v52
	v_mul_f32_e32 v53, 0x3fb8aa3b, v53
	v_exp_f32_e32 v52, v52
	v_exp_f32_e32 v53, v53
	v_cvt_pk_bf16_f32 v49, v50, v51
	s_nop 0
	v_lshlrev_b32_e32 v55, 16, v54
	v_lshlrev_b32_e32 v54, 16, v63
	v_mov_b32_e32 v63, v154
	v_add_co_u32_e32 v64, vcc, s0, v46
	v_pk_mul_f32 v[52:53], v[52:53], v[54:55]
	s_nop 0
	v_addc_co_u32_e32 v65, vcc, 0, v47, vcc
	v_mov_b32_e32 v64, v155
	v_sub_f32_e32 v54, v62, v83
	v_sub_f32_e32 v55, v62, v84
	v_mul_f32_e32 v54, 0x3fb8aa3b, v54
	v_mul_f32_e32 v55, 0x3fb8aa3b, v55
	v_exp_f32_e32 v54, v54
	v_exp_f32_e32 v55, v55
	v_cvt_pk_bf16_f32 v50, v52, v53
	s_mov_b32 s0, 0x18000
	s_nop 0
	v_lshlrev_b32_e32 v65, 16, v64
	v_lshlrev_b32_e32 v64, 16, v63
	v_pk_mul_f32 v[54:55], v[54:55], v[64:65]
	s_nop 0
	v_cvt_pk_bf16_f32 v51, v54, v55
	global_store_dwordx4 v[2:3], v[48:51], off offset:256
	s_nop 1
	v_add_co_u32_e32 v50, vcc, s0, v46
	s_mov_b32 s0, 0x1a000
	s_nop 0
	v_addc_co_u32_e32 v51, vcc, 0, v47, vcc
	v_mov_b32_e32 v52, v156
	v_add_co_u32_e32 v50, vcc, s0, v46
	s_mov_b32 s0, 0x1b000
	s_nop 0
	v_addc_co_u32_e32 v51, vcc, 0, v47, vcc
	v_mov_b32_e32 v50, v157
	v_sub_f32_e32 v48, v62, v85
	v_sub_f32_e32 v49, v62, v86
	v_mul_f32_e32 v48, 0x3fb8aa3b, v48
	v_mul_f32_e32 v49, 0x3fb8aa3b, v49
	v_exp_f32_e32 v48, v48
	v_exp_f32_e32 v49, v49
	s_nop 0
	v_lshlrev_b32_e32 v51, 16, v50
	v_lshlrev_b32_e32 v50, 16, v52
	v_add_co_u32_e32 v52, vcc, s0, v46
	s_mov_b32 s0, 0x1d000
	s_nop 0
	v_addc_co_u32_e32 v53, vcc, 0, v47, vcc
	v_mov_b32_e32 v54, v158
	v_add_co_u32_e32 v52, vcc, s0, v46
	s_mov_b32 s0, 0x1e000
	s_nop 0
	v_addc_co_u32_e32 v53, vcc, 0, v47, vcc
	v_mov_b32_e32 v52, v159
	v_pk_mul_f32 v[48:49], v[48:49], v[50:51]
	v_sub_f32_e32 v50, v62, v87
	v_sub_f32_e32 v51, v62, v88
	v_mul_f32_e32 v50, 0x3fb8aa3b, v50
	v_mul_f32_e32 v51, 0x3fb8aa3b, v51
	v_exp_f32_e32 v50, v50
	v_exp_f32_e32 v51, v51
	v_cvt_pk_bf16_f32 v48, v48, v49
	s_nop 0
	v_lshlrev_b32_e32 v53, 16, v52
	v_lshlrev_b32_e32 v52, 16, v54
	v_add_co_u32_e32 v54, vcc, s0, v46
	s_mov_b32 s0, 0x20000
	s_nop 0
	v_addc_co_u32_e32 v55, vcc, 0, v47, vcc
	v_mov_b32_e32 v63, v160
	v_add_co_u32_e32 v54, vcc, s0, v46
	s_mov_b32 s0, 0x21000
	s_nop 0
	v_addc_co_u32_e32 v55, vcc, 0, v47, vcc
	v_mov_b32_e32 v54, v161
	v_add_co_u32_e32 v64, vcc, s0, v46
	s_mov_b32 s0, 0x23000
	s_nop 0
	v_addc_co_u32_e32 v65, vcc, 0, v47, vcc
	v_pk_mul_f32 v[50:51], v[50:51], v[52:53]
	v_sub_f32_e32 v52, v62, v89
	v_sub_f32_e32 v53, v62, v90
	v_mul_f32_e32 v52, 0x3fb8aa3b, v52
	v_mul_f32_e32 v53, 0x3fb8aa3b, v53
	v_exp_f32_e32 v52, v52
	v_exp_f32_e32 v53, v53
	v_cvt_pk_bf16_f32 v49, v50, v51
	s_nop 0
	v_lshlrev_b32_e32 v55, 16, v54
	v_lshlrev_b32_e32 v54, 16, v63
	v_mov_b32_e32 v63, v162
	v_add_co_u32_e32 v64, vcc, s0, v46
	v_pk_mul_f32 v[52:53], v[52:53], v[54:55]
	s_nop 0
	v_addc_co_u32_e32 v65, vcc, 0, v47, vcc
	v_mov_b32_e32 v64, v163
	v_sub_f32_e32 v54, v62, v91
	v_sub_f32_e32 v55, v62, v92
	v_mul_f32_e32 v54, 0x3fb8aa3b, v54
	v_mul_f32_e32 v55, 0x3fb8aa3b, v55
	v_exp_f32_e32 v54, v54
	v_exp_f32_e32 v55, v55
	v_cvt_pk_bf16_f32 v50, v52, v53
; __device__ __forceinline__ unsigned pk2(float lo, float hi) { f32x2_t v = {lo, hi}; bf16x2_t b = __builtin_convertvector(v, bf16x2_t); return __builtin_bit_cast(unsigned, b); }
; __device__ __forceinline__ void gla_prep_item(LAS unsigned char* lds, int item, const bf16_t* Z, const float* W2, const float* Bg, bf16_t* KDT, float* DEC) {
;     ...
;     for (int t8 = 0; t8 < 8; ++t8) {
;         float kv[8];
; #pragma unroll
;         for (int e = 0; e < 8; ++e) {
;             const int t = t8 * 8 + e;
;             bc += gv[t];
;             kv[e] = bf2f(gk[(size_t)t * ZLD]) * __expf(bend - bc);
;         }
;         u32x4 o; o.x = pk2(kv[0], kv[1]); o.y = pk2(kv[2], kv[3]); o.z = pk2(kv[4], kv[5]); o.w = pk2(kv[6], kv[7]);
;         *(u32x4*)(dst + ((t8 >> 2) * 64 + (t8 & 3) * 16) * 8) = o;
	s_mov_b32 s0, 0x24000
	s_nop 0
	v_lshlrev_b32_e32 v65, 16, v64
	v_lshlrev_b32_e32 v64, 16, v63
	v_pk_mul_f32 v[54:55], v[54:55], v[64:65]
	s_nop 0
	v_cvt_pk_bf16_f32 v51, v54, v55
	global_store_dwordx4 v[2:3], v[48:51], off offset:512
	s_nop 1
	v_add_co_u32_e32 v50, vcc, s0, v46
	s_mov_b32 s0, 0x26000
	s_nop 0
	v_addc_co_u32_e32 v51, vcc, 0, v47, vcc
	v_mov_b32_e32 v52, v164
	v_add_co_u32_e32 v50, vcc, s0, v46
	s_mov_b32 s0, 0x27000
	s_nop 0
	v_addc_co_u32_e32 v51, vcc, 0, v47, vcc
	v_mov_b32_e32 v50, v165
	v_sub_f32_e32 v48, v62, v93
	v_sub_f32_e32 v49, v62, v94
	v_mul_f32_e32 v48, 0x3fb8aa3b, v48
	v_mul_f32_e32 v49, 0x3fb8aa3b, v49
	v_exp_f32_e32 v48, v48
	v_exp_f32_e32 v49, v49
	s_nop 0
	v_lshlrev_b32_e32 v51, 16, v50
	v_lshlrev_b32_e32 v50, 16, v52
	v_add_co_u32_e32 v52, vcc, s0, v46
	s_mov_b32 s0, 0x29000
	s_nop 0
	v_addc_co_u32_e32 v53, vcc, 0, v47, vcc
	v_mov_b32_e32 v54, v166
	v_add_co_u32_e32 v52, vcc, s0, v46
	s_mov_b32 s0, 0x2a000
	s_nop 0
	v_addc_co_u32_e32 v53, vcc, 0, v47, vcc
	v_mov_b32_e32 v52, v167
	v_pk_mul_f32 v[48:49], v[48:49], v[50:51]
	v_sub_f32_e32 v50, v62, v95
	v_sub_f32_e32 v51, v62, v96
	v_mul_f32_e32 v50, 0x3fb8aa3b, v50
	v_mul_f32_e32 v51, 0x3fb8aa3b, v51
	v_exp_f32_e32 v50, v50
	v_exp_f32_e32 v51, v51
	v_cvt_pk_bf16_f32 v48, v48, v49
	s_nop 0
	v_lshlrev_b32_e32 v53, 16, v52
	v_lshlrev_b32_e32 v52, 16, v54
	v_add_co_u32_e32 v54, vcc, s0, v46
	s_mov_b32 s0, 0x2c000
	s_nop 0
	v_addc_co_u32_e32 v55, vcc, 0, v47, vcc
	v_mov_b32_e32 v63, v168
	v_add_co_u32_e32 v54, vcc, s0, v46
	s_mov_b32 s0, 0x2d000
	s_nop 0
	v_addc_co_u32_e32 v55, vcc, 0, v47, vcc
	v_mov_b32_e32 v54, v169
	v_add_co_u32_e32 v64, vcc, s0, v46
	s_mov_b32 s0, 0x2f000
	s_nop 0
	v_addc_co_u32_e32 v65, vcc, 0, v47, vcc
	v_pk_mul_f32 v[50:51], v[50:51], v[52:53]
	v_sub_f32_e32 v52, v62, v97
	v_sub_f32_e32 v53, v62, v98
	v_mul_f32_e32 v52, 0x3fb8aa3b, v52
	v_mul_f32_e32 v53, 0x3fb8aa3b, v53
	v_exp_f32_e32 v52, v52
	v_exp_f32_e32 v53, v53
	v_cvt_pk_bf16_f32 v49, v50, v51
	s_nop 0
	v_lshlrev_b32_e32 v55, 16, v54
	v_lshlrev_b32_e32 v54, 16, v63
	v_mov_b32_e32 v63, v170
	v_add_co_u32_e32 v64, vcc, s0, v46
	v_pk_mul_f32 v[52:53], v[52:53], v[54:55]
	s_nop 0
	v_addc_co_u32_e32 v65, vcc, 0, v47, vcc
	v_mov_b32_e32 v64, v171
	v_sub_f32_e32 v54, v62, v99
	v_sub_f32_e32 v55, v62, v100
	v_mul_f32_e32 v54, 0x3fb8aa3b, v54
	v_mul_f32_e32 v55, 0x3fb8aa3b, v55
	v_exp_f32_e32 v54, v54
	v_exp_f32_e32 v55, v55
	v_cvt_pk_bf16_f32 v50, v52, v53
	s_mov_b32 s0, 0x30000
	s_nop 0
	v_lshlrev_b32_e32 v65, 16, v64
	v_lshlrev_b32_e32 v64, 16, v63
	v_pk_mul_f32 v[54:55], v[54:55], v[64:65]
	s_nop 0
	v_cvt_pk_bf16_f32 v51, v54, v55
	global_store_dwordx4 v[2:3], v[48:51], off offset:768
	s_nop 1
	v_add_co_u32_e32 v50, vcc, s0, v46
	s_mov_b32 s0, 0x32000
	s_nop 0
	v_addc_co_u32_e32 v51, vcc, 0, v47, vcc
	v_mov_b32_e32 v52, v172
	v_add_co_u32_e32 v50, vcc, s0, v46
	s_mov_b32 s0, 0x33000
	s_nop 0
	v_addc_co_u32_e32 v51, vcc, 0, v47, vcc
	v_mov_b32_e32 v50, v173
	v_sub_f32_e32 v48, v62, v101
	v_sub_f32_e32 v49, v62, v102
	v_mul_f32_e32 v48, 0x3fb8aa3b, v48
	v_mul_f32_e32 v49, 0x3fb8aa3b, v49
	v_exp_f32_e32 v48, v48
	v_exp_f32_e32 v49, v49
	s_nop 0
	v_lshlrev_b32_e32 v51, 16, v50
	v_lshlrev_b32_e32 v50, 16, v52
	v_add_co_u32_e32 v52, vcc, s0, v46
	s_mov_b32 s0, 0x35000
	s_nop 0
	v_addc_co_u32_e32 v53, vcc, 0, v47, vcc
	v_mov_b32_e32 v54, v174
	v_add_co_u32_e32 v52, vcc, s0, v46
	s_mov_b32 s0, 0x36000
	s_nop 0
	v_addc_co_u32_e32 v53, vcc, 0, v47, vcc
	v_mov_b32_e32 v52, v175
	v_pk_mul_f32 v[48:49], v[48:49], v[50:51]
	v_sub_f32_e32 v50, v62, v103
	v_sub_f32_e32 v51, v62, v104
	v_mul_f32_e32 v50, 0x3fb8aa3b, v50
	v_mul_f32_e32 v51, 0x3fb8aa3b, v51
	v_exp_f32_e32 v50, v50
	v_exp_f32_e32 v51, v51
	v_cvt_pk_bf16_f32 v48, v48, v49
	s_nop 0
	v_lshlrev_b32_e32 v53, 16, v52
	v_lshlrev_b32_e32 v52, 16, v54
	v_add_co_u32_e32 v54, vcc, s0, v46
	s_mov_b32 s0, 0x38000
	s_nop 0
	v_addc_co_u32_e32 v55, vcc, 0, v47, vcc
	v_mov_b32_e32 v63, v176
	v_add_co_u32_e32 v54, vcc, s0, v46
	s_mov_b32 s0, 0x39000
	s_nop 0
	v_addc_co_u32_e32 v55, vcc, 0, v47, vcc
	v_mov_b32_e32 v54, v177
	v_add_co_u32_e32 v64, vcc, s0, v46
	s_mov_b32 s0, 0x3b000
	s_nop 0
	v_addc_co_u32_e32 v65, vcc, 0, v47, vcc
	v_pk_mul_f32 v[50:51], v[50:51], v[52:53]
	v_sub_f32_e32 v52, v62, v105
	v_sub_f32_e32 v53, v62, v106
	v_mul_f32_e32 v52, 0x3fb8aa3b, v52
	v_mul_f32_e32 v53, 0x3fb8aa3b, v53
	v_exp_f32_e32 v52, v52
	v_exp_f32_e32 v53, v53
	v_cvt_pk_bf16_f32 v49, v50, v51
	s_nop 0
	v_lshlrev_b32_e32 v55, 16, v54
	v_lshlrev_b32_e32 v54, 16, v63
	v_mov_b32_e32 v63, v178
	v_add_co_u32_e32 v64, vcc, s0, v46
	v_pk_mul_f32 v[52:53], v[52:53], v[54:55]
	s_nop 0
	v_addc_co_u32_e32 v65, vcc, 0, v47, vcc
	v_mov_b32_e32 v64, v179
	v_sub_f32_e32 v54, v62, v107
	v_sub_f32_e32 v55, v62, v108
	v_mul_f32_e32 v54, 0x3fb8aa3b, v54
	v_mul_f32_e32 v55, 0x3fb8aa3b, v55
	v_exp_f32_e32 v54, v54
	v_exp_f32_e32 v55, v55
	v_cvt_pk_bf16_f32 v50, v52, v53
	s_mov_b32 s0, 0x3c000
	s_nop 0
	v_lshlrev_b32_e32 v65, 16, v64
	v_lshlrev_b32_e32 v64, 16, v63
	v_pk_mul_f32 v[54:55], v[54:55], v[64:65]
	s_nop 0
	v_cvt_pk_bf16_f32 v51, v54, v55
	global_store_dwordx4 v[2:3], v[48:51], off offset:1024
	s_nop 1
	v_add_co_u32_e32 v50, vcc, s0, v46
	s_mov_b32 s0, 0x3e000
	s_nop 0
	v_addc_co_u32_e32 v51, vcc, 0, v47, vcc
	v_mov_b32_e32 v52, v180
	v_add_co_u32_e32 v50, vcc, s0, v46
	s_mov_b32 s0, 0x3f000
	s_nop 0
	v_addc_co_u32_e32 v51, vcc, 0, v47, vcc
	v_mov_b32_e32 v50, v181
	v_sub_f32_e32 v48, v62, v109
	v_sub_f32_e32 v49, v62, v110
	v_mul_f32_e32 v48, 0x3fb8aa3b, v48
	v_mul_f32_e32 v49, 0x3fb8aa3b, v49
	v_exp_f32_e32 v48, v48
	v_exp_f32_e32 v49, v49
	s_nop 0
	v_lshlrev_b32_e32 v51, 16, v50
; __device__ __forceinline__ unsigned pk2(float lo, float hi) { f32x2_t v = {lo, hi}; bf16x2_t b = __builtin_convertvector(v, bf16x2_t); return __builtin_bit_cast(unsigned, b); }
; __device__ __forceinline__ void gla_prep_item(LAS unsigned char* lds, int item, const bf16_t* Z, const float* W2, const float* Bg, bf16_t* KDT, float* DEC) {
;     ...
;     for (int t8 = 0; t8 < 8; ++t8) {
;         float kv[8];
; #pragma unroll
;         for (int e = 0; e < 8; ++e) {
;             const int t = t8 * 8 + e;
;             bc += gv[t];
;             kv[e] = bf2f(gk[(size_t)t * ZLD]) * __expf(bend - bc);
;         }
;         u32x4 o; o.x = pk2(kv[0], kv[1]); o.y = pk2(kv[2], kv[3]); o.z = pk2(kv[4], kv[5]); o.w = pk2(kv[6], kv[7]);
;         *(u32x4*)(dst + ((t8 >> 2) * 64 + (t8 & 3) * 16) * 8) = o;
	v_lshlrev_b32_e32 v50, 16, v52
	v_add_co_u32_e32 v52, vcc, s0, v46
	s_mov_b32 s0, 0x41000
	s_nop 0
	v_addc_co_u32_e32 v53, vcc, 0, v47, vcc
	v_mov_b32_e32 v54, v182
	v_add_co_u32_e32 v52, vcc, s0, v46
	s_mov_b32 s0, 0x42000
	s_nop 0
	v_addc_co_u32_e32 v53, vcc, 0, v47, vcc
	v_mov_b32_e32 v52, v183
	v_pk_mul_f32 v[48:49], v[48:49], v[50:51]
	v_sub_f32_e32 v50, v62, v111
	v_sub_f32_e32 v51, v62, v112
	v_mul_f32_e32 v50, 0x3fb8aa3b, v50
	v_mul_f32_e32 v51, 0x3fb8aa3b, v51
	v_exp_f32_e32 v50, v50
	v_exp_f32_e32 v51, v51
	v_cvt_pk_bf16_f32 v48, v48, v49
	s_nop 0
	v_lshlrev_b32_e32 v53, 16, v52
	v_lshlrev_b32_e32 v52, 16, v54
	v_add_co_u32_e32 v54, vcc, s0, v46
	s_mov_b32 s0, 0x44000
	s_nop 0
	v_addc_co_u32_e32 v55, vcc, 0, v47, vcc
	v_mov_b32_e32 v63, v186
	v_add_co_u32_e32 v54, vcc, s0, v46
	s_mov_b32 s0, 0x45000
	s_nop 0
	v_addc_co_u32_e32 v55, vcc, 0, v47, vcc
	v_mov_b32_e32 v54, v187
	v_add_co_u32_e32 v64, vcc, s0, v46
	s_mov_b32 s0, 0x47000
	s_nop 0
	v_addc_co_u32_e32 v65, vcc, 0, v47, vcc
	v_pk_mul_f32 v[50:51], v[50:51], v[52:53]
	v_sub_f32_e32 v52, v62, v113
	v_sub_f32_e32 v53, v62, v114
	v_mul_f32_e32 v52, 0x3fb8aa3b, v52
	v_mul_f32_e32 v53, 0x3fb8aa3b, v53
	v_exp_f32_e32 v52, v52
	v_exp_f32_e32 v53, v53
	v_cvt_pk_bf16_f32 v49, v50, v51
	s_nop 0
	v_lshlrev_b32_e32 v55, 16, v54
	v_lshlrev_b32_e32 v54, 16, v63
	v_mov_b32_e32 v63, v188
	v_add_co_u32_e32 v64, vcc, s0, v46
	v_pk_mul_f32 v[52:53], v[52:53], v[54:55]
	s_nop 0
	v_addc_co_u32_e32 v65, vcc, 0, v47, vcc
	v_mov_b32_e32 v64, v189
	v_sub_f32_e32 v54, v62, v115
	v_sub_f32_e32 v55, v62, v116
	v_mul_f32_e32 v54, 0x3fb8aa3b, v54
	v_mul_f32_e32 v55, 0x3fb8aa3b, v55
	v_exp_f32_e32 v54, v54
	v_exp_f32_e32 v55, v55
	v_cvt_pk_bf16_f32 v50, v52, v53
	s_mov_b32 s0, 0x48000
	s_nop 0
	v_lshlrev_b32_e32 v65, 16, v64
	v_lshlrev_b32_e32 v64, 16, v63
	v_pk_mul_f32 v[54:55], v[54:55], v[64:65]
	s_nop 0
	v_cvt_pk_bf16_f32 v51, v54, v55
	global_store_dwordx4 v[2:3], v[48:51], off offset:1280
	s_nop 1
	v_add_co_u32_e32 v50, vcc, s0, v46
	s_mov_b32 s0, 0x4a000
	s_nop 0
	v_addc_co_u32_e32 v51, vcc, 0, v47, vcc
	v_mov_b32_e32 v52, v190
	v_add_co_u32_e32 v50, vcc, s0, v46
	s_mov_b32 s0, 0x4b000
	s_nop 0
	v_addc_co_u32_e32 v51, vcc, 0, v47, vcc
	v_mov_b32_e32 v50, v191
	v_sub_f32_e32 v48, v62, v117
	v_sub_f32_e32 v49, v62, v118
	v_mul_f32_e32 v48, 0x3fb8aa3b, v48
	v_mul_f32_e32 v49, 0x3fb8aa3b, v49
	v_exp_f32_e32 v48, v48
	v_exp_f32_e32 v49, v49
	s_nop 0
	v_lshlrev_b32_e32 v51, 16, v50
	v_lshlrev_b32_e32 v50, 16, v52
	v_add_co_u32_e32 v52, vcc, s0, v46
	s_mov_b32 s0, 0x4d000
	s_nop 0
	v_addc_co_u32_e32 v53, vcc, 0, v47, vcc
	v_mov_b32_e32 v54, v192
	v_add_co_u32_e32 v52, vcc, s0, v46
	s_mov_b32 s0, 0x4e000
	s_nop 0
	v_addc_co_u32_e32 v53, vcc, 0, v47, vcc
	v_mov_b32_e32 v52, v193
	v_pk_mul_f32 v[48:49], v[48:49], v[50:51]
	v_sub_f32_e32 v50, v62, v119
	v_sub_f32_e32 v51, v62, v120
	v_mul_f32_e32 v50, 0x3fb8aa3b, v50
	v_mul_f32_e32 v51, 0x3fb8aa3b, v51
	v_exp_f32_e32 v50, v50
	v_exp_f32_e32 v51, v51
	v_cvt_pk_bf16_f32 v48, v48, v49
	s_nop 0
	v_lshlrev_b32_e32 v53, 16, v52
	v_lshlrev_b32_e32 v52, 16, v54
	v_add_co_u32_e32 v54, vcc, s0, v46
	s_mov_b32 s0, 0x50000
	s_nop 0
	v_addc_co_u32_e32 v55, vcc, 0, v47, vcc
	v_mov_b32_e32 v63, v194
	v_add_co_u32_e32 v54, vcc, s0, v46
	s_mov_b32 s0, 0x51000
	s_nop 0
	v_addc_co_u32_e32 v55, vcc, 0, v47, vcc
	v_mov_b32_e32 v54, v195
	v_add_co_u32_e32 v64, vcc, s0, v46
	s_mov_b32 s0, 0x53000
	s_nop 0
	v_addc_co_u32_e32 v65, vcc, 0, v47, vcc
	v_pk_mul_f32 v[50:51], v[50:51], v[52:53]
	v_sub_f32_e32 v52, v62, v121
	v_sub_f32_e32 v53, v62, v122
	v_mul_f32_e32 v52, 0x3fb8aa3b, v52
; __device__ __forceinline__ unsigned pk2(float lo, float hi) { f32x2_t v = {lo, hi}; bf16x2_t b = __builtin_convertvector(v, bf16x2_t); return __builtin_bit_cast(unsigned, b); }
; __device__ __forceinline__ void gla_prep_item(LAS unsigned char* lds, int item, const bf16_t* Z, const float* W2, const float* Bg, bf16_t* KDT, float* DEC) {
;     ...
;     for (int t8 = 0; t8 < 8; ++t8) {
;         float kv[8];
; #pragma unroll
;         for (int e = 0; e < 8; ++e) {
;             const int t = t8 * 8 + e;
;             bc += gv[t];
;             kv[e] = bf2f(gk[(size_t)t * ZLD]) * __expf(bend - bc);
;         }
;         u32x4 o; o.x = pk2(kv[0], kv[1]); o.y = pk2(kv[2], kv[3]); o.z = pk2(kv[4], kv[5]); o.w = pk2(kv[6], kv[7]);
;         *(u32x4*)(dst + ((t8 >> 2) * 64 + (t8 & 3) * 16) * 8) = o;
;     }
;     DEC[(size_t)((b * 4 + h) * 32 + c) * 128 + kd] = expf(bend);
;     __syncthreads();
	v_mul_f32_e32 v53, 0x3fb8aa3b, v53
	v_exp_f32_e32 v52, v52
	v_exp_f32_e32 v53, v53
	v_cvt_pk_bf16_f32 v49, v50, v51
	s_nop 0
	v_lshlrev_b32_e32 v55, 16, v54
	v_lshlrev_b32_e32 v54, 16, v63
	v_mov_b32_e32 v63, v196
	v_add_co_u32_e32 v64, vcc, s0, v46
	v_pk_mul_f32 v[52:53], v[52:53], v[54:55]
	s_nop 0
	v_addc_co_u32_e32 v65, vcc, 0, v47, vcc
	v_mov_b32_e32 v64, v197
	v_sub_f32_e32 v54, v62, v123
	v_sub_f32_e32 v55, v62, v124
	v_mul_f32_e32 v54, 0x3fb8aa3b, v54
	v_mul_f32_e32 v55, 0x3fb8aa3b, v55
	v_exp_f32_e32 v54, v54
	v_exp_f32_e32 v55, v55
	v_cvt_pk_bf16_f32 v50, v52, v53
	s_mov_b32 s0, 0x3fb8aa3b
	s_nop 0
	v_lshlrev_b32_e32 v65, 16, v64
	v_lshlrev_b32_e32 v64, 16, v63
	v_pk_mul_f32 v[54:55], v[54:55], v[64:65]
	s_nop 0
	v_cvt_pk_bf16_f32 v51, v54, v55
	global_store_dwordx4 v[2:3], v[48:51], off offset:1536
	s_nop 1
	v_add_co_u32_e32 v50, vcc, s37, v46
	v_sub_f32_e32 v48, v62, v125
	s_nop 0
	v_addc_co_u32_e32 v51, vcc, 0, v47, vcc
	v_mov_b32_e32 v52, v198
	v_add_co_u32_e32 v50, vcc, s52, v46
	v_sub_f32_e32 v49, v62, v126
	s_nop 0
	v_addc_co_u32_e32 v51, vcc, 0, v47, vcc
	v_mov_b32_e32 v50, v199
	v_mul_f32_e32 v48, 0x3fb8aa3b, v48
	v_mul_f32_e32 v49, 0x3fb8aa3b, v49
	v_exp_f32_e32 v48, v48
	v_exp_f32_e32 v49, v49
	s_nop 0
	v_lshlrev_b32_e32 v51, 16, v50
	v_lshlrev_b32_e32 v50, 16, v52
	v_add_co_u32_e32 v52, vcc, s53, v46
	v_pk_mul_f32 v[48:49], v[48:49], v[50:51]
	s_nop 0
	v_addc_co_u32_e32 v53, vcc, 0, v47, vcc
	v_mov_b32_e32 v54, v200
	v_add_co_u32_e32 v52, vcc, s58, v46
	v_sub_f32_e32 v50, v62, v127
	s_nop 0
	v_addc_co_u32_e32 v53, vcc, 0, v47, vcc
	v_mov_b32_e32 v52, v201
	v_sub_f32_e32 v51, v62, v128
	v_mul_f32_e32 v50, 0x3fb8aa3b, v50
	v_mul_f32_e32 v51, 0x3fb8aa3b, v51
	v_exp_f32_e32 v50, v50
	v_exp_f32_e32 v51, v51
	s_nop 0
	v_lshlrev_b32_e32 v53, 16, v52
	v_lshlrev_b32_e32 v52, 16, v54
	v_add_co_u32_e32 v54, vcc, s59, v46
	v_pk_mul_f32 v[50:51], v[50:51], v[52:53]
	s_nop 0
	v_addc_co_u32_e32 v55, vcc, 0, v47, vcc
	v_mov_b32_e32 v63, v202
	v_add_co_u32_e32 v54, vcc, s60, v46
	v_sub_f32_e32 v52, v62, v129
	s_nop 0
	v_addc_co_u32_e32 v55, vcc, 0, v47, vcc
	v_mov_b32_e32 v54, v203
	v_add_co_u32_e32 v64, vcc, s61, v46
	v_sub_f32_e32 v53, v62, v130
	s_nop 0
	v_addc_co_u32_e32 v65, vcc, 0, v47, vcc
	v_add_co_u32_e32 v46, vcc, s62, v46
	v_mul_f32_e32 v52, 0x3fb8aa3b, v52
	s_nop 0
	v_addc_co_u32_e32 v47, vcc, 0, v47, vcc
	v_mov_b32_e32 v46, v205
	v_mul_f32_e32 v53, 0x3fb8aa3b, v53
	v_exp_f32_e32 v52, v52
	v_exp_f32_e32 v53, v53
	v_cmp_ngt_f32_e32 vcc, s63, v62
	s_nop 0
	v_lshlrev_b32_e32 v55, 16, v54
	v_lshlrev_b32_e32 v54, 16, v63
	v_mov_b32_e32 v63, v204
	v_pk_mul_f32 v[52:53], v[52:53], v[54:55]
	v_sub_f32_e32 v54, v62, v131
	v_sub_f32_e32 v55, v62, v62
	v_mul_f32_e32 v54, 0x3fb8aa3b, v54
	v_mul_f32_e32 v55, 0x3fb8aa3b, v55
	v_exp_f32_e32 v54, v54
	v_exp_f32_e32 v55, v55
	s_nop 0
	v_lshlrev_b32_e32 v47, 16, v46
	s_nop 0
	v_lshlrev_b32_e32 v46, 16, v63
	v_pk_mul_f32 v[54:55], v[54:55], v[46:47]
	v_cvt_pk_bf16_f32 v46, v48, v49
	v_cvt_pk_bf16_f32 v47, v50, v51
	v_cvt_pk_bf16_f32 v48, v52, v53
	v_cvt_pk_bf16_f32 v49, v54, v55
	global_store_dwordx4 v[2:3], v[46:49], off offset:1792
	v_mul_f32_e32 v2, 0x3fb8aa3b, v62
	v_fma_f32 v3, v62, s0, -v2
	v_rndne_f32_e32 v46, v2
	v_fmac_f32_e32 v3, 0x32a5705f, v62
	v_sub_f32_e32 v2, v2, v46
	v_add_f32_e32 v2, v2, v3
	v_exp_f32_e32 v2, v2
	v_cvt_i32_f32_e32 v3, v46
	v_ldexp_f32 v2, v2, v3
	v_cndmask_b32_e32 v2, 0, v2, vcc
	v_cmp_nlt_f32_e32 vcc, s64, v62
	s_nop 1
	v_cndmask_b32_e32 v2, v61, v2, vcc
	global_store_dword v[0:1], v2, off
	s_barrier
	s_cbranch_scc0 .LBB0_597
	s_branch .LBB0_595
